# k2_cpv
# speedup vs baseline: 1.0284x; 1.0284x over previous
; DI void norm_store_row(const float4 v[4], const float* __restrict__ g, u16* __restrict__ dst, int lane) {
;   float ss = 0.f;
; #pragma unroll
;   for (int i = 0; i < 4; ++i) ss += v[i].x * v[i].x + v[i].y * v[i].y + v[i].z * v[i].z + v[i].w * v[i].w;
;   ss = wave_sum(ss);
;   const float r = rsqrtf(ss * (1.f / 1024.f) + 1e-6f);
; DI void phase_init(const Params& p, char* smem) {
;   const int tid = threadIdx.x, lane = tid & 63, wave = tid >> 6;
;   float* h = (float*)(p.ws + OFF_H);
;   u16* xn = (u16*)(p.ws + OFF_XN);
;   u16* wreg = (u16*)(p.ws + OFF_W);
;   for (int row = blockIdx.x * 4 + wave; row < T; row += gridDim.x * 4) {
;     const int b = row / LT, t = row % LT;
;     const float* src = t < 16 ? p.in[1] + (size_t)t * DM : p.in[0] + ((size_t)b * 8192 + (t - 16)) * DM;
;     float4 v[4];
; #pragma unroll
;     for (int i = 0; i < 4; ++i) v[i] = ((const float4*)src)[i * 64 + lane];
; #pragma unroll
;     for (int i = 0; i < 4; ++i) ((float4*)(h + (size_t)row * DM))[i * 64 + lane] = v[i];
;     norm_store_row(v, p.in[2], xn + (size_t)row * DM, lane);
_Z10hybrid_fwd6Params:
	s_load_dwordx2 s[68:69], s[0:1], 0xb8
	s_load_dwordx8 s[60:67], s[0:1], 0x98
	v_bfe_u32 v180, v0, 6, 4
	v_lshl_or_b32 v182, s2, 2, v180
	s_mov_b32 s3, 0x10080
	v_readfirstlane_b32 s94, v180
	s_mov_b32 s95, s2
	s_mov_b32 s90, 0
	s_add_u32 s72, s0, 0xc8
	v_cmp_gt_i32_e64 s[4:5], s3, v182
	s_mov_b32 s3, 0x1007f
	s_addc_u32 s73, s1, 0
	v_and_b32_e32 v176, 63, v0
	v_cmp_lt_i32_e32 vcc, s3, v182
	s_and_saveexec_b64 s[6:7], vcc
	s_xor_b64 s[6:7], exec, s[6:7]
	v_mov_b32_e32 v177, 0
	s_or_saveexec_b64 s[6:7], s[6:7]
	s_load_dword s70, s[0:1], 0xc8
	v_mbcnt_lo_u32_b32 v216, -1, 0
	v_lshlrev_b32_e32 v184, 3, v176
	v_lshlrev_b32_e32 v178, 4, v176
	s_xor_b64 exec, exec, s[6:7]
	s_cbranch_execz .LBB0_10
	v_mbcnt_hi_u32_b32 v2, -1, v216
	v_and_b32_e32 v1, 64, v2
	v_add_u32_e32 v3, 64, v1
	v_xor_b32_e32 v1, 32, v2
	v_cmp_lt_i32_e32 vcc, v1, v3
	v_xor_b32_e32 v4, 16, v2
	s_load_dwordx4 s[8:11], s[0:1], 0x0
	s_load_dwordx2 s[12:13], s[0:1], 0x10
	v_cndmask_b32_e32 v1, v2, v1, vcc
	v_cmp_lt_i32_e32 vcc, v4, v3
	s_mov_b64 s[14:15], 0x10080000
	v_lshlrev_b32_e32 v1, 2, v1
	v_cndmask_b32_e32 v4, v2, v4, vcc
	v_lshlrev_b32_e32 v20, 2, v4
	v_xor_b32_e32 v4, 8, v2
	v_cmp_lt_i32_e32 vcc, v4, v3
	s_waitcnt lgkmcnt(0)
	s_lshl_b32 s3, s70, 2
	s_mov_b32 s16, 0x7fc01ff1
	v_cndmask_b32_e32 v4, v2, v4, vcc
	v_lshlrev_b32_e32 v21, 2, v4
	v_xor_b32_e32 v4, 4, v2
	v_cmp_lt_i32_e32 vcc, v4, v3
	v_lshlrev_b32_e32 v10, 4, v176
	v_mov_b32_e32 v25, 0x358637bd
	v_cndmask_b32_e32 v4, v2, v4, vcc
	v_lshlrev_b32_e32 v22, 2, v4
	v_xor_b32_e32 v4, 2, v2
	v_cmp_lt_i32_e32 vcc, v4, v3
	s_mov_b32 s17, 0x800000
	s_mov_b32 s18, 0x1007f
	v_cndmask_b32_e32 v4, v2, v4, vcc
	v_lshlrev_b32_e32 v23, 2, v4
	v_xor_b32_e32 v4, 1, v2
	v_cmp_lt_i32_e32 vcc, v4, v3
	v_mov_b32_e32 v3, 0
	v_mov_b32_e32 v185, v3
	v_cndmask_b32_e32 v2, v2, v4, vcc
	v_lshl_add_u64 v[4:5], s[68:69], 0, v[184:185]
	v_mov_b32_e32 v179, v3
	v_lshlrev_b32_e32 v24, 2, v2
	v_lshl_add_u64 v[4:5], v[4:5], 0, s[14:15]
	v_mov_b32_e32 v177, v3
	v_lshl_add_u64 v[6:7], s[12:13], 0, v[178:179]
	v_lshl_add_u64 v[8:9], s[68:69], 0, v[178:179]
	s_mov_b64 s[12:13], 0
	v_mov_b32_e32 v11, v3
	v_mov_b32_e32 v12, v182
	s_branch .LBB0_5

; DI void phase_init(const Params& p, char* smem) {
;     ...
;     for (int row = blockIdx.x * 4 + wave; row < 4 * NEXP; row += gridDim.x * 4) {
;       const int arr = row >> 14, e = row & (NEXP - 1), layer = arr >> 1, which = arr & 1;
;       const float* src = (which ? p.in[20] : p.in[19]) + ((size_t)layer * NEXP + e) * DM + lane * 16;
;       float4 v[4];
; #pragma unroll
;       for (int i = 0; i < 4; ++i) v[i] = ((const float4*)src)[i];
;       float mx = 0.f;
; #pragma unroll
;       for (int i = 0; i < 4; ++i) mx = fmaxf(mx, fmaxf(fmaxf(fabsf(v[i].x), fabsf(v[i].y)), fmaxf(fabsf(v[i].z), fabsf(v[i].w))));
; #pragma unroll
;       for (int o = 32; o; o >>= 1) mx = fmaxf(mx, __shfl_xor(mx, o));
;       int ex2 = 0;
;       if (mx > 0.f) { (void)frexpf(mx, &ex2); ex2 = 7 - ex2; }
;       const float sc = ldexpf(1.f, ex2 + 0), isc = ldexpf(1.f, -ex2);
;       u32x4 w;
; #pragma unroll
;       for (int i = 0; i < 4; ++i) {
;         int t = __builtin_amdgcn_cvt_pk_fp8_f32(v[i].x * sc, v[i].y * sc, 0, false);
;         t = __builtin_amdgcn_cvt_pk_fp8_f32(v[i].z * sc, v[i].w * sc, t, true);
;         w[i] = (unsigned)t;
;       }
;       *(u32x4*)(ex + (size_t)row * DM + lane * 16) = w;
;       if (lane == 0) exs[row] = isc;
.LBB0_67:
	v_ashrrev_i32_e32 v20, 15, v8
	v_and_b32_e32 v2, 0x4000, v8
	v_cmp_eq_u32_e64 s[0:1], 0, v2
	v_ashrrev_i32_e32 v21, 31, v20
	v_and_b32_e32 v2, 0xfffc00, v15
	v_cndmask_b32_e64 v23, v16, v17, s[0:1]
	v_cndmask_b32_e64 v22, v18, v19, s[0:1]
	v_lshlrev_b64 v[20:21], 26, v[20:21]
	v_lshl_add_u64 v[20:21], v[22:23], 0, v[20:21]
	v_lshlrev_b32_e32 v2, 2, v2
	v_lshl_add_u64 v[20:21], v[20:21], 0, v[2:3]
	v_lshl_add_u64 v[36:37], v[20:21], 0, v[6:7]
	global_load_dwordx4 v[20:23], v[36:37], off
	global_load_dwordx4 v[24:27], v[36:37], off offset:16
	global_load_dwordx4 v[28:31], v[36:37], off offset:32
	global_load_dwordx4 v[32:35], v[36:37], off offset:48
	s_waitcnt vmcnt(3)
	v_max_f32_e64 v2, |v23|, |v23|
	v_max_f32_e64 v9, |v22|, |v22|
	s_waitcnt vmcnt(2)
	v_max_f32_e64 v36, |v27|, |v27|
	v_max_f32_e64 v37, |v26|, |v26|
	s_waitcnt vmcnt(1)
	v_max_f32_e64 v38, |v31|, |v31|
	v_max_f32_e64 v39, |v30|, |v30|
	s_waitcnt vmcnt(0)
	v_max_f32_e64 v40, |v35|, |v35|
	v_max_f32_e64 v41, |v34|, |v34|
	v_max_f32_e32 v2, v9, v2
	v_max_f32_e32 v9, v37, v36
	v_max_f32_e32 v36, v39, v38
	v_max_f32_e32 v37, v41, v40
	v_max3_f32 v2, |v20|, |v21|, v2
	v_max3_f32 v9, |v24|, |v25|, v9
	v_max3_f32 v36, |v28|, |v29|, v36
	v_max3_f32 v37, |v32|, |v33|, v37
	v_max3_f32 v2, v2, 0, v9
	v_max3_f32 v2, v2, v36, v37
	ds_bpermute_b32 v9, v1, v2
	v_mov_b32_e32 v36, v3
	v_mov_b32_e32 v37, v3
	v_mov_b32_e32 v38, v3
	v_mov_b32_e32 v39, v3
	s_waitcnt lgkmcnt(0)
	v_max_f32_e32 v9, v9, v9
	v_max_f32_e32 v2, v2, v9
	ds_bpermute_b32 v9, v10, v2
	s_waitcnt lgkmcnt(0)
	v_max_f32_e32 v9, v9, v9
	v_max_f32_e32 v2, v2, v9
	ds_bpermute_b32 v9, v11, v2
	s_waitcnt lgkmcnt(0)
	v_max_f32_e32 v9, v9, v9
	v_max_f32_e32 v2, v2, v9
	ds_bpermute_b32 v9, v12, v2
	s_waitcnt lgkmcnt(0)
	v_max_f32_e32 v9, v9, v9
	v_max_f32_e32 v2, v2, v9
	ds_bpermute_b32 v9, v13, v2
	s_waitcnt lgkmcnt(0)
	v_max_f32_e32 v9, v9, v9
	v_max_f32_e32 v2, v2, v9
	ds_bpermute_b32 v9, v14, v2
	s_waitcnt lgkmcnt(0)
	v_max_f32_e32 v9, v9, v9
	v_max_f32_e32 v2, v2, v9
	v_frexp_exp_i32_f32_e32 v9, v2
	v_sub_u32_e32 v9, 7, v9
	v_cmp_lt_f32_e64 s[0:1], 0, v2
	s_nop 1
	v_cndmask_b32_e64 v2, 0, v9, s[0:1]
	v_ldexp_f32 v9, 1.0, v2
	v_mul_f32_e32 v20, v20, v9
	v_mul_f32_e32 v21, v21, v9
	v_mul_f32_e32 v24, v24, v9
	v_mul_f32_e32 v25, v25, v9
	v_mul_f32_e32 v28, v28, v9
	v_mul_f32_e32 v29, v29, v9
	v_mul_f32_e32 v32, v32, v9
	v_mul_f32_e32 v33, v33, v9
	v_cvt_pk_fp8_f32 v36, v20, v21
	v_cvt_pk_fp8_f32 v37, v24, v25
	v_cvt_pk_fp8_f32 v38, v28, v29
	v_cvt_pk_fp8_f32 v39, v32, v33
	v_mul_f32_e32 v22, v22, v9
	v_mul_f32_e32 v23, v23, v9
	v_mul_f32_e32 v26, v26, v9
	v_mul_f32_e32 v27, v27, v9
	v_mul_f32_e32 v30, v30, v9
	v_mul_f32_e32 v31, v31, v9
	v_mul_f32_e32 v34, v34, v9
	v_mul_f32_e32 v9, v35, v9
	v_cvt_pk_fp8_f32 v36, v22, v23 op_sel:[0,0,1]
	v_cvt_pk_fp8_f32 v37, v26, v27 op_sel:[0,0,1]
	v_cvt_pk_fp8_f32 v38, v30, v31 op_sel:[0,0,1]
	v_cvt_pk_fp8_f32 v39, v34, v9 op_sel:[0,0,1]
	v_ashrrev_i32_e32 v9, 31, v8
	v_lshlrev_b64 v[20:21], 10, v[8:9]
	v_lshl_add_u64 v[20:21], v[4:5], 0, v[20:21]
	v_and_b32_e32 v22, 0x3fff, v8
	v_and_b32_e32 v23, 0xffffc000, v8
	v_lshlrev_b32_e32 v23, 10, v23
	v_lshl_add_u32 v23, v22, 7, v23
	v_lshrrev_b32_e32 v24, 3, v176
	v_lshl_add_u32 v23, v24, 21, v23
	v_and_b32_e32 v24, 7, v176
	v_lshl_add_u32 v22, v24, 4, v23
	v_add_u32_e32 v22, 0x180c0000, v22
	v_mov_b32_e32 v23, 0
	v_lshl_add_u64 v[24:25], s[68:69], 0, v[22:23]
	v_and_b32_e32 v26, 0x4000, v8
	v_cmp_ne_u32_e64 s[0:1], 0, v26
	s_nop 1
	v_cndmask_b32_e64 v20, v20, v24, s[0:1]
	v_cndmask_b32_e64 v21, v21, v25, s[0:1]
	global_store_dwordx4 v[20:21], v[36:39], off
	s_and_saveexec_b64 s[0:1], vcc
	s_cbranch_execz .LBB0_66
	v_sub_u32_e32 v2, 0, v2
	v_ldexp_f32 v2, 1.0, v2
	v_lshl_add_u64 v[20:21], v[8:9], 2, s[24:25]
	global_store_dword v[20:21], v2, off
	s_branch .LBB0_66

; #define PH_SYNC(n) run_phase<n>(p, smem); grid.sync();
; __global__ void __launch_bounds__(256, 2) hybrid_fwd(Params p) {
;   __shared__ __attribute__((aligned(16))) char smem[SMEM_BYTES];
;   cg::grid_group grid = cg::this_grid();
;   PH_SYNC(0) PH_SYNC(1) PH_SYNC(2) PH_SYNC(3) PH_SYNC(4) PH_SYNC(5) PH_SYNC(6) PH_SYNC(7)
;   PH_SYNC(8) PH_SYNC(17) PH_SYNC(9) PH_SYNC(10) PH_SYNC(11) PH_SYNC(12) PH_SYNC(13) PH_SYNC(14) PH_SYNC(15)
.LBB0_117:
	s_waitcnt vmcnt(63) expcnt(7) lgkmcnt(15)
	s_add_u32 s90, s90, 1
	s_waitcnt vmcnt(0) lgkmcnt(0)
	s_barrier
	s_and_saveexec_b64 s[8:9], s[0:1]
	s_cbranch_execz .LBB0_127
	buffer_wbl2 sc1
	s_waitcnt vmcnt(0)
	s_add_u32 s10, s68, 0x1e000000
	s_addc_u32 s11, s69, 0
	v_mov_b32_e32 v2, 0
	v_mov_b32_e32 v0, 1
	global_atomic_add v2, v0, s[10:11]
	s_mul_i32 s12, s70, s90
	s_mov_b32 s13, 0
	v_mov_b32_e32 v1, s12

; #define PH_SYNC(n) run_phase<n>(p, smem); grid.sync();
; __global__ void __launch_bounds__(256, 2) hybrid_fwd(Params p) {
;   __shared__ __attribute__((aligned(16))) char smem[SMEM_BYTES];
;   cg::grid_group grid = cg::this_grid();
;   PH_SYNC(0) PH_SYNC(1) PH_SYNC(2) PH_SYNC(3) PH_SYNC(4) PH_SYNC(5) PH_SYNC(6) PH_SYNC(7)
;   PH_SYNC(8) PH_SYNC(17) PH_SYNC(9) PH_SYNC(10) PH_SYNC(11) PH_SYNC(12) PH_SYNC(13) PH_SYNC(14) PH_SYNC(15)
.LBB0_134:
	s_or_b64 exec, exec, s[20:21]
	s_waitcnt lgkmcnt(0)
	s_add_u32 s90, s90, 1
	s_waitcnt vmcnt(0) lgkmcnt(0)
	s_barrier
	s_and_saveexec_b64 s[8:9], s[0:1]
	s_cbranch_execz .LBB0_144
	buffer_wbl2 sc1
	s_waitcnt vmcnt(0)
	s_add_u32 s10, s68, 0x1e000000
	s_addc_u32 s11, s69, 0
	v_mov_b32_e32 v2, 0
	v_mov_b32_e32 v0, 1
	global_atomic_add v2, v0, s[10:11]
	s_mul_i32 s12, s70, s90
	s_mov_b32 s13, 0
	v_mov_b32_e32 v1, s12

; #define PH_SYNC(n) run_phase<n>(p, smem); grid.sync();
; __global__ void __launch_bounds__(256, 2) hybrid_fwd(Params p) {
;   __shared__ __attribute__((aligned(16))) char smem[SMEM_BYTES];
;   cg::grid_group grid = cg::this_grid();
;   PH_SYNC(0) PH_SYNC(1) PH_SYNC(2) PH_SYNC(3) PH_SYNC(4) PH_SYNC(5) PH_SYNC(6) PH_SYNC(7)
;   PH_SYNC(8) PH_SYNC(17) PH_SYNC(9) PH_SYNC(10) PH_SYNC(11) PH_SYNC(12) PH_SYNC(13) PH_SYNC(14) PH_SYNC(15)
.LBB0_350:
	s_waitcnt vmcnt(63) expcnt(7) lgkmcnt(15)
	s_add_u32 s90, s90, 1
	s_waitcnt vmcnt(0) lgkmcnt(0)
	s_barrier
	s_and_saveexec_b64 s[6:7], s[0:1]
	s_cbranch_execz .LBB0_360
	buffer_wbl2 sc1
	s_waitcnt vmcnt(0)
	s_add_u32 s8, s68, 0x1e000000
	s_addc_u32 s9, s69, 0
	v_mov_b32_e32 v2, 0
	v_mov_b32_e32 v0, 1
	global_atomic_add v2, v0, s[8:9]
	s_mul_i32 s10, s70, s90
	s_mov_b32 s11, 0
	v_mov_b32_e32 v1, s10

; #define PH_SYNC(n) run_phase<n>(p, smem); grid.sync();
; __global__ void __launch_bounds__(256, 2) hybrid_fwd(Params p) {
;   __shared__ __attribute__((aligned(16))) char smem[SMEM_BYTES];
;   cg::grid_group grid = cg::this_grid();
;   PH_SYNC(0) PH_SYNC(1) PH_SYNC(2) PH_SYNC(3) PH_SYNC(4) PH_SYNC(5) PH_SYNC(6) PH_SYNC(7)
;   PH_SYNC(8) PH_SYNC(17) PH_SYNC(9) PH_SYNC(10) PH_SYNC(11) PH_SYNC(12) PH_SYNC(13) PH_SYNC(14) PH_SYNC(15)
.LBB0_409:
	s_waitcnt lgkmcnt(0)
	s_add_u32 s90, s90, 1
	s_waitcnt vmcnt(0) lgkmcnt(0)
	s_barrier
	s_and_saveexec_b64 s[6:7], s[0:1]
	s_cbranch_execz .LBB0_419
	buffer_wbl2 sc1
	s_waitcnt vmcnt(0)
	s_add_u32 s8, s68, 0x1e000000
	s_addc_u32 s9, s69, 0
	v_mov_b32_e32 v2, 0
	v_mov_b32_e32 v0, 1
	global_atomic_add v2, v0, s[8:9]
	s_mul_i32 s10, s70, s90
	s_mov_b32 s11, 0
	v_mov_b32_e32 v1, s10

; #define PH_SYNC(n) run_phase<n>(p, smem); grid.sync();
; __global__ void __launch_bounds__(256, 2) hybrid_fwd(Params p) {
;   __shared__ __attribute__((aligned(16))) char smem[SMEM_BYTES];
;   cg::grid_group grid = cg::this_grid();
;   PH_SYNC(0) PH_SYNC(1) PH_SYNC(2) PH_SYNC(3) PH_SYNC(4) PH_SYNC(5) PH_SYNC(6) PH_SYNC(7)
;   PH_SYNC(8) PH_SYNC(17) PH_SYNC(9) PH_SYNC(10) PH_SYNC(11) PH_SYNC(12) PH_SYNC(13) PH_SYNC(14) PH_SYNC(15)
.LBB0_429:
	s_add_u32 s90, s90, 1
	s_waitcnt vmcnt(0) lgkmcnt(0)
	s_barrier
	s_and_saveexec_b64 s[10:11], s[0:1]
	s_cbranch_execz .LBB0_439
	buffer_wbl2 sc1
	s_waitcnt vmcnt(0)
	s_add_u32 s12, s68, 0x1e000000
	s_addc_u32 s13, s69, 0
	v_mov_b32_e32 v2, 0
	v_mov_b32_e32 v0, 1
	global_atomic_add v2, v0, s[12:13]
	s_mul_i32 s14, s70, s90
	s_mov_b32 s15, 0
	v_mov_b32_e32 v1, s14

; #define PH_SYNC(n) run_phase<n>(p, smem); grid.sync();
; __global__ void __launch_bounds__(256, 2) hybrid_fwd(Params p) {
;   __shared__ __attribute__((aligned(16))) char smem[SMEM_BYTES];
;   cg::grid_group grid = cg::this_grid();
;   PH_SYNC(0) PH_SYNC(1) PH_SYNC(2) PH_SYNC(3) PH_SYNC(4) PH_SYNC(5) PH_SYNC(6) PH_SYNC(7)
;   PH_SYNC(8) PH_SYNC(17) PH_SYNC(9) PH_SYNC(10) PH_SYNC(11) PH_SYNC(12) PH_SYNC(13) PH_SYNC(14) PH_SYNC(15)
.LBB0_442:
	s_or_b64 exec, exec, s[10:11]
	s_add_u32 s90, s90, 1
	s_waitcnt vmcnt(0) lgkmcnt(0)
	s_barrier
	s_and_saveexec_b64 s[10:11], s[0:1]
	s_cbranch_execz .LBB0_452
	buffer_wbl2 sc1
	s_waitcnt vmcnt(0)
	s_add_u32 s12, s68, 0x1e000000
	s_addc_u32 s13, s69, 0
	v_mov_b32_e32 v2, 0
	v_mov_b32_e32 v0, 1
	global_atomic_add v2, v0, s[12:13]
	s_mul_i32 s14, s70, s90
	s_mov_b32 s15, 0
	v_mov_b32_e32 v1, s14

; #define PH_SYNC(n) run_phase<n>(p, smem); grid.sync();
; __global__ void __launch_bounds__(256, 2) hybrid_fwd(Params p) {
;   __shared__ __attribute__((aligned(16))) char smem[SMEM_BYTES];
;   cg::grid_group grid = cg::this_grid();
;   PH_SYNC(0) PH_SYNC(1) PH_SYNC(2) PH_SYNC(3) PH_SYNC(4) PH_SYNC(5) PH_SYNC(6) PH_SYNC(7)
;   PH_SYNC(8) PH_SYNC(17) PH_SYNC(9) PH_SYNC(10) PH_SYNC(11) PH_SYNC(12) PH_SYNC(13) PH_SYNC(14) PH_SYNC(15)
.LBB0_464:
	s_waitcnt vmcnt(63) expcnt(7) lgkmcnt(15)
	s_add_u32 s90, s90, 1
	s_waitcnt vmcnt(0) lgkmcnt(0)
	s_barrier
	s_and_saveexec_b64 s[10:11], s[0:1]
	s_cbranch_execz .LBB0_474
	buffer_wbl2 sc1
	s_waitcnt vmcnt(0)
	s_add_u32 s12, s68, 0x1e000000
	s_addc_u32 s13, s69, 0
	v_mov_b32_e32 v2, 0
	v_mov_b32_e32 v0, 1
	global_atomic_add v2, v0, s[12:13]
	s_mul_i32 s14, s70, s90
	s_mov_b32 s15, 0
	v_mov_b32_e32 v1, s14

; #define PH_SYNC(n) run_phase<n>(p, smem); grid.sync();
; __global__ void __launch_bounds__(256, 2) hybrid_fwd(Params p) {
;   __shared__ __attribute__((aligned(16))) char smem[SMEM_BYTES];
;   cg::grid_group grid = cg::this_grid();
;   PH_SYNC(0) PH_SYNC(1) PH_SYNC(2) PH_SYNC(3) PH_SYNC(4) PH_SYNC(5) PH_SYNC(6) PH_SYNC(7)
;   PH_SYNC(8) PH_SYNC(17) PH_SYNC(9) PH_SYNC(10) PH_SYNC(11) PH_SYNC(12) PH_SYNC(13) PH_SYNC(14) PH_SYNC(15)
.LBB0_491:
	s_waitcnt lgkmcnt(0)
	s_add_u32 s90, s90, 1
	s_waitcnt vmcnt(0) lgkmcnt(0)
	s_barrier
	s_and_saveexec_b64 s[10:11], s[0:1]
	s_cbranch_execz .LBB0_501
	buffer_wbl2 sc1
	s_waitcnt vmcnt(0)
	s_add_u32 s12, s68, 0x1e000000
	s_addc_u32 s13, s69, 0
	v_mov_b32_e32 v2, 0
	v_mov_b32_e32 v0, 1
	global_atomic_add v2, v0, s[12:13]
	s_mul_i32 s14, s70, s90
	s_mov_b32 s15, 0
	v_mov_b32_e32 v1, s14

; DI void phase_peer_b(const Params& p, int layer, const float* gnext, bool last) {
;   const int tid = threadIdx.x, lane = tid & 63, wave = tid >> 6;
;   const float* wbuf = (const float*)(p.ws + OFF_R + R_WBUF);
;   const int* ibuf = (const int*)(p.ws + OFF_R + R_IBUF);
;   u16* xnw = (u16*)(p.ws + OFF_XN);
;   float* hbuf = (float*)(p.ws + OFF_H);
;   const unsigned char* EV = (const unsigned char*)(p.ws + OFF_EXP) + (size_t)(layer * 2 + 1) * NEXP * DM;
; #pragma unroll 1
;   for (size_t row = (size_t)blockIdx.x * 4 + wave; row < (size_t)T; row += (size_t)gridDim.x * 4) {
;     const int i0 = ibuf[row * 128 + lane], i1 = ibuf[row * 128 + 64 + lane];
;     const float w0 = wbuf[row * 128 + lane], w1 = wbuf[row * 128 + 64 + lane];
;     float acc[16];
; #pragma unroll
;     for (int i = 0; i < 16; ++i) acc[i] = 0.f;
; #pragma unroll 1
;     for (int bt = 0; bt < 8; ++bt) {
;       u32x4 vr[16];
; #pragma unroll
;       for (int j = 0; j < 16; ++j) {
;         const int e = bt * 16 + j;
;         const int eidx = __builtin_amdgcn_readlane(e < 64 ? i0 : i1, e & 63);
;         vr[j] = *(const u32x4*)(EV + (size_t)eidx * DM + lane * 16);
;       }
.LBB0_501:
	s_or_b64 exec, exec, s[10:11]
	s_add_u32 s58, s68, 0x294a0800
	s_addc_u32 s59, s69, 0
	s_mov_b32 s3, 0
	v_mov_b32_e32 v181, 0
	s_add_u32 s60, s68, 0x2b4b0800
	v_lshl_add_u64 v[192:193], s[2:3], 2, v[180:181]
	s_mov_b64 s[10:11], 0x10080
	s_addc_u32 s61, s69, 0
	v_cmp_gt_u64_e64 s[10:11], s[10:11], v[192:193]
	v_lshlrev_b32_e32 v196, 6, v176
	s_barrier
	s_mov_b64 exec, -1
	v_mbcnt_lo_u32_b32 v165, -1, 0
	v_mbcnt_hi_u32_b32 v165, -1, v165
	v_and_b32_e32 v160, 7, v165
	v_lshlrev_b32_e32 v167, 6, v160
	v_lshlrev_b32_e32 v160, 4, v160
	v_lshrrev_b32_e32 v166, 3, v165
	s_and_b32 s24, s95, 7
	s_lshr_b32 s22, s95, 3
	s_lshr_b32 s23, s70, 3
	s_cmp_ge_u32 s22, s23
	s_cbranch_scc1 .Lpv0_end
	s_lshl_b32 s22, s22, 2
	s_add_u32 s22, s22, s94
	s_lshl_b32 s23, s23, 2
	s_lshl_b32 s25, s24, 21
	s_add_u32 s25, s25, 0x190c0000
	s_add_u32 s14, s68, s25
	s_addc_u32 s15, s69, 0
	s_add_u32 s16, s68, 0x2b4b0800
	s_addc_u32 s17, s69, 0
	s_add_u32 s18, s68, 0x294a0800
	s_addc_u32 s19, s69, 0
	s_lshl_b32 s25, s24, 9
	s_add_u32 s20, s68, s25
	s_addc_u32 s21, s69, 0
	s_cmpk_ge_u32 s22, 0x2010
	s_cbranch_scc1 .Lpv0_end
.Lpv0_item:
	v_mov_b32_e32 v162, s22
	v_lshl_add_u32 v162, v162, 3, v166
	v_lshlrev_b32_e32 v163, 9, v162
	v_lshl_add_u32 v164, v162, 12, v167
	v_mov_b32_e32 v0, 0
	v_mov_b32_e32 v1, 0
	v_mov_b32_e32 v2, 0
	v_mov_b32_e32 v3, 0
	v_mov_b32_e32 v4, 0
	v_mov_b32_e32 v5, 0
	v_mov_b32_e32 v6, 0
	v_mov_b32_e32 v7, 0
	v_mov_b32_e32 v8, 0
	v_mov_b32_e32 v9, 0
	v_mov_b32_e32 v10, 0
	v_mov_b32_e32 v11, 0
	v_mov_b32_e32 v12, 0
	v_mov_b32_e32 v13, 0
	v_mov_b32_e32 v14, 0
	v_mov_b32_e32 v15, 0
	global_load_dwordx4 v[16:19], v163, s[16:17] offset:0
	global_load_dwordx4 v[20:23], v163, s[16:17] offset:16
	global_load_dwordx4 v[24:27], v163, s[16:17] offset:32
	global_load_dwordx4 v[28:31], v163, s[16:17] offset:48
	global_load_dwordx4 v[48:51], v163, s[18:19] offset:0
	global_load_dwordx4 v[52:55], v163, s[18:19] offset:16
	global_load_dwordx4 v[56:59], v163, s[18:19] offset:32
	global_load_dwordx4 v[60:63], v163, s[18:19] offset:48
	global_load_dwordx4 v[32:35], v163, s[16:17] offset:64
	global_load_dwordx4 v[36:39], v163, s[16:17] offset:80
	global_load_dwordx4 v[40:43], v163, s[16:17] offset:96
	global_load_dwordx4 v[44:47], v163, s[16:17] offset:112
	s_waitcnt vmcnt(0)
	v_lshl_add_u32 v161, v16, 7, v160
	global_load_dwordx4 v[80:83], v161, s[14:15]
	v_lshl_add_u32 v161, v17, 7, v160
	global_load_dwordx4 v[84:87], v161, s[14:15]
	v_lshl_add_u32 v161, v18, 7, v160
	global_load_dwordx4 v[88:91], v161, s[14:15]
	v_lshl_add_u32 v161, v19, 7, v160
	global_load_dwordx4 v[92:95], v161, s[14:15]
	v_lshl_add_u32 v161, v20, 7, v160
	global_load_dwordx4 v[96:99], v161, s[14:15]
	v_lshl_add_u32 v161, v21, 7, v160
	global_load_dwordx4 v[100:103], v161, s[14:15]
	v_lshl_add_u32 v161, v22, 7, v160
	global_load_dwordx4 v[104:107], v161, s[14:15]
	v_lshl_add_u32 v161, v23, 7, v160
	global_load_dwordx4 v[108:111], v161, s[14:15]
	v_lshl_add_u32 v161, v24, 7, v160
	global_load_dwordx4 v[112:115], v161, s[14:15]
	v_lshl_add_u32 v161, v25, 7, v160
	global_load_dwordx4 v[116:119], v161, s[14:15]
	v_lshl_add_u32 v161, v26, 7, v160
	global_load_dwordx4 v[120:123], v161, s[14:15]
	v_lshl_add_u32 v161, v27, 7, v160
	global_load_dwordx4 v[124:127], v161, s[14:15]
	v_lshl_add_u32 v161, v28, 7, v160
	global_load_dwordx4 v[128:131], v161, s[14:15]
	v_lshl_add_u32 v161, v29, 7, v160
	global_load_dwordx4 v[132:135], v161, s[14:15]
	v_lshl_add_u32 v161, v30, 7, v160
	global_load_dwordx4 v[136:139], v161, s[14:15]
	v_lshl_add_u32 v161, v31, 7, v160
	global_load_dwordx4 v[140:143], v161, s[14:15]
	global_load_dwordx4 v[16:19], v163, s[16:17] offset:128
	global_load_dwordx4 v[20:23], v163, s[16:17] offset:144
	global_load_dwordx4 v[24:27], v163, s[16:17] offset:160
	global_load_dwordx4 v[28:31], v163, s[16:17] offset:176
	global_load_dwordx4 v[64:67], v163, s[18:19] offset:64
	global_load_dwordx4 v[68:71], v163, s[18:19] offset:80
	global_load_dwordx4 v[72:75], v163, s[18:19] offset:96
	global_load_dwordx4 v[76:79], v163, s[18:19] offset:112
	s_waitcnt vmcnt(23)
	v_cvt_pk_f32_fp8_e32 v[144:145], v80
	v_cvt_pk_f32_fp8_sdwa v[146:147], v80 src0_sel:WORD_1
	v_cvt_pk_f32_fp8_e32 v[148:149], v81
	v_cvt_pk_f32_fp8_sdwa v[150:151], v81 src0_sel:WORD_1
	v_cvt_pk_f32_fp8_e32 v[152:153], v82
	v_cvt_pk_f32_fp8_sdwa v[154:155], v82 src0_sel:WORD_1
	v_cvt_pk_f32_fp8_e32 v[156:157], v83
	v_cvt_pk_f32_fp8_sdwa v[158:159], v83 src0_sel:WORD_1
	v_fmac_f32_e32 v0, v48, v144
	v_fmac_f32_e32 v1, v48, v145
	v_fmac_f32_e32 v2, v48, v146
	v_fmac_f32_e32 v3, v48, v147
	v_fmac_f32_e32 v4, v48, v148
	v_fmac_f32_e32 v5, v48, v149
	v_fmac_f32_e32 v6, v48, v150
	v_fmac_f32_e32 v7, v48, v151
	v_fmac_f32_e32 v8, v48, v152
	v_fmac_f32_e32 v9, v48, v153
	v_fmac_f32_e32 v10, v48, v154
	v_fmac_f32_e32 v11, v48, v155
	v_fmac_f32_e32 v12, v48, v156
	v_fmac_f32_e32 v13, v48, v157
	v_fmac_f32_e32 v14, v48, v158
	v_fmac_f32_e32 v15, v48, v159
	v_lshl_add_u32 v161, v32, 7, v160
	global_load_dwordx4 v[80:83], v161, s[14:15]
	s_waitcnt vmcnt(23)
	v_cvt_pk_f32_fp8_e32 v[144:145], v84
	v_cvt_pk_f32_fp8_sdwa v[146:147], v84 src0_sel:WORD_1
	v_cvt_pk_f32_fp8_e32 v[148:149], v85
	v_cvt_pk_f32_fp8_sdwa v[150:151], v85 src0_sel:WORD_1
	v_cvt_pk_f32_fp8_e32 v[152:153], v86
	v_cvt_pk_f32_fp8_sdwa v[154:155], v86 src0_sel:WORD_1
	v_cvt_pk_f32_fp8_e32 v[156:157], v87
	v_cvt_pk_f32_fp8_sdwa v[158:159], v87 src0_sel:WORD_1
	v_fmac_f32_e32 v0, v49, v144
	v_fmac_f32_e32 v1, v49, v145
	v_fmac_f32_e32 v2, v49, v146
	v_fmac_f32_e32 v3, v49, v147
	v_fmac_f32_e32 v4, v49, v148
	v_fmac_f32_e32 v5, v49, v149
	v_fmac_f32_e32 v6, v49, v150
	v_fmac_f32_e32 v7, v49, v151
	v_fmac_f32_e32 v8, v49, v152
	v_fmac_f32_e32 v9, v49, v153
	v_fmac_f32_e32 v10, v49, v154
	v_fmac_f32_e32 v11, v49, v155
	v_fmac_f32_e32 v12, v49, v156
	v_fmac_f32_e32 v13, v49, v157
	v_fmac_f32_e32 v14, v49, v158
	v_fmac_f32_e32 v15, v49, v159
	v_lshl_add_u32 v161, v33, 7, v160
	global_load_dwordx4 v[84:87], v161, s[14:15]
	s_waitcnt vmcnt(23)
; DI void phase_peer_b(const Params& p, int layer, const float* gnext, bool last) {
;     ...
;     for (int bt = 0; bt < 8; ++bt) {
;       u32x4 vr[16];
; #pragma unroll
;       for (int j = 0; j < 16; ++j) {
;         const int e = bt * 16 + j;
;         const int eidx = __builtin_amdgcn_readlane(e < 64 ? i0 : i1, e & 63);
;         vr[j] = *(const u32x4*)(EV + (size_t)eidx * DM + lane * 16);
;       }
; #pragma unroll
;       for (int j = 0; j < 16; ++j) {
;         const int e = bt * 16 + j;
;         const float wj = __int_as_float(__builtin_amdgcn_readlane(__float_as_int(e < 64 ? w0 : w1), e & 63));
; #pragma unroll
;         for (int w = 0; w < 4; ++w) {
;           const f32x2 lo = __builtin_amdgcn_cvt_pk_f32_fp8((int)vr[j][w], false);
;           const f32x2 hi = __builtin_amdgcn_cvt_pk_f32_fp8((int)vr[j][w], true);
;           acc[4 * w] += wj * lo[0]; acc[4 * w + 1] += wj * lo[1]; acc[4 * w + 2] += wj * hi[0]; acc[4 * w + 3] += wj * hi[1];
;         }
;       }
	v_cvt_pk_f32_fp8_e32 v[144:145], v88
	v_cvt_pk_f32_fp8_sdwa v[146:147], v88 src0_sel:WORD_1
	v_cvt_pk_f32_fp8_e32 v[148:149], v89
	v_cvt_pk_f32_fp8_sdwa v[150:151], v89 src0_sel:WORD_1
	v_cvt_pk_f32_fp8_e32 v[152:153], v90
	v_cvt_pk_f32_fp8_sdwa v[154:155], v90 src0_sel:WORD_1
	v_cvt_pk_f32_fp8_e32 v[156:157], v91
	v_cvt_pk_f32_fp8_sdwa v[158:159], v91 src0_sel:WORD_1
	v_fmac_f32_e32 v0, v50, v144
	v_fmac_f32_e32 v1, v50, v145
	v_fmac_f32_e32 v2, v50, v146
	v_fmac_f32_e32 v3, v50, v147
	v_fmac_f32_e32 v4, v50, v148
	v_fmac_f32_e32 v5, v50, v149
	v_fmac_f32_e32 v6, v50, v150
	v_fmac_f32_e32 v7, v50, v151
	v_fmac_f32_e32 v8, v50, v152
	v_fmac_f32_e32 v9, v50, v153
	v_fmac_f32_e32 v10, v50, v154
	v_fmac_f32_e32 v11, v50, v155
	v_fmac_f32_e32 v12, v50, v156
	v_fmac_f32_e32 v13, v50, v157
	v_fmac_f32_e32 v14, v50, v158
	v_fmac_f32_e32 v15, v50, v159
	v_lshl_add_u32 v161, v34, 7, v160
	global_load_dwordx4 v[88:91], v161, s[14:15]
	s_waitcnt vmcnt(23)
	v_cvt_pk_f32_fp8_e32 v[144:145], v92
	v_cvt_pk_f32_fp8_sdwa v[146:147], v92 src0_sel:WORD_1
	v_cvt_pk_f32_fp8_e32 v[148:149], v93
	v_cvt_pk_f32_fp8_sdwa v[150:151], v93 src0_sel:WORD_1
	v_cvt_pk_f32_fp8_e32 v[152:153], v94
	v_cvt_pk_f32_fp8_sdwa v[154:155], v94 src0_sel:WORD_1
	v_cvt_pk_f32_fp8_e32 v[156:157], v95
	v_cvt_pk_f32_fp8_sdwa v[158:159], v95 src0_sel:WORD_1
	v_fmac_f32_e32 v0, v51, v144
	v_fmac_f32_e32 v1, v51, v145
	v_fmac_f32_e32 v2, v51, v146
	v_fmac_f32_e32 v3, v51, v147
	v_fmac_f32_e32 v4, v51, v148
	v_fmac_f32_e32 v5, v51, v149
	v_fmac_f32_e32 v6, v51, v150
	v_fmac_f32_e32 v7, v51, v151
	v_fmac_f32_e32 v8, v51, v152
	v_fmac_f32_e32 v9, v51, v153
	v_fmac_f32_e32 v10, v51, v154
	v_fmac_f32_e32 v11, v51, v155
	v_fmac_f32_e32 v12, v51, v156
	v_fmac_f32_e32 v13, v51, v157
	v_fmac_f32_e32 v14, v51, v158
	v_fmac_f32_e32 v15, v51, v159
	v_lshl_add_u32 v161, v35, 7, v160
	global_load_dwordx4 v[92:95], v161, s[14:15]
	s_waitcnt vmcnt(23)
	v_cvt_pk_f32_fp8_e32 v[144:145], v96
	v_cvt_pk_f32_fp8_sdwa v[146:147], v96 src0_sel:WORD_1
	v_cvt_pk_f32_fp8_e32 v[148:149], v97
	v_cvt_pk_f32_fp8_sdwa v[150:151], v97 src0_sel:WORD_1
	v_cvt_pk_f32_fp8_e32 v[152:153], v98
	v_cvt_pk_f32_fp8_sdwa v[154:155], v98 src0_sel:WORD_1
	v_cvt_pk_f32_fp8_e32 v[156:157], v99
	v_cvt_pk_f32_fp8_sdwa v[158:159], v99 src0_sel:WORD_1
	v_fmac_f32_e32 v0, v52, v144
	v_fmac_f32_e32 v1, v52, v145
	v_fmac_f32_e32 v2, v52, v146
	v_fmac_f32_e32 v3, v52, v147
	v_fmac_f32_e32 v4, v52, v148
	v_fmac_f32_e32 v5, v52, v149
	v_fmac_f32_e32 v6, v52, v150
	v_fmac_f32_e32 v7, v52, v151
	v_fmac_f32_e32 v8, v52, v152
	v_fmac_f32_e32 v9, v52, v153
	v_fmac_f32_e32 v10, v52, v154
	v_fmac_f32_e32 v11, v52, v155
	v_fmac_f32_e32 v12, v52, v156
	v_fmac_f32_e32 v13, v52, v157
	v_fmac_f32_e32 v14, v52, v158
	v_fmac_f32_e32 v15, v52, v159
	v_lshl_add_u32 v161, v36, 7, v160
	global_load_dwordx4 v[96:99], v161, s[14:15]
	s_waitcnt vmcnt(23)
	v_cvt_pk_f32_fp8_e32 v[144:145], v100
	v_cvt_pk_f32_fp8_sdwa v[146:147], v100 src0_sel:WORD_1
	v_cvt_pk_f32_fp8_e32 v[148:149], v101
	v_cvt_pk_f32_fp8_sdwa v[150:151], v101 src0_sel:WORD_1
	v_cvt_pk_f32_fp8_e32 v[152:153], v102
	v_cvt_pk_f32_fp8_sdwa v[154:155], v102 src0_sel:WORD_1
	v_cvt_pk_f32_fp8_e32 v[156:157], v103
	v_cvt_pk_f32_fp8_sdwa v[158:159], v103 src0_sel:WORD_1
	v_fmac_f32_e32 v0, v53, v144
	v_fmac_f32_e32 v1, v53, v145
	v_fmac_f32_e32 v2, v53, v146
	v_fmac_f32_e32 v3, v53, v147
	v_fmac_f32_e32 v4, v53, v148
	v_fmac_f32_e32 v5, v53, v149
	v_fmac_f32_e32 v6, v53, v150
	v_fmac_f32_e32 v7, v53, v151
	v_fmac_f32_e32 v8, v53, v152
	v_fmac_f32_e32 v9, v53, v153
	v_fmac_f32_e32 v10, v53, v154
	v_fmac_f32_e32 v11, v53, v155
	v_fmac_f32_e32 v12, v53, v156
	v_fmac_f32_e32 v13, v53, v157
	v_fmac_f32_e32 v14, v53, v158
	v_fmac_f32_e32 v15, v53, v159
	v_lshl_add_u32 v161, v37, 7, v160
	global_load_dwordx4 v[100:103], v161, s[14:15]
	s_waitcnt vmcnt(23)
	v_cvt_pk_f32_fp8_e32 v[144:145], v104
	v_cvt_pk_f32_fp8_sdwa v[146:147], v104 src0_sel:WORD_1
	v_cvt_pk_f32_fp8_e32 v[148:149], v105
	v_cvt_pk_f32_fp8_sdwa v[150:151], v105 src0_sel:WORD_1
	v_cvt_pk_f32_fp8_e32 v[152:153], v106
	v_cvt_pk_f32_fp8_sdwa v[154:155], v106 src0_sel:WORD_1
	v_cvt_pk_f32_fp8_e32 v[156:157], v107
	v_cvt_pk_f32_fp8_sdwa v[158:159], v107 src0_sel:WORD_1
	v_fmac_f32_e32 v0, v54, v144
	v_fmac_f32_e32 v1, v54, v145
	v_fmac_f32_e32 v2, v54, v146
	v_fmac_f32_e32 v3, v54, v147
	v_fmac_f32_e32 v4, v54, v148
	v_fmac_f32_e32 v5, v54, v149
	v_fmac_f32_e32 v6, v54, v150
	v_fmac_f32_e32 v7, v54, v151
	v_fmac_f32_e32 v8, v54, v152
	v_fmac_f32_e32 v9, v54, v153
	v_fmac_f32_e32 v10, v54, v154
	v_fmac_f32_e32 v11, v54, v155
	v_fmac_f32_e32 v12, v54, v156
	v_fmac_f32_e32 v13, v54, v157
	v_fmac_f32_e32 v14, v54, v158
	v_fmac_f32_e32 v15, v54, v159
	v_lshl_add_u32 v161, v38, 7, v160
	global_load_dwordx4 v[104:107], v161, s[14:15]
	s_waitcnt vmcnt(23)
	v_cvt_pk_f32_fp8_e32 v[144:145], v108
	v_cvt_pk_f32_fp8_sdwa v[146:147], v108 src0_sel:WORD_1
	v_cvt_pk_f32_fp8_e32 v[148:149], v109
	v_cvt_pk_f32_fp8_sdwa v[150:151], v109 src0_sel:WORD_1
	v_cvt_pk_f32_fp8_e32 v[152:153], v110
	v_cvt_pk_f32_fp8_sdwa v[154:155], v110 src0_sel:WORD_1
	v_cvt_pk_f32_fp8_e32 v[156:157], v111
	v_cvt_pk_f32_fp8_sdwa v[158:159], v111 src0_sel:WORD_1
	v_fmac_f32_e32 v0, v55, v144
	v_fmac_f32_e32 v1, v55, v145
	v_fmac_f32_e32 v2, v55, v146
	v_fmac_f32_e32 v3, v55, v147
	v_fmac_f32_e32 v4, v55, v148
	v_fmac_f32_e32 v5, v55, v149
	v_fmac_f32_e32 v6, v55, v150
	v_fmac_f32_e32 v7, v55, v151
	v_fmac_f32_e32 v8, v55, v152
	v_fmac_f32_e32 v9, v55, v153
	v_fmac_f32_e32 v10, v55, v154
	v_fmac_f32_e32 v11, v55, v155
	v_fmac_f32_e32 v12, v55, v156
	v_fmac_f32_e32 v13, v55, v157
	v_fmac_f32_e32 v14, v55, v158
	v_fmac_f32_e32 v15, v55, v159
	v_lshl_add_u32 v161, v39, 7, v160
	global_load_dwordx4 v[108:111], v161, s[14:15]
	s_waitcnt vmcnt(23)
; DI void phase_peer_b(const Params& p, int layer, const float* gnext, bool last) {
;     ...
;     for (int bt = 0; bt < 8; ++bt) {
;       u32x4 vr[16];
; #pragma unroll
;       for (int j = 0; j < 16; ++j) {
;         const int e = bt * 16 + j;
;         const int eidx = __builtin_amdgcn_readlane(e < 64 ? i0 : i1, e & 63);
;         vr[j] = *(const u32x4*)(EV + (size_t)eidx * DM + lane * 16);
;       }
; #pragma unroll
;       for (int j = 0; j < 16; ++j) {
;         const int e = bt * 16 + j;
;         const float wj = __int_as_float(__builtin_amdgcn_readlane(__float_as_int(e < 64 ? w0 : w1), e & 63));
; #pragma unroll
;         for (int w = 0; w < 4; ++w) {
;           const f32x2 lo = __builtin_amdgcn_cvt_pk_f32_fp8((int)vr[j][w], false);
;           const f32x2 hi = __builtin_amdgcn_cvt_pk_f32_fp8((int)vr[j][w], true);
;           acc[4 * w] += wj * lo[0]; acc[4 * w + 1] += wj * lo[1]; acc[4 * w + 2] += wj * hi[0]; acc[4 * w + 3] += wj * hi[1];
;         }
;       }
	v_cvt_pk_f32_fp8_e32 v[144:145], v112
	v_cvt_pk_f32_fp8_sdwa v[146:147], v112 src0_sel:WORD_1
	v_cvt_pk_f32_fp8_e32 v[148:149], v113
	v_cvt_pk_f32_fp8_sdwa v[150:151], v113 src0_sel:WORD_1
	v_cvt_pk_f32_fp8_e32 v[152:153], v114
	v_cvt_pk_f32_fp8_sdwa v[154:155], v114 src0_sel:WORD_1
	v_cvt_pk_f32_fp8_e32 v[156:157], v115
	v_cvt_pk_f32_fp8_sdwa v[158:159], v115 src0_sel:WORD_1
	v_fmac_f32_e32 v0, v56, v144
	v_fmac_f32_e32 v1, v56, v145
	v_fmac_f32_e32 v2, v56, v146
	v_fmac_f32_e32 v3, v56, v147
	v_fmac_f32_e32 v4, v56, v148
	v_fmac_f32_e32 v5, v56, v149
	v_fmac_f32_e32 v6, v56, v150
	v_fmac_f32_e32 v7, v56, v151
	v_fmac_f32_e32 v8, v56, v152
	v_fmac_f32_e32 v9, v56, v153
	v_fmac_f32_e32 v10, v56, v154
	v_fmac_f32_e32 v11, v56, v155
	v_fmac_f32_e32 v12, v56, v156
	v_fmac_f32_e32 v13, v56, v157
	v_fmac_f32_e32 v14, v56, v158
	v_fmac_f32_e32 v15, v56, v159
	v_lshl_add_u32 v161, v40, 7, v160
	global_load_dwordx4 v[112:115], v161, s[14:15]
	s_waitcnt vmcnt(23)
	v_cvt_pk_f32_fp8_e32 v[144:145], v116
	v_cvt_pk_f32_fp8_sdwa v[146:147], v116 src0_sel:WORD_1
	v_cvt_pk_f32_fp8_e32 v[148:149], v117
	v_cvt_pk_f32_fp8_sdwa v[150:151], v117 src0_sel:WORD_1
	v_cvt_pk_f32_fp8_e32 v[152:153], v118
	v_cvt_pk_f32_fp8_sdwa v[154:155], v118 src0_sel:WORD_1
	v_cvt_pk_f32_fp8_e32 v[156:157], v119
	v_cvt_pk_f32_fp8_sdwa v[158:159], v119 src0_sel:WORD_1
	v_fmac_f32_e32 v0, v57, v144
	v_fmac_f32_e32 v1, v57, v145
	v_fmac_f32_e32 v2, v57, v146
	v_fmac_f32_e32 v3, v57, v147
	v_fmac_f32_e32 v4, v57, v148
	v_fmac_f32_e32 v5, v57, v149
	v_fmac_f32_e32 v6, v57, v150
	v_fmac_f32_e32 v7, v57, v151
	v_fmac_f32_e32 v8, v57, v152
	v_fmac_f32_e32 v9, v57, v153
	v_fmac_f32_e32 v10, v57, v154
	v_fmac_f32_e32 v11, v57, v155
	v_fmac_f32_e32 v12, v57, v156
	v_fmac_f32_e32 v13, v57, v157
	v_fmac_f32_e32 v14, v57, v158
	v_fmac_f32_e32 v15, v57, v159
	v_lshl_add_u32 v161, v41, 7, v160
	global_load_dwordx4 v[116:119], v161, s[14:15]
	s_waitcnt vmcnt(23)
	v_cvt_pk_f32_fp8_e32 v[144:145], v120
	v_cvt_pk_f32_fp8_sdwa v[146:147], v120 src0_sel:WORD_1
	v_cvt_pk_f32_fp8_e32 v[148:149], v121
	v_cvt_pk_f32_fp8_sdwa v[150:151], v121 src0_sel:WORD_1
	v_cvt_pk_f32_fp8_e32 v[152:153], v122
	v_cvt_pk_f32_fp8_sdwa v[154:155], v122 src0_sel:WORD_1
	v_cvt_pk_f32_fp8_e32 v[156:157], v123
	v_cvt_pk_f32_fp8_sdwa v[158:159], v123 src0_sel:WORD_1
	v_fmac_f32_e32 v0, v58, v144
	v_fmac_f32_e32 v1, v58, v145
	v_fmac_f32_e32 v2, v58, v146
	v_fmac_f32_e32 v3, v58, v147
	v_fmac_f32_e32 v4, v58, v148
	v_fmac_f32_e32 v5, v58, v149
	v_fmac_f32_e32 v6, v58, v150
	v_fmac_f32_e32 v7, v58, v151
	v_fmac_f32_e32 v8, v58, v152
	v_fmac_f32_e32 v9, v58, v153
	v_fmac_f32_e32 v10, v58, v154
	v_fmac_f32_e32 v11, v58, v155
	v_fmac_f32_e32 v12, v58, v156
	v_fmac_f32_e32 v13, v58, v157
	v_fmac_f32_e32 v14, v58, v158
	v_fmac_f32_e32 v15, v58, v159
	v_lshl_add_u32 v161, v42, 7, v160
	global_load_dwordx4 v[120:123], v161, s[14:15]
	s_waitcnt vmcnt(23)
	v_cvt_pk_f32_fp8_e32 v[144:145], v124
	v_cvt_pk_f32_fp8_sdwa v[146:147], v124 src0_sel:WORD_1
	v_cvt_pk_f32_fp8_e32 v[148:149], v125
	v_cvt_pk_f32_fp8_sdwa v[150:151], v125 src0_sel:WORD_1
	v_cvt_pk_f32_fp8_e32 v[152:153], v126
	v_cvt_pk_f32_fp8_sdwa v[154:155], v126 src0_sel:WORD_1
	v_cvt_pk_f32_fp8_e32 v[156:157], v127
	v_cvt_pk_f32_fp8_sdwa v[158:159], v127 src0_sel:WORD_1
	v_fmac_f32_e32 v0, v59, v144
	v_fmac_f32_e32 v1, v59, v145
	v_fmac_f32_e32 v2, v59, v146
	v_fmac_f32_e32 v3, v59, v147
	v_fmac_f32_e32 v4, v59, v148
	v_fmac_f32_e32 v5, v59, v149
	v_fmac_f32_e32 v6, v59, v150
	v_fmac_f32_e32 v7, v59, v151
	v_fmac_f32_e32 v8, v59, v152
	v_fmac_f32_e32 v9, v59, v153
	v_fmac_f32_e32 v10, v59, v154
	v_fmac_f32_e32 v11, v59, v155
	v_fmac_f32_e32 v12, v59, v156
	v_fmac_f32_e32 v13, v59, v157
	v_fmac_f32_e32 v14, v59, v158
	v_fmac_f32_e32 v15, v59, v159
	v_lshl_add_u32 v161, v43, 7, v160
	global_load_dwordx4 v[124:127], v161, s[14:15]
	s_waitcnt vmcnt(23)
	v_cvt_pk_f32_fp8_e32 v[144:145], v128
	v_cvt_pk_f32_fp8_sdwa v[146:147], v128 src0_sel:WORD_1
	v_cvt_pk_f32_fp8_e32 v[148:149], v129
	v_cvt_pk_f32_fp8_sdwa v[150:151], v129 src0_sel:WORD_1
	v_cvt_pk_f32_fp8_e32 v[152:153], v130
	v_cvt_pk_f32_fp8_sdwa v[154:155], v130 src0_sel:WORD_1
	v_cvt_pk_f32_fp8_e32 v[156:157], v131
	v_cvt_pk_f32_fp8_sdwa v[158:159], v131 src0_sel:WORD_1
	v_fmac_f32_e32 v0, v60, v144
	v_fmac_f32_e32 v1, v60, v145
	v_fmac_f32_e32 v2, v60, v146
	v_fmac_f32_e32 v3, v60, v147
	v_fmac_f32_e32 v4, v60, v148
	v_fmac_f32_e32 v5, v60, v149
	v_fmac_f32_e32 v6, v60, v150
	v_fmac_f32_e32 v7, v60, v151
	v_fmac_f32_e32 v8, v60, v152
	v_fmac_f32_e32 v9, v60, v153
	v_fmac_f32_e32 v10, v60, v154
	v_fmac_f32_e32 v11, v60, v155
	v_fmac_f32_e32 v12, v60, v156
	v_fmac_f32_e32 v13, v60, v157
	v_fmac_f32_e32 v14, v60, v158
	v_fmac_f32_e32 v15, v60, v159
	v_lshl_add_u32 v161, v44, 7, v160
	global_load_dwordx4 v[128:131], v161, s[14:15]
	s_waitcnt vmcnt(23)
	v_cvt_pk_f32_fp8_e32 v[144:145], v132
	v_cvt_pk_f32_fp8_sdwa v[146:147], v132 src0_sel:WORD_1
	v_cvt_pk_f32_fp8_e32 v[148:149], v133
	v_cvt_pk_f32_fp8_sdwa v[150:151], v133 src0_sel:WORD_1
	v_cvt_pk_f32_fp8_e32 v[152:153], v134
	v_cvt_pk_f32_fp8_sdwa v[154:155], v134 src0_sel:WORD_1
	v_cvt_pk_f32_fp8_e32 v[156:157], v135
	v_cvt_pk_f32_fp8_sdwa v[158:159], v135 src0_sel:WORD_1
	v_fmac_f32_e32 v0, v61, v144
	v_fmac_f32_e32 v1, v61, v145
	v_fmac_f32_e32 v2, v61, v146
	v_fmac_f32_e32 v3, v61, v147
	v_fmac_f32_e32 v4, v61, v148
	v_fmac_f32_e32 v5, v61, v149
	v_fmac_f32_e32 v6, v61, v150
	v_fmac_f32_e32 v7, v61, v151
	v_fmac_f32_e32 v8, v61, v152
	v_fmac_f32_e32 v9, v61, v153
	v_fmac_f32_e32 v10, v61, v154
	v_fmac_f32_e32 v11, v61, v155
	v_fmac_f32_e32 v12, v61, v156
	v_fmac_f32_e32 v13, v61, v157
	v_fmac_f32_e32 v14, v61, v158
	v_fmac_f32_e32 v15, v61, v159
	v_lshl_add_u32 v161, v45, 7, v160
	global_load_dwordx4 v[132:135], v161, s[14:15]
	s_waitcnt vmcnt(23)
; DI void phase_peer_b(const Params& p, int layer, const float* gnext, bool last) {
;     ...
;     for (int bt = 0; bt < 8; ++bt) {
;       u32x4 vr[16];
; #pragma unroll
;       for (int j = 0; j < 16; ++j) {
;         const int e = bt * 16 + j;
;         const int eidx = __builtin_amdgcn_readlane(e < 64 ? i0 : i1, e & 63);
;         vr[j] = *(const u32x4*)(EV + (size_t)eidx * DM + lane * 16);
;       }
; #pragma unroll
;       for (int j = 0; j < 16; ++j) {
;         const int e = bt * 16 + j;
;         const float wj = __int_as_float(__builtin_amdgcn_readlane(__float_as_int(e < 64 ? w0 : w1), e & 63));
; #pragma unroll
;         for (int w = 0; w < 4; ++w) {
;           const f32x2 lo = __builtin_amdgcn_cvt_pk_f32_fp8((int)vr[j][w], false);
;           const f32x2 hi = __builtin_amdgcn_cvt_pk_f32_fp8((int)vr[j][w], true);
;           acc[4 * w] += wj * lo[0]; acc[4 * w + 1] += wj * lo[1]; acc[4 * w + 2] += wj * hi[0]; acc[4 * w + 3] += wj * hi[1];
;         }
;       }
	v_cvt_pk_f32_fp8_e32 v[144:145], v136
	v_cvt_pk_f32_fp8_sdwa v[146:147], v136 src0_sel:WORD_1
	v_cvt_pk_f32_fp8_e32 v[148:149], v137
	v_cvt_pk_f32_fp8_sdwa v[150:151], v137 src0_sel:WORD_1
	v_cvt_pk_f32_fp8_e32 v[152:153], v138
	v_cvt_pk_f32_fp8_sdwa v[154:155], v138 src0_sel:WORD_1
	v_cvt_pk_f32_fp8_e32 v[156:157], v139
	v_cvt_pk_f32_fp8_sdwa v[158:159], v139 src0_sel:WORD_1
	v_fmac_f32_e32 v0, v62, v144
	v_fmac_f32_e32 v1, v62, v145
	v_fmac_f32_e32 v2, v62, v146
	v_fmac_f32_e32 v3, v62, v147
	v_fmac_f32_e32 v4, v62, v148
	v_fmac_f32_e32 v5, v62, v149
	v_fmac_f32_e32 v6, v62, v150
	v_fmac_f32_e32 v7, v62, v151
	v_fmac_f32_e32 v8, v62, v152
	v_fmac_f32_e32 v9, v62, v153
	v_fmac_f32_e32 v10, v62, v154
	v_fmac_f32_e32 v11, v62, v155
	v_fmac_f32_e32 v12, v62, v156
	v_fmac_f32_e32 v13, v62, v157
	v_fmac_f32_e32 v14, v62, v158
	v_fmac_f32_e32 v15, v62, v159
	v_lshl_add_u32 v161, v46, 7, v160
	global_load_dwordx4 v[136:139], v161, s[14:15]
	s_waitcnt vmcnt(23)
	v_cvt_pk_f32_fp8_e32 v[144:145], v140
	v_cvt_pk_f32_fp8_sdwa v[146:147], v140 src0_sel:WORD_1
	v_cvt_pk_f32_fp8_e32 v[148:149], v141
	v_cvt_pk_f32_fp8_sdwa v[150:151], v141 src0_sel:WORD_1
	v_cvt_pk_f32_fp8_e32 v[152:153], v142
	v_cvt_pk_f32_fp8_sdwa v[154:155], v142 src0_sel:WORD_1
	v_cvt_pk_f32_fp8_e32 v[156:157], v143
	v_cvt_pk_f32_fp8_sdwa v[158:159], v143 src0_sel:WORD_1
	v_fmac_f32_e32 v0, v63, v144
	v_fmac_f32_e32 v1, v63, v145
	v_fmac_f32_e32 v2, v63, v146
	v_fmac_f32_e32 v3, v63, v147
	v_fmac_f32_e32 v4, v63, v148
	v_fmac_f32_e32 v5, v63, v149
	v_fmac_f32_e32 v6, v63, v150
	v_fmac_f32_e32 v7, v63, v151
	v_fmac_f32_e32 v8, v63, v152
	v_fmac_f32_e32 v9, v63, v153
	v_fmac_f32_e32 v10, v63, v154
	v_fmac_f32_e32 v11, v63, v155
	v_fmac_f32_e32 v12, v63, v156
	v_fmac_f32_e32 v13, v63, v157
	v_fmac_f32_e32 v14, v63, v158
	v_fmac_f32_e32 v15, v63, v159
	v_lshl_add_u32 v161, v47, 7, v160
	global_load_dwordx4 v[140:143], v161, s[14:15]
	global_load_dwordx4 v[32:35], v163, s[16:17] offset:192
	global_load_dwordx4 v[36:39], v163, s[16:17] offset:208
	global_load_dwordx4 v[40:43], v163, s[16:17] offset:224
	global_load_dwordx4 v[44:47], v163, s[16:17] offset:240
	global_load_dwordx4 v[48:51], v163, s[18:19] offset:128
	global_load_dwordx4 v[52:55], v163, s[18:19] offset:144
	global_load_dwordx4 v[56:59], v163, s[18:19] offset:160
	global_load_dwordx4 v[60:63], v163, s[18:19] offset:176
	s_waitcnt vmcnt(23)
	v_cvt_pk_f32_fp8_e32 v[144:145], v80
	v_cvt_pk_f32_fp8_sdwa v[146:147], v80 src0_sel:WORD_1
	v_cvt_pk_f32_fp8_e32 v[148:149], v81
	v_cvt_pk_f32_fp8_sdwa v[150:151], v81 src0_sel:WORD_1
	v_cvt_pk_f32_fp8_e32 v[152:153], v82
	v_cvt_pk_f32_fp8_sdwa v[154:155], v82 src0_sel:WORD_1
	v_cvt_pk_f32_fp8_e32 v[156:157], v83
	v_cvt_pk_f32_fp8_sdwa v[158:159], v83 src0_sel:WORD_1
	v_fmac_f32_e32 v0, v64, v144
	v_fmac_f32_e32 v1, v64, v145
	v_fmac_f32_e32 v2, v64, v146
	v_fmac_f32_e32 v3, v64, v147
	v_fmac_f32_e32 v4, v64, v148
	v_fmac_f32_e32 v5, v64, v149
	v_fmac_f32_e32 v6, v64, v150
	v_fmac_f32_e32 v7, v64, v151
	v_fmac_f32_e32 v8, v64, v152
	v_fmac_f32_e32 v9, v64, v153
	v_fmac_f32_e32 v10, v64, v154
	v_fmac_f32_e32 v11, v64, v155
	v_fmac_f32_e32 v12, v64, v156
	v_fmac_f32_e32 v13, v64, v157
	v_fmac_f32_e32 v14, v64, v158
	v_fmac_f32_e32 v15, v64, v159
	v_lshl_add_u32 v161, v16, 7, v160
	global_load_dwordx4 v[80:83], v161, s[14:15]
	s_waitcnt vmcnt(23)
	v_cvt_pk_f32_fp8_e32 v[144:145], v84
	v_cvt_pk_f32_fp8_sdwa v[146:147], v84 src0_sel:WORD_1
	v_cvt_pk_f32_fp8_e32 v[148:149], v85
	v_cvt_pk_f32_fp8_sdwa v[150:151], v85 src0_sel:WORD_1
	v_cvt_pk_f32_fp8_e32 v[152:153], v86
	v_cvt_pk_f32_fp8_sdwa v[154:155], v86 src0_sel:WORD_1
	v_cvt_pk_f32_fp8_e32 v[156:157], v87
	v_cvt_pk_f32_fp8_sdwa v[158:159], v87 src0_sel:WORD_1
	v_fmac_f32_e32 v0, v65, v144
	v_fmac_f32_e32 v1, v65, v145
	v_fmac_f32_e32 v2, v65, v146
	v_fmac_f32_e32 v3, v65, v147
	v_fmac_f32_e32 v4, v65, v148
	v_fmac_f32_e32 v5, v65, v149
	v_fmac_f32_e32 v6, v65, v150
	v_fmac_f32_e32 v7, v65, v151
	v_fmac_f32_e32 v8, v65, v152
	v_fmac_f32_e32 v9, v65, v153
	v_fmac_f32_e32 v10, v65, v154
	v_fmac_f32_e32 v11, v65, v155
	v_fmac_f32_e32 v12, v65, v156
	v_fmac_f32_e32 v13, v65, v157
	v_fmac_f32_e32 v14, v65, v158
	v_fmac_f32_e32 v15, v65, v159
	v_lshl_add_u32 v161, v17, 7, v160
	global_load_dwordx4 v[84:87], v161, s[14:15]
	s_waitcnt vmcnt(23)
	v_cvt_pk_f32_fp8_e32 v[144:145], v88
	v_cvt_pk_f32_fp8_sdwa v[146:147], v88 src0_sel:WORD_1
	v_cvt_pk_f32_fp8_e32 v[148:149], v89
	v_cvt_pk_f32_fp8_sdwa v[150:151], v89 src0_sel:WORD_1
	v_cvt_pk_f32_fp8_e32 v[152:153], v90
	v_cvt_pk_f32_fp8_sdwa v[154:155], v90 src0_sel:WORD_1
	v_cvt_pk_f32_fp8_e32 v[156:157], v91
	v_cvt_pk_f32_fp8_sdwa v[158:159], v91 src0_sel:WORD_1
	v_fmac_f32_e32 v0, v66, v144
	v_fmac_f32_e32 v1, v66, v145
	v_fmac_f32_e32 v2, v66, v146
	v_fmac_f32_e32 v3, v66, v147
	v_fmac_f32_e32 v4, v66, v148
	v_fmac_f32_e32 v5, v66, v149
	v_fmac_f32_e32 v6, v66, v150
	v_fmac_f32_e32 v7, v66, v151
	v_fmac_f32_e32 v8, v66, v152
	v_fmac_f32_e32 v9, v66, v153
	v_fmac_f32_e32 v10, v66, v154
	v_fmac_f32_e32 v11, v66, v155
	v_fmac_f32_e32 v12, v66, v156
	v_fmac_f32_e32 v13, v66, v157
	v_fmac_f32_e32 v14, v66, v158
	v_fmac_f32_e32 v15, v66, v159
	v_lshl_add_u32 v161, v18, 7, v160
	global_load_dwordx4 v[88:91], v161, s[14:15]
	s_waitcnt vmcnt(23)
; DI void phase_peer_b(const Params& p, int layer, const float* gnext, bool last) {
;     ...
;     for (int bt = 0; bt < 8; ++bt) {
;       u32x4 vr[16];
; #pragma unroll
;       for (int j = 0; j < 16; ++j) {
;         const int e = bt * 16 + j;
;         const int eidx = __builtin_amdgcn_readlane(e < 64 ? i0 : i1, e & 63);
;         vr[j] = *(const u32x4*)(EV + (size_t)eidx * DM + lane * 16);
;       }
; #pragma unroll
;       for (int j = 0; j < 16; ++j) {
;         const int e = bt * 16 + j;
;         const float wj = __int_as_float(__builtin_amdgcn_readlane(__float_as_int(e < 64 ? w0 : w1), e & 63));
; #pragma unroll
;         for (int w = 0; w < 4; ++w) {
;           const f32x2 lo = __builtin_amdgcn_cvt_pk_f32_fp8((int)vr[j][w], false);
;           const f32x2 hi = __builtin_amdgcn_cvt_pk_f32_fp8((int)vr[j][w], true);
;           acc[4 * w] += wj * lo[0]; acc[4 * w + 1] += wj * lo[1]; acc[4 * w + 2] += wj * hi[0]; acc[4 * w + 3] += wj * hi[1];
;         }
;       }
	v_cvt_pk_f32_fp8_e32 v[144:145], v92
	v_cvt_pk_f32_fp8_sdwa v[146:147], v92 src0_sel:WORD_1
	v_cvt_pk_f32_fp8_e32 v[148:149], v93
	v_cvt_pk_f32_fp8_sdwa v[150:151], v93 src0_sel:WORD_1
	v_cvt_pk_f32_fp8_e32 v[152:153], v94
	v_cvt_pk_f32_fp8_sdwa v[154:155], v94 src0_sel:WORD_1
	v_cvt_pk_f32_fp8_e32 v[156:157], v95
	v_cvt_pk_f32_fp8_sdwa v[158:159], v95 src0_sel:WORD_1
	v_fmac_f32_e32 v0, v67, v144
	v_fmac_f32_e32 v1, v67, v145
	v_fmac_f32_e32 v2, v67, v146
	v_fmac_f32_e32 v3, v67, v147
	v_fmac_f32_e32 v4, v67, v148
	v_fmac_f32_e32 v5, v67, v149
	v_fmac_f32_e32 v6, v67, v150
	v_fmac_f32_e32 v7, v67, v151
	v_fmac_f32_e32 v8, v67, v152
	v_fmac_f32_e32 v9, v67, v153
	v_fmac_f32_e32 v10, v67, v154
	v_fmac_f32_e32 v11, v67, v155
	v_fmac_f32_e32 v12, v67, v156
	v_fmac_f32_e32 v13, v67, v157
	v_fmac_f32_e32 v14, v67, v158
	v_fmac_f32_e32 v15, v67, v159
	v_lshl_add_u32 v161, v19, 7, v160
	global_load_dwordx4 v[92:95], v161, s[14:15]
	s_waitcnt vmcnt(23)
	v_cvt_pk_f32_fp8_e32 v[144:145], v96
	v_cvt_pk_f32_fp8_sdwa v[146:147], v96 src0_sel:WORD_1
	v_cvt_pk_f32_fp8_e32 v[148:149], v97
	v_cvt_pk_f32_fp8_sdwa v[150:151], v97 src0_sel:WORD_1
	v_cvt_pk_f32_fp8_e32 v[152:153], v98
	v_cvt_pk_f32_fp8_sdwa v[154:155], v98 src0_sel:WORD_1
	v_cvt_pk_f32_fp8_e32 v[156:157], v99
	v_cvt_pk_f32_fp8_sdwa v[158:159], v99 src0_sel:WORD_1
	v_fmac_f32_e32 v0, v68, v144
	v_fmac_f32_e32 v1, v68, v145
	v_fmac_f32_e32 v2, v68, v146
	v_fmac_f32_e32 v3, v68, v147
	v_fmac_f32_e32 v4, v68, v148
	v_fmac_f32_e32 v5, v68, v149
	v_fmac_f32_e32 v6, v68, v150
	v_fmac_f32_e32 v7, v68, v151
	v_fmac_f32_e32 v8, v68, v152
	v_fmac_f32_e32 v9, v68, v153
	v_fmac_f32_e32 v10, v68, v154
	v_fmac_f32_e32 v11, v68, v155
	v_fmac_f32_e32 v12, v68, v156
	v_fmac_f32_e32 v13, v68, v157
	v_fmac_f32_e32 v14, v68, v158
	v_fmac_f32_e32 v15, v68, v159
	v_lshl_add_u32 v161, v20, 7, v160
	global_load_dwordx4 v[96:99], v161, s[14:15]
	s_waitcnt vmcnt(23)
	v_cvt_pk_f32_fp8_e32 v[144:145], v100
	v_cvt_pk_f32_fp8_sdwa v[146:147], v100 src0_sel:WORD_1
	v_cvt_pk_f32_fp8_e32 v[148:149], v101
	v_cvt_pk_f32_fp8_sdwa v[150:151], v101 src0_sel:WORD_1
	v_cvt_pk_f32_fp8_e32 v[152:153], v102
	v_cvt_pk_f32_fp8_sdwa v[154:155], v102 src0_sel:WORD_1
	v_cvt_pk_f32_fp8_e32 v[156:157], v103
	v_cvt_pk_f32_fp8_sdwa v[158:159], v103 src0_sel:WORD_1
	v_fmac_f32_e32 v0, v69, v144
	v_fmac_f32_e32 v1, v69, v145
	v_fmac_f32_e32 v2, v69, v146
	v_fmac_f32_e32 v3, v69, v147
	v_fmac_f32_e32 v4, v69, v148
	v_fmac_f32_e32 v5, v69, v149
	v_fmac_f32_e32 v6, v69, v150
	v_fmac_f32_e32 v7, v69, v151
	v_fmac_f32_e32 v8, v69, v152
	v_fmac_f32_e32 v9, v69, v153
	v_fmac_f32_e32 v10, v69, v154
	v_fmac_f32_e32 v11, v69, v155
	v_fmac_f32_e32 v12, v69, v156
	v_fmac_f32_e32 v13, v69, v157
	v_fmac_f32_e32 v14, v69, v158
	v_fmac_f32_e32 v15, v69, v159
	v_lshl_add_u32 v161, v21, 7, v160
	global_load_dwordx4 v[100:103], v161, s[14:15]
	s_waitcnt vmcnt(23)
	v_cvt_pk_f32_fp8_e32 v[144:145], v104
	v_cvt_pk_f32_fp8_sdwa v[146:147], v104 src0_sel:WORD_1
	v_cvt_pk_f32_fp8_e32 v[148:149], v105
	v_cvt_pk_f32_fp8_sdwa v[150:151], v105 src0_sel:WORD_1
	v_cvt_pk_f32_fp8_e32 v[152:153], v106
	v_cvt_pk_f32_fp8_sdwa v[154:155], v106 src0_sel:WORD_1
	v_cvt_pk_f32_fp8_e32 v[156:157], v107
	v_cvt_pk_f32_fp8_sdwa v[158:159], v107 src0_sel:WORD_1
	v_fmac_f32_e32 v0, v70, v144
	v_fmac_f32_e32 v1, v70, v145
	v_fmac_f32_e32 v2, v70, v146
	v_fmac_f32_e32 v3, v70, v147
	v_fmac_f32_e32 v4, v70, v148
	v_fmac_f32_e32 v5, v70, v149
	v_fmac_f32_e32 v6, v70, v150
	v_fmac_f32_e32 v7, v70, v151
	v_fmac_f32_e32 v8, v70, v152
	v_fmac_f32_e32 v9, v70, v153
	v_fmac_f32_e32 v10, v70, v154
	v_fmac_f32_e32 v11, v70, v155
	v_fmac_f32_e32 v12, v70, v156
	v_fmac_f32_e32 v13, v70, v157
	v_fmac_f32_e32 v14, v70, v158
	v_fmac_f32_e32 v15, v70, v159
	v_lshl_add_u32 v161, v22, 7, v160
	global_load_dwordx4 v[104:107], v161, s[14:15]
	s_waitcnt vmcnt(23)
	v_cvt_pk_f32_fp8_e32 v[144:145], v108
	v_cvt_pk_f32_fp8_sdwa v[146:147], v108 src0_sel:WORD_1
	v_cvt_pk_f32_fp8_e32 v[148:149], v109
	v_cvt_pk_f32_fp8_sdwa v[150:151], v109 src0_sel:WORD_1
	v_cvt_pk_f32_fp8_e32 v[152:153], v110
	v_cvt_pk_f32_fp8_sdwa v[154:155], v110 src0_sel:WORD_1
	v_cvt_pk_f32_fp8_e32 v[156:157], v111
	v_cvt_pk_f32_fp8_sdwa v[158:159], v111 src0_sel:WORD_1
	v_fmac_f32_e32 v0, v71, v144
	v_fmac_f32_e32 v1, v71, v145
	v_fmac_f32_e32 v2, v71, v146
	v_fmac_f32_e32 v3, v71, v147
	v_fmac_f32_e32 v4, v71, v148
	v_fmac_f32_e32 v5, v71, v149
	v_fmac_f32_e32 v6, v71, v150
	v_fmac_f32_e32 v7, v71, v151
	v_fmac_f32_e32 v8, v71, v152
	v_fmac_f32_e32 v9, v71, v153
	v_fmac_f32_e32 v10, v71, v154
	v_fmac_f32_e32 v11, v71, v155
	v_fmac_f32_e32 v12, v71, v156
	v_fmac_f32_e32 v13, v71, v157
	v_fmac_f32_e32 v14, v71, v158
	v_fmac_f32_e32 v15, v71, v159
	v_lshl_add_u32 v161, v23, 7, v160
	global_load_dwordx4 v[108:111], v161, s[14:15]
	s_waitcnt vmcnt(23)
	v_cvt_pk_f32_fp8_e32 v[144:145], v112
	v_cvt_pk_f32_fp8_sdwa v[146:147], v112 src0_sel:WORD_1
	v_cvt_pk_f32_fp8_e32 v[148:149], v113
	v_cvt_pk_f32_fp8_sdwa v[150:151], v113 src0_sel:WORD_1
	v_cvt_pk_f32_fp8_e32 v[152:153], v114
	v_cvt_pk_f32_fp8_sdwa v[154:155], v114 src0_sel:WORD_1
	v_cvt_pk_f32_fp8_e32 v[156:157], v115
	v_cvt_pk_f32_fp8_sdwa v[158:159], v115 src0_sel:WORD_1
	v_fmac_f32_e32 v0, v72, v144
	v_fmac_f32_e32 v1, v72, v145
	v_fmac_f32_e32 v2, v72, v146
	v_fmac_f32_e32 v3, v72, v147
	v_fmac_f32_e32 v4, v72, v148
	v_fmac_f32_e32 v5, v72, v149
	v_fmac_f32_e32 v6, v72, v150
	v_fmac_f32_e32 v7, v72, v151
	v_fmac_f32_e32 v8, v72, v152
	v_fmac_f32_e32 v9, v72, v153
	v_fmac_f32_e32 v10, v72, v154
	v_fmac_f32_e32 v11, v72, v155
	v_fmac_f32_e32 v12, v72, v156
	v_fmac_f32_e32 v13, v72, v157
	v_fmac_f32_e32 v14, v72, v158
	v_fmac_f32_e32 v15, v72, v159
	v_lshl_add_u32 v161, v24, 7, v160
	global_load_dwordx4 v[112:115], v161, s[14:15]
	s_waitcnt vmcnt(23)
; DI void phase_peer_b(const Params& p, int layer, const float* gnext, bool last) {
;     ...
;     for (int bt = 0; bt < 8; ++bt) {
;       u32x4 vr[16];
; #pragma unroll
;       for (int j = 0; j < 16; ++j) {
;         const int e = bt * 16 + j;
;         const int eidx = __builtin_amdgcn_readlane(e < 64 ? i0 : i1, e & 63);
;         vr[j] = *(const u32x4*)(EV + (size_t)eidx * DM + lane * 16);
;       }
; #pragma unroll
;       for (int j = 0; j < 16; ++j) {
;         const int e = bt * 16 + j;
;         const float wj = __int_as_float(__builtin_amdgcn_readlane(__float_as_int(e < 64 ? w0 : w1), e & 63));
; #pragma unroll
;         for (int w = 0; w < 4; ++w) {
;           const f32x2 lo = __builtin_amdgcn_cvt_pk_f32_fp8((int)vr[j][w], false);
;           const f32x2 hi = __builtin_amdgcn_cvt_pk_f32_fp8((int)vr[j][w], true);
;           acc[4 * w] += wj * lo[0]; acc[4 * w + 1] += wj * lo[1]; acc[4 * w + 2] += wj * hi[0]; acc[4 * w + 3] += wj * hi[1];
;         }
;       }
	v_cvt_pk_f32_fp8_e32 v[144:145], v116
	v_cvt_pk_f32_fp8_sdwa v[146:147], v116 src0_sel:WORD_1
	v_cvt_pk_f32_fp8_e32 v[148:149], v117
	v_cvt_pk_f32_fp8_sdwa v[150:151], v117 src0_sel:WORD_1
	v_cvt_pk_f32_fp8_e32 v[152:153], v118
	v_cvt_pk_f32_fp8_sdwa v[154:155], v118 src0_sel:WORD_1
	v_cvt_pk_f32_fp8_e32 v[156:157], v119
	v_cvt_pk_f32_fp8_sdwa v[158:159], v119 src0_sel:WORD_1
	v_fmac_f32_e32 v0, v73, v144
	v_fmac_f32_e32 v1, v73, v145
	v_fmac_f32_e32 v2, v73, v146
	v_fmac_f32_e32 v3, v73, v147
	v_fmac_f32_e32 v4, v73, v148
	v_fmac_f32_e32 v5, v73, v149
	v_fmac_f32_e32 v6, v73, v150
	v_fmac_f32_e32 v7, v73, v151
	v_fmac_f32_e32 v8, v73, v152
	v_fmac_f32_e32 v9, v73, v153
	v_fmac_f32_e32 v10, v73, v154
	v_fmac_f32_e32 v11, v73, v155
	v_fmac_f32_e32 v12, v73, v156
	v_fmac_f32_e32 v13, v73, v157
	v_fmac_f32_e32 v14, v73, v158
	v_fmac_f32_e32 v15, v73, v159
	v_lshl_add_u32 v161, v25, 7, v160
	global_load_dwordx4 v[116:119], v161, s[14:15]
	s_waitcnt vmcnt(23)
	v_cvt_pk_f32_fp8_e32 v[144:145], v120
	v_cvt_pk_f32_fp8_sdwa v[146:147], v120 src0_sel:WORD_1
	v_cvt_pk_f32_fp8_e32 v[148:149], v121
	v_cvt_pk_f32_fp8_sdwa v[150:151], v121 src0_sel:WORD_1
	v_cvt_pk_f32_fp8_e32 v[152:153], v122
	v_cvt_pk_f32_fp8_sdwa v[154:155], v122 src0_sel:WORD_1
	v_cvt_pk_f32_fp8_e32 v[156:157], v123
	v_cvt_pk_f32_fp8_sdwa v[158:159], v123 src0_sel:WORD_1
	v_fmac_f32_e32 v0, v74, v144
	v_fmac_f32_e32 v1, v74, v145
	v_fmac_f32_e32 v2, v74, v146
	v_fmac_f32_e32 v3, v74, v147
	v_fmac_f32_e32 v4, v74, v148
	v_fmac_f32_e32 v5, v74, v149
	v_fmac_f32_e32 v6, v74, v150
	v_fmac_f32_e32 v7, v74, v151
	v_fmac_f32_e32 v8, v74, v152
	v_fmac_f32_e32 v9, v74, v153
	v_fmac_f32_e32 v10, v74, v154
	v_fmac_f32_e32 v11, v74, v155
	v_fmac_f32_e32 v12, v74, v156
	v_fmac_f32_e32 v13, v74, v157
	v_fmac_f32_e32 v14, v74, v158
	v_fmac_f32_e32 v15, v74, v159
	v_lshl_add_u32 v161, v26, 7, v160
	global_load_dwordx4 v[120:123], v161, s[14:15]
	s_waitcnt vmcnt(23)
	v_cvt_pk_f32_fp8_e32 v[144:145], v124
	v_cvt_pk_f32_fp8_sdwa v[146:147], v124 src0_sel:WORD_1
	v_cvt_pk_f32_fp8_e32 v[148:149], v125
	v_cvt_pk_f32_fp8_sdwa v[150:151], v125 src0_sel:WORD_1
	v_cvt_pk_f32_fp8_e32 v[152:153], v126
	v_cvt_pk_f32_fp8_sdwa v[154:155], v126 src0_sel:WORD_1
	v_cvt_pk_f32_fp8_e32 v[156:157], v127
	v_cvt_pk_f32_fp8_sdwa v[158:159], v127 src0_sel:WORD_1
	v_fmac_f32_e32 v0, v75, v144
	v_fmac_f32_e32 v1, v75, v145
	v_fmac_f32_e32 v2, v75, v146
	v_fmac_f32_e32 v3, v75, v147
	v_fmac_f32_e32 v4, v75, v148
	v_fmac_f32_e32 v5, v75, v149
	v_fmac_f32_e32 v6, v75, v150
	v_fmac_f32_e32 v7, v75, v151
	v_fmac_f32_e32 v8, v75, v152
	v_fmac_f32_e32 v9, v75, v153
	v_fmac_f32_e32 v10, v75, v154
	v_fmac_f32_e32 v11, v75, v155
	v_fmac_f32_e32 v12, v75, v156
	v_fmac_f32_e32 v13, v75, v157
	v_fmac_f32_e32 v14, v75, v158
	v_fmac_f32_e32 v15, v75, v159
	v_lshl_add_u32 v161, v27, 7, v160
	global_load_dwordx4 v[124:127], v161, s[14:15]
	s_waitcnt vmcnt(23)
	v_cvt_pk_f32_fp8_e32 v[144:145], v128
	v_cvt_pk_f32_fp8_sdwa v[146:147], v128 src0_sel:WORD_1
	v_cvt_pk_f32_fp8_e32 v[148:149], v129
	v_cvt_pk_f32_fp8_sdwa v[150:151], v129 src0_sel:WORD_1
	v_cvt_pk_f32_fp8_e32 v[152:153], v130
	v_cvt_pk_f32_fp8_sdwa v[154:155], v130 src0_sel:WORD_1
	v_cvt_pk_f32_fp8_e32 v[156:157], v131
	v_cvt_pk_f32_fp8_sdwa v[158:159], v131 src0_sel:WORD_1
	v_fmac_f32_e32 v0, v76, v144
	v_fmac_f32_e32 v1, v76, v145
	v_fmac_f32_e32 v2, v76, v146
	v_fmac_f32_e32 v3, v76, v147
	v_fmac_f32_e32 v4, v76, v148
	v_fmac_f32_e32 v5, v76, v149
	v_fmac_f32_e32 v6, v76, v150
	v_fmac_f32_e32 v7, v76, v151
	v_fmac_f32_e32 v8, v76, v152
	v_fmac_f32_e32 v9, v76, v153
	v_fmac_f32_e32 v10, v76, v154
	v_fmac_f32_e32 v11, v76, v155
	v_fmac_f32_e32 v12, v76, v156
	v_fmac_f32_e32 v13, v76, v157
	v_fmac_f32_e32 v14, v76, v158
	v_fmac_f32_e32 v15, v76, v159
	v_lshl_add_u32 v161, v28, 7, v160
	global_load_dwordx4 v[128:131], v161, s[14:15]
	s_waitcnt vmcnt(23)
	v_cvt_pk_f32_fp8_e32 v[144:145], v132
	v_cvt_pk_f32_fp8_sdwa v[146:147], v132 src0_sel:WORD_1
	v_cvt_pk_f32_fp8_e32 v[148:149], v133
	v_cvt_pk_f32_fp8_sdwa v[150:151], v133 src0_sel:WORD_1
	v_cvt_pk_f32_fp8_e32 v[152:153], v134
	v_cvt_pk_f32_fp8_sdwa v[154:155], v134 src0_sel:WORD_1
	v_cvt_pk_f32_fp8_e32 v[156:157], v135
	v_cvt_pk_f32_fp8_sdwa v[158:159], v135 src0_sel:WORD_1
	v_fmac_f32_e32 v0, v77, v144
	v_fmac_f32_e32 v1, v77, v145
	v_fmac_f32_e32 v2, v77, v146
	v_fmac_f32_e32 v3, v77, v147
	v_fmac_f32_e32 v4, v77, v148
	v_fmac_f32_e32 v5, v77, v149
	v_fmac_f32_e32 v6, v77, v150
	v_fmac_f32_e32 v7, v77, v151
	v_fmac_f32_e32 v8, v77, v152
	v_fmac_f32_e32 v9, v77, v153
	v_fmac_f32_e32 v10, v77, v154
	v_fmac_f32_e32 v11, v77, v155
	v_fmac_f32_e32 v12, v77, v156
	v_fmac_f32_e32 v13, v77, v157
	v_fmac_f32_e32 v14, v77, v158
	v_fmac_f32_e32 v15, v77, v159
	v_lshl_add_u32 v161, v29, 7, v160
	global_load_dwordx4 v[132:135], v161, s[14:15]
	s_waitcnt vmcnt(23)
	v_cvt_pk_f32_fp8_e32 v[144:145], v136
	v_cvt_pk_f32_fp8_sdwa v[146:147], v136 src0_sel:WORD_1
	v_cvt_pk_f32_fp8_e32 v[148:149], v137
	v_cvt_pk_f32_fp8_sdwa v[150:151], v137 src0_sel:WORD_1
	v_cvt_pk_f32_fp8_e32 v[152:153], v138
	v_cvt_pk_f32_fp8_sdwa v[154:155], v138 src0_sel:WORD_1
	v_cvt_pk_f32_fp8_e32 v[156:157], v139
	v_cvt_pk_f32_fp8_sdwa v[158:159], v139 src0_sel:WORD_1
	v_fmac_f32_e32 v0, v78, v144
	v_fmac_f32_e32 v1, v78, v145
	v_fmac_f32_e32 v2, v78, v146
	v_fmac_f32_e32 v3, v78, v147
	v_fmac_f32_e32 v4, v78, v148
	v_fmac_f32_e32 v5, v78, v149
	v_fmac_f32_e32 v6, v78, v150
	v_fmac_f32_e32 v7, v78, v151
	v_fmac_f32_e32 v8, v78, v152
	v_fmac_f32_e32 v9, v78, v153
	v_fmac_f32_e32 v10, v78, v154
	v_fmac_f32_e32 v11, v78, v155
	v_fmac_f32_e32 v12, v78, v156
	v_fmac_f32_e32 v13, v78, v157
	v_fmac_f32_e32 v14, v78, v158
	v_fmac_f32_e32 v15, v78, v159
	v_lshl_add_u32 v161, v30, 7, v160
	global_load_dwordx4 v[136:139], v161, s[14:15]
	s_waitcnt vmcnt(23)
; DI void phase_peer_b(const Params& p, int layer, const float* gnext, bool last) {
;     ...
;     for (int bt = 0; bt < 8; ++bt) {
;       u32x4 vr[16];
; #pragma unroll
;       for (int j = 0; j < 16; ++j) {
;         const int e = bt * 16 + j;
;         const int eidx = __builtin_amdgcn_readlane(e < 64 ? i0 : i1, e & 63);
;         vr[j] = *(const u32x4*)(EV + (size_t)eidx * DM + lane * 16);
;       }
; #pragma unroll
;       for (int j = 0; j < 16; ++j) {
;         const int e = bt * 16 + j;
;         const float wj = __int_as_float(__builtin_amdgcn_readlane(__float_as_int(e < 64 ? w0 : w1), e & 63));
; #pragma unroll
;         for (int w = 0; w < 4; ++w) {
;           const f32x2 lo = __builtin_amdgcn_cvt_pk_f32_fp8((int)vr[j][w], false);
;           const f32x2 hi = __builtin_amdgcn_cvt_pk_f32_fp8((int)vr[j][w], true);
;           acc[4 * w] += wj * lo[0]; acc[4 * w + 1] += wj * lo[1]; acc[4 * w + 2] += wj * hi[0]; acc[4 * w + 3] += wj * hi[1];
;         }
;       }
	v_cvt_pk_f32_fp8_e32 v[144:145], v140
	v_cvt_pk_f32_fp8_sdwa v[146:147], v140 src0_sel:WORD_1
	v_cvt_pk_f32_fp8_e32 v[148:149], v141
	v_cvt_pk_f32_fp8_sdwa v[150:151], v141 src0_sel:WORD_1
	v_cvt_pk_f32_fp8_e32 v[152:153], v142
	v_cvt_pk_f32_fp8_sdwa v[154:155], v142 src0_sel:WORD_1
	v_cvt_pk_f32_fp8_e32 v[156:157], v143
	v_cvt_pk_f32_fp8_sdwa v[158:159], v143 src0_sel:WORD_1
	v_fmac_f32_e32 v0, v79, v144
	v_fmac_f32_e32 v1, v79, v145
	v_fmac_f32_e32 v2, v79, v146
	v_fmac_f32_e32 v3, v79, v147
	v_fmac_f32_e32 v4, v79, v148
	v_fmac_f32_e32 v5, v79, v149
	v_fmac_f32_e32 v6, v79, v150
	v_fmac_f32_e32 v7, v79, v151
	v_fmac_f32_e32 v8, v79, v152
	v_fmac_f32_e32 v9, v79, v153
	v_fmac_f32_e32 v10, v79, v154
	v_fmac_f32_e32 v11, v79, v155
	v_fmac_f32_e32 v12, v79, v156
	v_fmac_f32_e32 v13, v79, v157
	v_fmac_f32_e32 v14, v79, v158
	v_fmac_f32_e32 v15, v79, v159
	v_lshl_add_u32 v161, v31, 7, v160
	global_load_dwordx4 v[140:143], v161, s[14:15]
	global_load_dwordx4 v[16:19], v163, s[16:17] offset:256
	global_load_dwordx4 v[20:23], v163, s[16:17] offset:272
	global_load_dwordx4 v[24:27], v163, s[16:17] offset:288
	global_load_dwordx4 v[28:31], v163, s[16:17] offset:304
	global_load_dwordx4 v[64:67], v163, s[18:19] offset:192
	global_load_dwordx4 v[68:71], v163, s[18:19] offset:208
	global_load_dwordx4 v[72:75], v163, s[18:19] offset:224
	global_load_dwordx4 v[76:79], v163, s[18:19] offset:240
	s_waitcnt vmcnt(23)
	v_cvt_pk_f32_fp8_e32 v[144:145], v80
	v_cvt_pk_f32_fp8_sdwa v[146:147], v80 src0_sel:WORD_1
	v_cvt_pk_f32_fp8_e32 v[148:149], v81
	v_cvt_pk_f32_fp8_sdwa v[150:151], v81 src0_sel:WORD_1
	v_cvt_pk_f32_fp8_e32 v[152:153], v82
	v_cvt_pk_f32_fp8_sdwa v[154:155], v82 src0_sel:WORD_1
	v_cvt_pk_f32_fp8_e32 v[156:157], v83
	v_cvt_pk_f32_fp8_sdwa v[158:159], v83 src0_sel:WORD_1
	v_fmac_f32_e32 v0, v48, v144
	v_fmac_f32_e32 v1, v48, v145
	v_fmac_f32_e32 v2, v48, v146
	v_fmac_f32_e32 v3, v48, v147
	v_fmac_f32_e32 v4, v48, v148
	v_fmac_f32_e32 v5, v48, v149
	v_fmac_f32_e32 v6, v48, v150
	v_fmac_f32_e32 v7, v48, v151
	v_fmac_f32_e32 v8, v48, v152
	v_fmac_f32_e32 v9, v48, v153
	v_fmac_f32_e32 v10, v48, v154
	v_fmac_f32_e32 v11, v48, v155
	v_fmac_f32_e32 v12, v48, v156
	v_fmac_f32_e32 v13, v48, v157
	v_fmac_f32_e32 v14, v48, v158
	v_fmac_f32_e32 v15, v48, v159
	v_lshl_add_u32 v161, v32, 7, v160
	global_load_dwordx4 v[80:83], v161, s[14:15]
	s_waitcnt vmcnt(23)
	v_cvt_pk_f32_fp8_e32 v[144:145], v84
	v_cvt_pk_f32_fp8_sdwa v[146:147], v84 src0_sel:WORD_1
	v_cvt_pk_f32_fp8_e32 v[148:149], v85
	v_cvt_pk_f32_fp8_sdwa v[150:151], v85 src0_sel:WORD_1
	v_cvt_pk_f32_fp8_e32 v[152:153], v86
	v_cvt_pk_f32_fp8_sdwa v[154:155], v86 src0_sel:WORD_1
	v_cvt_pk_f32_fp8_e32 v[156:157], v87
	v_cvt_pk_f32_fp8_sdwa v[158:159], v87 src0_sel:WORD_1
	v_fmac_f32_e32 v0, v49, v144
	v_fmac_f32_e32 v1, v49, v145
	v_fmac_f32_e32 v2, v49, v146
	v_fmac_f32_e32 v3, v49, v147
	v_fmac_f32_e32 v4, v49, v148
	v_fmac_f32_e32 v5, v49, v149
	v_fmac_f32_e32 v6, v49, v150
	v_fmac_f32_e32 v7, v49, v151
	v_fmac_f32_e32 v8, v49, v152
	v_fmac_f32_e32 v9, v49, v153
	v_fmac_f32_e32 v10, v49, v154
	v_fmac_f32_e32 v11, v49, v155
	v_fmac_f32_e32 v12, v49, v156
	v_fmac_f32_e32 v13, v49, v157
	v_fmac_f32_e32 v14, v49, v158
	v_fmac_f32_e32 v15, v49, v159
	v_lshl_add_u32 v161, v33, 7, v160
	global_load_dwordx4 v[84:87], v161, s[14:15]
	s_waitcnt vmcnt(23)
	v_cvt_pk_f32_fp8_e32 v[144:145], v88
	v_cvt_pk_f32_fp8_sdwa v[146:147], v88 src0_sel:WORD_1
	v_cvt_pk_f32_fp8_e32 v[148:149], v89
	v_cvt_pk_f32_fp8_sdwa v[150:151], v89 src0_sel:WORD_1
	v_cvt_pk_f32_fp8_e32 v[152:153], v90
	v_cvt_pk_f32_fp8_sdwa v[154:155], v90 src0_sel:WORD_1
	v_cvt_pk_f32_fp8_e32 v[156:157], v91
	v_cvt_pk_f32_fp8_sdwa v[158:159], v91 src0_sel:WORD_1
	v_fmac_f32_e32 v0, v50, v144
	v_fmac_f32_e32 v1, v50, v145
	v_fmac_f32_e32 v2, v50, v146
	v_fmac_f32_e32 v3, v50, v147
	v_fmac_f32_e32 v4, v50, v148
	v_fmac_f32_e32 v5, v50, v149
	v_fmac_f32_e32 v6, v50, v150
	v_fmac_f32_e32 v7, v50, v151
	v_fmac_f32_e32 v8, v50, v152
	v_fmac_f32_e32 v9, v50, v153
	v_fmac_f32_e32 v10, v50, v154
	v_fmac_f32_e32 v11, v50, v155
	v_fmac_f32_e32 v12, v50, v156
	v_fmac_f32_e32 v13, v50, v157
	v_fmac_f32_e32 v14, v50, v158
	v_fmac_f32_e32 v15, v50, v159
	v_lshl_add_u32 v161, v34, 7, v160
	global_load_dwordx4 v[88:91], v161, s[14:15]
	s_waitcnt vmcnt(23)
	v_cvt_pk_f32_fp8_e32 v[144:145], v92
	v_cvt_pk_f32_fp8_sdwa v[146:147], v92 src0_sel:WORD_1
	v_cvt_pk_f32_fp8_e32 v[148:149], v93
	v_cvt_pk_f32_fp8_sdwa v[150:151], v93 src0_sel:WORD_1
	v_cvt_pk_f32_fp8_e32 v[152:153], v94
	v_cvt_pk_f32_fp8_sdwa v[154:155], v94 src0_sel:WORD_1
	v_cvt_pk_f32_fp8_e32 v[156:157], v95
	v_cvt_pk_f32_fp8_sdwa v[158:159], v95 src0_sel:WORD_1
	v_fmac_f32_e32 v0, v51, v144
	v_fmac_f32_e32 v1, v51, v145
	v_fmac_f32_e32 v2, v51, v146
	v_fmac_f32_e32 v3, v51, v147
	v_fmac_f32_e32 v4, v51, v148
	v_fmac_f32_e32 v5, v51, v149
	v_fmac_f32_e32 v6, v51, v150
	v_fmac_f32_e32 v7, v51, v151
	v_fmac_f32_e32 v8, v51, v152
	v_fmac_f32_e32 v9, v51, v153
	v_fmac_f32_e32 v10, v51, v154
	v_fmac_f32_e32 v11, v51, v155
	v_fmac_f32_e32 v12, v51, v156
	v_fmac_f32_e32 v13, v51, v157
	v_fmac_f32_e32 v14, v51, v158
	v_fmac_f32_e32 v15, v51, v159
	v_lshl_add_u32 v161, v35, 7, v160
	global_load_dwordx4 v[92:95], v161, s[14:15]
	s_waitcnt vmcnt(23)
; DI void phase_peer_b(const Params& p, int layer, const float* gnext, bool last) {
;     ...
;     for (int bt = 0; bt < 8; ++bt) {
;       u32x4 vr[16];
; #pragma unroll
;       for (int j = 0; j < 16; ++j) {
;         const int e = bt * 16 + j;
;         const int eidx = __builtin_amdgcn_readlane(e < 64 ? i0 : i1, e & 63);
;         vr[j] = *(const u32x4*)(EV + (size_t)eidx * DM + lane * 16);
;       }
; #pragma unroll
;       for (int j = 0; j < 16; ++j) {
;         const int e = bt * 16 + j;
;         const float wj = __int_as_float(__builtin_amdgcn_readlane(__float_as_int(e < 64 ? w0 : w1), e & 63));
; #pragma unroll
;         for (int w = 0; w < 4; ++w) {
;           const f32x2 lo = __builtin_amdgcn_cvt_pk_f32_fp8((int)vr[j][w], false);
;           const f32x2 hi = __builtin_amdgcn_cvt_pk_f32_fp8((int)vr[j][w], true);
;           acc[4 * w] += wj * lo[0]; acc[4 * w + 1] += wj * lo[1]; acc[4 * w + 2] += wj * hi[0]; acc[4 * w + 3] += wj * hi[1];
;         }
;       }
	v_cvt_pk_f32_fp8_e32 v[144:145], v96
	v_cvt_pk_f32_fp8_sdwa v[146:147], v96 src0_sel:WORD_1
	v_cvt_pk_f32_fp8_e32 v[148:149], v97
	v_cvt_pk_f32_fp8_sdwa v[150:151], v97 src0_sel:WORD_1
	v_cvt_pk_f32_fp8_e32 v[152:153], v98
	v_cvt_pk_f32_fp8_sdwa v[154:155], v98 src0_sel:WORD_1
	v_cvt_pk_f32_fp8_e32 v[156:157], v99
	v_cvt_pk_f32_fp8_sdwa v[158:159], v99 src0_sel:WORD_1
	v_fmac_f32_e32 v0, v52, v144
	v_fmac_f32_e32 v1, v52, v145
	v_fmac_f32_e32 v2, v52, v146
	v_fmac_f32_e32 v3, v52, v147
	v_fmac_f32_e32 v4, v52, v148
	v_fmac_f32_e32 v5, v52, v149
	v_fmac_f32_e32 v6, v52, v150
	v_fmac_f32_e32 v7, v52, v151
	v_fmac_f32_e32 v8, v52, v152
	v_fmac_f32_e32 v9, v52, v153
	v_fmac_f32_e32 v10, v52, v154
	v_fmac_f32_e32 v11, v52, v155
	v_fmac_f32_e32 v12, v52, v156
	v_fmac_f32_e32 v13, v52, v157
	v_fmac_f32_e32 v14, v52, v158
	v_fmac_f32_e32 v15, v52, v159
	v_lshl_add_u32 v161, v36, 7, v160
	global_load_dwordx4 v[96:99], v161, s[14:15]
	s_waitcnt vmcnt(23)
	v_cvt_pk_f32_fp8_e32 v[144:145], v100
	v_cvt_pk_f32_fp8_sdwa v[146:147], v100 src0_sel:WORD_1
	v_cvt_pk_f32_fp8_e32 v[148:149], v101
	v_cvt_pk_f32_fp8_sdwa v[150:151], v101 src0_sel:WORD_1
	v_cvt_pk_f32_fp8_e32 v[152:153], v102
	v_cvt_pk_f32_fp8_sdwa v[154:155], v102 src0_sel:WORD_1
	v_cvt_pk_f32_fp8_e32 v[156:157], v103
	v_cvt_pk_f32_fp8_sdwa v[158:159], v103 src0_sel:WORD_1
	v_fmac_f32_e32 v0, v53, v144
	v_fmac_f32_e32 v1, v53, v145
	v_fmac_f32_e32 v2, v53, v146
	v_fmac_f32_e32 v3, v53, v147
	v_fmac_f32_e32 v4, v53, v148
	v_fmac_f32_e32 v5, v53, v149
	v_fmac_f32_e32 v6, v53, v150
	v_fmac_f32_e32 v7, v53, v151
	v_fmac_f32_e32 v8, v53, v152
	v_fmac_f32_e32 v9, v53, v153
	v_fmac_f32_e32 v10, v53, v154
	v_fmac_f32_e32 v11, v53, v155
	v_fmac_f32_e32 v12, v53, v156
	v_fmac_f32_e32 v13, v53, v157
	v_fmac_f32_e32 v14, v53, v158
	v_fmac_f32_e32 v15, v53, v159
	v_lshl_add_u32 v161, v37, 7, v160
	global_load_dwordx4 v[100:103], v161, s[14:15]
	s_waitcnt vmcnt(23)
	v_cvt_pk_f32_fp8_e32 v[144:145], v104
	v_cvt_pk_f32_fp8_sdwa v[146:147], v104 src0_sel:WORD_1
	v_cvt_pk_f32_fp8_e32 v[148:149], v105
	v_cvt_pk_f32_fp8_sdwa v[150:151], v105 src0_sel:WORD_1
	v_cvt_pk_f32_fp8_e32 v[152:153], v106
	v_cvt_pk_f32_fp8_sdwa v[154:155], v106 src0_sel:WORD_1
	v_cvt_pk_f32_fp8_e32 v[156:157], v107
	v_cvt_pk_f32_fp8_sdwa v[158:159], v107 src0_sel:WORD_1
	v_fmac_f32_e32 v0, v54, v144
	v_fmac_f32_e32 v1, v54, v145
	v_fmac_f32_e32 v2, v54, v146
	v_fmac_f32_e32 v3, v54, v147
	v_fmac_f32_e32 v4, v54, v148
	v_fmac_f32_e32 v5, v54, v149
	v_fmac_f32_e32 v6, v54, v150
	v_fmac_f32_e32 v7, v54, v151
	v_fmac_f32_e32 v8, v54, v152
	v_fmac_f32_e32 v9, v54, v153
	v_fmac_f32_e32 v10, v54, v154
	v_fmac_f32_e32 v11, v54, v155
	v_fmac_f32_e32 v12, v54, v156
	v_fmac_f32_e32 v13, v54, v157
	v_fmac_f32_e32 v14, v54, v158
	v_fmac_f32_e32 v15, v54, v159
	v_lshl_add_u32 v161, v38, 7, v160
	global_load_dwordx4 v[104:107], v161, s[14:15]
	s_waitcnt vmcnt(23)
	v_cvt_pk_f32_fp8_e32 v[144:145], v108
	v_cvt_pk_f32_fp8_sdwa v[146:147], v108 src0_sel:WORD_1
	v_cvt_pk_f32_fp8_e32 v[148:149], v109
	v_cvt_pk_f32_fp8_sdwa v[150:151], v109 src0_sel:WORD_1
	v_cvt_pk_f32_fp8_e32 v[152:153], v110
	v_cvt_pk_f32_fp8_sdwa v[154:155], v110 src0_sel:WORD_1
	v_cvt_pk_f32_fp8_e32 v[156:157], v111
	v_cvt_pk_f32_fp8_sdwa v[158:159], v111 src0_sel:WORD_1
	v_fmac_f32_e32 v0, v55, v144
	v_fmac_f32_e32 v1, v55, v145
	v_fmac_f32_e32 v2, v55, v146
	v_fmac_f32_e32 v3, v55, v147
	v_fmac_f32_e32 v4, v55, v148
	v_fmac_f32_e32 v5, v55, v149
	v_fmac_f32_e32 v6, v55, v150
	v_fmac_f32_e32 v7, v55, v151
	v_fmac_f32_e32 v8, v55, v152
	v_fmac_f32_e32 v9, v55, v153
	v_fmac_f32_e32 v10, v55, v154
	v_fmac_f32_e32 v11, v55, v155
	v_fmac_f32_e32 v12, v55, v156
	v_fmac_f32_e32 v13, v55, v157
	v_fmac_f32_e32 v14, v55, v158
	v_fmac_f32_e32 v15, v55, v159
	v_lshl_add_u32 v161, v39, 7, v160
	global_load_dwordx4 v[108:111], v161, s[14:15]
	s_waitcnt vmcnt(23)
	v_cvt_pk_f32_fp8_e32 v[144:145], v112
	v_cvt_pk_f32_fp8_sdwa v[146:147], v112 src0_sel:WORD_1
	v_cvt_pk_f32_fp8_e32 v[148:149], v113
	v_cvt_pk_f32_fp8_sdwa v[150:151], v113 src0_sel:WORD_1
	v_cvt_pk_f32_fp8_e32 v[152:153], v114
	v_cvt_pk_f32_fp8_sdwa v[154:155], v114 src0_sel:WORD_1
	v_cvt_pk_f32_fp8_e32 v[156:157], v115
	v_cvt_pk_f32_fp8_sdwa v[158:159], v115 src0_sel:WORD_1
	v_fmac_f32_e32 v0, v56, v144
	v_fmac_f32_e32 v1, v56, v145
	v_fmac_f32_e32 v2, v56, v146
	v_fmac_f32_e32 v3, v56, v147
	v_fmac_f32_e32 v4, v56, v148
	v_fmac_f32_e32 v5, v56, v149
	v_fmac_f32_e32 v6, v56, v150
	v_fmac_f32_e32 v7, v56, v151
	v_fmac_f32_e32 v8, v56, v152
	v_fmac_f32_e32 v9, v56, v153
	v_fmac_f32_e32 v10, v56, v154
	v_fmac_f32_e32 v11, v56, v155
	v_fmac_f32_e32 v12, v56, v156
	v_fmac_f32_e32 v13, v56, v157
	v_fmac_f32_e32 v14, v56, v158
	v_fmac_f32_e32 v15, v56, v159
	v_lshl_add_u32 v161, v40, 7, v160
	global_load_dwordx4 v[112:115], v161, s[14:15]
	s_waitcnt vmcnt(23)
	v_cvt_pk_f32_fp8_e32 v[144:145], v116
	v_cvt_pk_f32_fp8_sdwa v[146:147], v116 src0_sel:WORD_1
	v_cvt_pk_f32_fp8_e32 v[148:149], v117
	v_cvt_pk_f32_fp8_sdwa v[150:151], v117 src0_sel:WORD_1
	v_cvt_pk_f32_fp8_e32 v[152:153], v118
	v_cvt_pk_f32_fp8_sdwa v[154:155], v118 src0_sel:WORD_1
	v_cvt_pk_f32_fp8_e32 v[156:157], v119
	v_cvt_pk_f32_fp8_sdwa v[158:159], v119 src0_sel:WORD_1
	v_fmac_f32_e32 v0, v57, v144
	v_fmac_f32_e32 v1, v57, v145
	v_fmac_f32_e32 v2, v57, v146
	v_fmac_f32_e32 v3, v57, v147
	v_fmac_f32_e32 v4, v57, v148
	v_fmac_f32_e32 v5, v57, v149
	v_fmac_f32_e32 v6, v57, v150
	v_fmac_f32_e32 v7, v57, v151
	v_fmac_f32_e32 v8, v57, v152
	v_fmac_f32_e32 v9, v57, v153
	v_fmac_f32_e32 v10, v57, v154
	v_fmac_f32_e32 v11, v57, v155
	v_fmac_f32_e32 v12, v57, v156
	v_fmac_f32_e32 v13, v57, v157
	v_fmac_f32_e32 v14, v57, v158
	v_fmac_f32_e32 v15, v57, v159
	v_lshl_add_u32 v161, v41, 7, v160
	global_load_dwordx4 v[116:119], v161, s[14:15]
	s_waitcnt vmcnt(23)
; DI void phase_peer_b(const Params& p, int layer, const float* gnext, bool last) {
;     ...
;     for (int bt = 0; bt < 8; ++bt) {
;       u32x4 vr[16];
; #pragma unroll
;       for (int j = 0; j < 16; ++j) {
;         const int e = bt * 16 + j;
;         const int eidx = __builtin_amdgcn_readlane(e < 64 ? i0 : i1, e & 63);
;         vr[j] = *(const u32x4*)(EV + (size_t)eidx * DM + lane * 16);
;       }
; #pragma unroll
;       for (int j = 0; j < 16; ++j) {
;         const int e = bt * 16 + j;
;         const float wj = __int_as_float(__builtin_amdgcn_readlane(__float_as_int(e < 64 ? w0 : w1), e & 63));
; #pragma unroll
;         for (int w = 0; w < 4; ++w) {
;           const f32x2 lo = __builtin_amdgcn_cvt_pk_f32_fp8((int)vr[j][w], false);
;           const f32x2 hi = __builtin_amdgcn_cvt_pk_f32_fp8((int)vr[j][w], true);
;           acc[4 * w] += wj * lo[0]; acc[4 * w + 1] += wj * lo[1]; acc[4 * w + 2] += wj * hi[0]; acc[4 * w + 3] += wj * hi[1];
;         }
;       }
	v_cvt_pk_f32_fp8_e32 v[144:145], v120
	v_cvt_pk_f32_fp8_sdwa v[146:147], v120 src0_sel:WORD_1
	v_cvt_pk_f32_fp8_e32 v[148:149], v121
	v_cvt_pk_f32_fp8_sdwa v[150:151], v121 src0_sel:WORD_1
	v_cvt_pk_f32_fp8_e32 v[152:153], v122
	v_cvt_pk_f32_fp8_sdwa v[154:155], v122 src0_sel:WORD_1
	v_cvt_pk_f32_fp8_e32 v[156:157], v123
	v_cvt_pk_f32_fp8_sdwa v[158:159], v123 src0_sel:WORD_1
	v_fmac_f32_e32 v0, v58, v144
	v_fmac_f32_e32 v1, v58, v145
	v_fmac_f32_e32 v2, v58, v146
	v_fmac_f32_e32 v3, v58, v147
	v_fmac_f32_e32 v4, v58, v148
	v_fmac_f32_e32 v5, v58, v149
	v_fmac_f32_e32 v6, v58, v150
	v_fmac_f32_e32 v7, v58, v151
	v_fmac_f32_e32 v8, v58, v152
	v_fmac_f32_e32 v9, v58, v153
	v_fmac_f32_e32 v10, v58, v154
	v_fmac_f32_e32 v11, v58, v155
	v_fmac_f32_e32 v12, v58, v156
	v_fmac_f32_e32 v13, v58, v157
	v_fmac_f32_e32 v14, v58, v158
	v_fmac_f32_e32 v15, v58, v159
	v_lshl_add_u32 v161, v42, 7, v160
	global_load_dwordx4 v[120:123], v161, s[14:15]
	s_waitcnt vmcnt(23)
	v_cvt_pk_f32_fp8_e32 v[144:145], v124
	v_cvt_pk_f32_fp8_sdwa v[146:147], v124 src0_sel:WORD_1
	v_cvt_pk_f32_fp8_e32 v[148:149], v125
	v_cvt_pk_f32_fp8_sdwa v[150:151], v125 src0_sel:WORD_1
	v_cvt_pk_f32_fp8_e32 v[152:153], v126
	v_cvt_pk_f32_fp8_sdwa v[154:155], v126 src0_sel:WORD_1
	v_cvt_pk_f32_fp8_e32 v[156:157], v127
	v_cvt_pk_f32_fp8_sdwa v[158:159], v127 src0_sel:WORD_1
	v_fmac_f32_e32 v0, v59, v144
	v_fmac_f32_e32 v1, v59, v145
	v_fmac_f32_e32 v2, v59, v146
	v_fmac_f32_e32 v3, v59, v147
	v_fmac_f32_e32 v4, v59, v148
	v_fmac_f32_e32 v5, v59, v149
	v_fmac_f32_e32 v6, v59, v150
	v_fmac_f32_e32 v7, v59, v151
	v_fmac_f32_e32 v8, v59, v152
	v_fmac_f32_e32 v9, v59, v153
	v_fmac_f32_e32 v10, v59, v154
	v_fmac_f32_e32 v11, v59, v155
	v_fmac_f32_e32 v12, v59, v156
	v_fmac_f32_e32 v13, v59, v157
	v_fmac_f32_e32 v14, v59, v158
	v_fmac_f32_e32 v15, v59, v159
	v_lshl_add_u32 v161, v43, 7, v160
	global_load_dwordx4 v[124:127], v161, s[14:15]
	s_waitcnt vmcnt(23)
	v_cvt_pk_f32_fp8_e32 v[144:145], v128
	v_cvt_pk_f32_fp8_sdwa v[146:147], v128 src0_sel:WORD_1
	v_cvt_pk_f32_fp8_e32 v[148:149], v129
	v_cvt_pk_f32_fp8_sdwa v[150:151], v129 src0_sel:WORD_1
	v_cvt_pk_f32_fp8_e32 v[152:153], v130
	v_cvt_pk_f32_fp8_sdwa v[154:155], v130 src0_sel:WORD_1
	v_cvt_pk_f32_fp8_e32 v[156:157], v131
	v_cvt_pk_f32_fp8_sdwa v[158:159], v131 src0_sel:WORD_1
	v_fmac_f32_e32 v0, v60, v144
	v_fmac_f32_e32 v1, v60, v145
	v_fmac_f32_e32 v2, v60, v146
	v_fmac_f32_e32 v3, v60, v147
	v_fmac_f32_e32 v4, v60, v148
	v_fmac_f32_e32 v5, v60, v149
	v_fmac_f32_e32 v6, v60, v150
	v_fmac_f32_e32 v7, v60, v151
	v_fmac_f32_e32 v8, v60, v152
	v_fmac_f32_e32 v9, v60, v153
	v_fmac_f32_e32 v10, v60, v154
	v_fmac_f32_e32 v11, v60, v155
	v_fmac_f32_e32 v12, v60, v156
	v_fmac_f32_e32 v13, v60, v157
	v_fmac_f32_e32 v14, v60, v158
	v_fmac_f32_e32 v15, v60, v159
	v_lshl_add_u32 v161, v44, 7, v160
	global_load_dwordx4 v[128:131], v161, s[14:15]
	s_waitcnt vmcnt(23)
	v_cvt_pk_f32_fp8_e32 v[144:145], v132
	v_cvt_pk_f32_fp8_sdwa v[146:147], v132 src0_sel:WORD_1
	v_cvt_pk_f32_fp8_e32 v[148:149], v133
	v_cvt_pk_f32_fp8_sdwa v[150:151], v133 src0_sel:WORD_1
	v_cvt_pk_f32_fp8_e32 v[152:153], v134
	v_cvt_pk_f32_fp8_sdwa v[154:155], v134 src0_sel:WORD_1
	v_cvt_pk_f32_fp8_e32 v[156:157], v135
	v_cvt_pk_f32_fp8_sdwa v[158:159], v135 src0_sel:WORD_1
	v_fmac_f32_e32 v0, v61, v144
	v_fmac_f32_e32 v1, v61, v145
	v_fmac_f32_e32 v2, v61, v146
	v_fmac_f32_e32 v3, v61, v147
	v_fmac_f32_e32 v4, v61, v148
	v_fmac_f32_e32 v5, v61, v149
	v_fmac_f32_e32 v6, v61, v150
	v_fmac_f32_e32 v7, v61, v151
	v_fmac_f32_e32 v8, v61, v152
	v_fmac_f32_e32 v9, v61, v153
	v_fmac_f32_e32 v10, v61, v154
	v_fmac_f32_e32 v11, v61, v155
	v_fmac_f32_e32 v12, v61, v156
	v_fmac_f32_e32 v13, v61, v157
	v_fmac_f32_e32 v14, v61, v158
	v_fmac_f32_e32 v15, v61, v159
	v_lshl_add_u32 v161, v45, 7, v160
	global_load_dwordx4 v[132:135], v161, s[14:15]
	s_waitcnt vmcnt(23)
	v_cvt_pk_f32_fp8_e32 v[144:145], v136
	v_cvt_pk_f32_fp8_sdwa v[146:147], v136 src0_sel:WORD_1
	v_cvt_pk_f32_fp8_e32 v[148:149], v137
	v_cvt_pk_f32_fp8_sdwa v[150:151], v137 src0_sel:WORD_1
	v_cvt_pk_f32_fp8_e32 v[152:153], v138
	v_cvt_pk_f32_fp8_sdwa v[154:155], v138 src0_sel:WORD_1
	v_cvt_pk_f32_fp8_e32 v[156:157], v139
	v_cvt_pk_f32_fp8_sdwa v[158:159], v139 src0_sel:WORD_1
	v_fmac_f32_e32 v0, v62, v144
	v_fmac_f32_e32 v1, v62, v145
	v_fmac_f32_e32 v2, v62, v146
	v_fmac_f32_e32 v3, v62, v147
	v_fmac_f32_e32 v4, v62, v148
	v_fmac_f32_e32 v5, v62, v149
	v_fmac_f32_e32 v6, v62, v150
	v_fmac_f32_e32 v7, v62, v151
	v_fmac_f32_e32 v8, v62, v152
	v_fmac_f32_e32 v9, v62, v153
	v_fmac_f32_e32 v10, v62, v154
	v_fmac_f32_e32 v11, v62, v155
	v_fmac_f32_e32 v12, v62, v156
	v_fmac_f32_e32 v13, v62, v157
	v_fmac_f32_e32 v14, v62, v158
	v_fmac_f32_e32 v15, v62, v159
	v_lshl_add_u32 v161, v46, 7, v160
	global_load_dwordx4 v[136:139], v161, s[14:15]
	s_waitcnt vmcnt(23)
	v_cvt_pk_f32_fp8_e32 v[144:145], v140
	v_cvt_pk_f32_fp8_sdwa v[146:147], v140 src0_sel:WORD_1
	v_cvt_pk_f32_fp8_e32 v[148:149], v141
	v_cvt_pk_f32_fp8_sdwa v[150:151], v141 src0_sel:WORD_1
	v_cvt_pk_f32_fp8_e32 v[152:153], v142
	v_cvt_pk_f32_fp8_sdwa v[154:155], v142 src0_sel:WORD_1
	v_cvt_pk_f32_fp8_e32 v[156:157], v143
	v_cvt_pk_f32_fp8_sdwa v[158:159], v143 src0_sel:WORD_1
	v_fmac_f32_e32 v0, v63, v144
	v_fmac_f32_e32 v1, v63, v145
	v_fmac_f32_e32 v2, v63, v146
	v_fmac_f32_e32 v3, v63, v147
	v_fmac_f32_e32 v4, v63, v148
	v_fmac_f32_e32 v5, v63, v149
	v_fmac_f32_e32 v6, v63, v150
	v_fmac_f32_e32 v7, v63, v151
	v_fmac_f32_e32 v8, v63, v152
	v_fmac_f32_e32 v9, v63, v153
	v_fmac_f32_e32 v10, v63, v154
	v_fmac_f32_e32 v11, v63, v155
	v_fmac_f32_e32 v12, v63, v156
	v_fmac_f32_e32 v13, v63, v157
	v_fmac_f32_e32 v14, v63, v158
	v_fmac_f32_e32 v15, v63, v159
	v_lshl_add_u32 v161, v47, 7, v160
	global_load_dwordx4 v[140:143], v161, s[14:15]
	global_load_dwordx4 v[32:35], v163, s[16:17] offset:320
	global_load_dwordx4 v[36:39], v163, s[16:17] offset:336
	global_load_dwordx4 v[40:43], v163, s[16:17] offset:352
	global_load_dwordx4 v[44:47], v163, s[16:17] offset:368
	global_load_dwordx4 v[48:51], v163, s[18:19] offset:256
	global_load_dwordx4 v[52:55], v163, s[18:19] offset:272
	global_load_dwordx4 v[56:59], v163, s[18:19] offset:288
	global_load_dwordx4 v[60:63], v163, s[18:19] offset:304
	s_waitcnt vmcnt(23)
; DI void phase_peer_b(const Params& p, int layer, const float* gnext, bool last) {
;     ...
;     for (int bt = 0; bt < 8; ++bt) {
;       u32x4 vr[16];
; #pragma unroll
;       for (int j = 0; j < 16; ++j) {
;         const int e = bt * 16 + j;
;         const int eidx = __builtin_amdgcn_readlane(e < 64 ? i0 : i1, e & 63);
;         vr[j] = *(const u32x4*)(EV + (size_t)eidx * DM + lane * 16);
;       }
; #pragma unroll
;       for (int j = 0; j < 16; ++j) {
;         const int e = bt * 16 + j;
;         const float wj = __int_as_float(__builtin_amdgcn_readlane(__float_as_int(e < 64 ? w0 : w1), e & 63));
; #pragma unroll
;         for (int w = 0; w < 4; ++w) {
;           const f32x2 lo = __builtin_amdgcn_cvt_pk_f32_fp8((int)vr[j][w], false);
;           const f32x2 hi = __builtin_amdgcn_cvt_pk_f32_fp8((int)vr[j][w], true);
;           acc[4 * w] += wj * lo[0]; acc[4 * w + 1] += wj * lo[1]; acc[4 * w + 2] += wj * hi[0]; acc[4 * w + 3] += wj * hi[1];
;         }
;       }
	v_cvt_pk_f32_fp8_e32 v[144:145], v80
	v_cvt_pk_f32_fp8_sdwa v[146:147], v80 src0_sel:WORD_1
	v_cvt_pk_f32_fp8_e32 v[148:149], v81
	v_cvt_pk_f32_fp8_sdwa v[150:151], v81 src0_sel:WORD_1
	v_cvt_pk_f32_fp8_e32 v[152:153], v82
	v_cvt_pk_f32_fp8_sdwa v[154:155], v82 src0_sel:WORD_1
	v_cvt_pk_f32_fp8_e32 v[156:157], v83
	v_cvt_pk_f32_fp8_sdwa v[158:159], v83 src0_sel:WORD_1
	v_fmac_f32_e32 v0, v64, v144
	v_fmac_f32_e32 v1, v64, v145
	v_fmac_f32_e32 v2, v64, v146
	v_fmac_f32_e32 v3, v64, v147
	v_fmac_f32_e32 v4, v64, v148
	v_fmac_f32_e32 v5, v64, v149
	v_fmac_f32_e32 v6, v64, v150
	v_fmac_f32_e32 v7, v64, v151
	v_fmac_f32_e32 v8, v64, v152
	v_fmac_f32_e32 v9, v64, v153
	v_fmac_f32_e32 v10, v64, v154
	v_fmac_f32_e32 v11, v64, v155
	v_fmac_f32_e32 v12, v64, v156
	v_fmac_f32_e32 v13, v64, v157
	v_fmac_f32_e32 v14, v64, v158
	v_fmac_f32_e32 v15, v64, v159
	v_lshl_add_u32 v161, v16, 7, v160
	global_load_dwordx4 v[80:83], v161, s[14:15]
	s_waitcnt vmcnt(23)
	v_cvt_pk_f32_fp8_e32 v[144:145], v84
	v_cvt_pk_f32_fp8_sdwa v[146:147], v84 src0_sel:WORD_1
	v_cvt_pk_f32_fp8_e32 v[148:149], v85
	v_cvt_pk_f32_fp8_sdwa v[150:151], v85 src0_sel:WORD_1
	v_cvt_pk_f32_fp8_e32 v[152:153], v86
	v_cvt_pk_f32_fp8_sdwa v[154:155], v86 src0_sel:WORD_1
	v_cvt_pk_f32_fp8_e32 v[156:157], v87
	v_cvt_pk_f32_fp8_sdwa v[158:159], v87 src0_sel:WORD_1
	v_fmac_f32_e32 v0, v65, v144
	v_fmac_f32_e32 v1, v65, v145
	v_fmac_f32_e32 v2, v65, v146
	v_fmac_f32_e32 v3, v65, v147
	v_fmac_f32_e32 v4, v65, v148
	v_fmac_f32_e32 v5, v65, v149
	v_fmac_f32_e32 v6, v65, v150
	v_fmac_f32_e32 v7, v65, v151
	v_fmac_f32_e32 v8, v65, v152
	v_fmac_f32_e32 v9, v65, v153
	v_fmac_f32_e32 v10, v65, v154
	v_fmac_f32_e32 v11, v65, v155
	v_fmac_f32_e32 v12, v65, v156
	v_fmac_f32_e32 v13, v65, v157
	v_fmac_f32_e32 v14, v65, v158
	v_fmac_f32_e32 v15, v65, v159
	v_lshl_add_u32 v161, v17, 7, v160
	global_load_dwordx4 v[84:87], v161, s[14:15]
	s_waitcnt vmcnt(23)
	v_cvt_pk_f32_fp8_e32 v[144:145], v88
	v_cvt_pk_f32_fp8_sdwa v[146:147], v88 src0_sel:WORD_1
	v_cvt_pk_f32_fp8_e32 v[148:149], v89
	v_cvt_pk_f32_fp8_sdwa v[150:151], v89 src0_sel:WORD_1
	v_cvt_pk_f32_fp8_e32 v[152:153], v90
	v_cvt_pk_f32_fp8_sdwa v[154:155], v90 src0_sel:WORD_1
	v_cvt_pk_f32_fp8_e32 v[156:157], v91
	v_cvt_pk_f32_fp8_sdwa v[158:159], v91 src0_sel:WORD_1
	v_fmac_f32_e32 v0, v66, v144
	v_fmac_f32_e32 v1, v66, v145
	v_fmac_f32_e32 v2, v66, v146
	v_fmac_f32_e32 v3, v66, v147
	v_fmac_f32_e32 v4, v66, v148
	v_fmac_f32_e32 v5, v66, v149
	v_fmac_f32_e32 v6, v66, v150
	v_fmac_f32_e32 v7, v66, v151
	v_fmac_f32_e32 v8, v66, v152
	v_fmac_f32_e32 v9, v66, v153
	v_fmac_f32_e32 v10, v66, v154
	v_fmac_f32_e32 v11, v66, v155
	v_fmac_f32_e32 v12, v66, v156
	v_fmac_f32_e32 v13, v66, v157
	v_fmac_f32_e32 v14, v66, v158
	v_fmac_f32_e32 v15, v66, v159
	v_lshl_add_u32 v161, v18, 7, v160
	global_load_dwordx4 v[88:91], v161, s[14:15]
	s_waitcnt vmcnt(23)
	v_cvt_pk_f32_fp8_e32 v[144:145], v92
	v_cvt_pk_f32_fp8_sdwa v[146:147], v92 src0_sel:WORD_1
	v_cvt_pk_f32_fp8_e32 v[148:149], v93
	v_cvt_pk_f32_fp8_sdwa v[150:151], v93 src0_sel:WORD_1
	v_cvt_pk_f32_fp8_e32 v[152:153], v94
	v_cvt_pk_f32_fp8_sdwa v[154:155], v94 src0_sel:WORD_1
	v_cvt_pk_f32_fp8_e32 v[156:157], v95
	v_cvt_pk_f32_fp8_sdwa v[158:159], v95 src0_sel:WORD_1
	v_fmac_f32_e32 v0, v67, v144
	v_fmac_f32_e32 v1, v67, v145
	v_fmac_f32_e32 v2, v67, v146
	v_fmac_f32_e32 v3, v67, v147
	v_fmac_f32_e32 v4, v67, v148
	v_fmac_f32_e32 v5, v67, v149
	v_fmac_f32_e32 v6, v67, v150
	v_fmac_f32_e32 v7, v67, v151
	v_fmac_f32_e32 v8, v67, v152
	v_fmac_f32_e32 v9, v67, v153
	v_fmac_f32_e32 v10, v67, v154
	v_fmac_f32_e32 v11, v67, v155
	v_fmac_f32_e32 v12, v67, v156
	v_fmac_f32_e32 v13, v67, v157
	v_fmac_f32_e32 v14, v67, v158
	v_fmac_f32_e32 v15, v67, v159
	v_lshl_add_u32 v161, v19, 7, v160
	global_load_dwordx4 v[92:95], v161, s[14:15]
	s_waitcnt vmcnt(23)
	v_cvt_pk_f32_fp8_e32 v[144:145], v96
	v_cvt_pk_f32_fp8_sdwa v[146:147], v96 src0_sel:WORD_1
	v_cvt_pk_f32_fp8_e32 v[148:149], v97
	v_cvt_pk_f32_fp8_sdwa v[150:151], v97 src0_sel:WORD_1
	v_cvt_pk_f32_fp8_e32 v[152:153], v98
	v_cvt_pk_f32_fp8_sdwa v[154:155], v98 src0_sel:WORD_1
	v_cvt_pk_f32_fp8_e32 v[156:157], v99
	v_cvt_pk_f32_fp8_sdwa v[158:159], v99 src0_sel:WORD_1
	v_fmac_f32_e32 v0, v68, v144
	v_fmac_f32_e32 v1, v68, v145
	v_fmac_f32_e32 v2, v68, v146
	v_fmac_f32_e32 v3, v68, v147
	v_fmac_f32_e32 v4, v68, v148
	v_fmac_f32_e32 v5, v68, v149
	v_fmac_f32_e32 v6, v68, v150
	v_fmac_f32_e32 v7, v68, v151
	v_fmac_f32_e32 v8, v68, v152
	v_fmac_f32_e32 v9, v68, v153
	v_fmac_f32_e32 v10, v68, v154
	v_fmac_f32_e32 v11, v68, v155
	v_fmac_f32_e32 v12, v68, v156
	v_fmac_f32_e32 v13, v68, v157
	v_fmac_f32_e32 v14, v68, v158
	v_fmac_f32_e32 v15, v68, v159
	v_lshl_add_u32 v161, v20, 7, v160
	global_load_dwordx4 v[96:99], v161, s[14:15]
	s_waitcnt vmcnt(23)
	v_cvt_pk_f32_fp8_e32 v[144:145], v100
	v_cvt_pk_f32_fp8_sdwa v[146:147], v100 src0_sel:WORD_1
	v_cvt_pk_f32_fp8_e32 v[148:149], v101
	v_cvt_pk_f32_fp8_sdwa v[150:151], v101 src0_sel:WORD_1
	v_cvt_pk_f32_fp8_e32 v[152:153], v102
	v_cvt_pk_f32_fp8_sdwa v[154:155], v102 src0_sel:WORD_1
	v_cvt_pk_f32_fp8_e32 v[156:157], v103
	v_cvt_pk_f32_fp8_sdwa v[158:159], v103 src0_sel:WORD_1
	v_fmac_f32_e32 v0, v69, v144
	v_fmac_f32_e32 v1, v69, v145
	v_fmac_f32_e32 v2, v69, v146
	v_fmac_f32_e32 v3, v69, v147
	v_fmac_f32_e32 v4, v69, v148
	v_fmac_f32_e32 v5, v69, v149
	v_fmac_f32_e32 v6, v69, v150
	v_fmac_f32_e32 v7, v69, v151
	v_fmac_f32_e32 v8, v69, v152
	v_fmac_f32_e32 v9, v69, v153
	v_fmac_f32_e32 v10, v69, v154
	v_fmac_f32_e32 v11, v69, v155
	v_fmac_f32_e32 v12, v69, v156
	v_fmac_f32_e32 v13, v69, v157
	v_fmac_f32_e32 v14, v69, v158
	v_fmac_f32_e32 v15, v69, v159
	v_lshl_add_u32 v161, v21, 7, v160
	global_load_dwordx4 v[100:103], v161, s[14:15]
	s_waitcnt vmcnt(23)
; DI void phase_peer_b(const Params& p, int layer, const float* gnext, bool last) {
;     ...
;     for (int bt = 0; bt < 8; ++bt) {
;       u32x4 vr[16];
; #pragma unroll
;       for (int j = 0; j < 16; ++j) {
;         const int e = bt * 16 + j;
;         const int eidx = __builtin_amdgcn_readlane(e < 64 ? i0 : i1, e & 63);
;         vr[j] = *(const u32x4*)(EV + (size_t)eidx * DM + lane * 16);
;       }
; #pragma unroll
;       for (int j = 0; j < 16; ++j) {
;         const int e = bt * 16 + j;
;         const float wj = __int_as_float(__builtin_amdgcn_readlane(__float_as_int(e < 64 ? w0 : w1), e & 63));
; #pragma unroll
;         for (int w = 0; w < 4; ++w) {
;           const f32x2 lo = __builtin_amdgcn_cvt_pk_f32_fp8((int)vr[j][w], false);
;           const f32x2 hi = __builtin_amdgcn_cvt_pk_f32_fp8((int)vr[j][w], true);
;           acc[4 * w] += wj * lo[0]; acc[4 * w + 1] += wj * lo[1]; acc[4 * w + 2] += wj * hi[0]; acc[4 * w + 3] += wj * hi[1];
;         }
;       }
	v_cvt_pk_f32_fp8_e32 v[144:145], v104
	v_cvt_pk_f32_fp8_sdwa v[146:147], v104 src0_sel:WORD_1
	v_cvt_pk_f32_fp8_e32 v[148:149], v105
	v_cvt_pk_f32_fp8_sdwa v[150:151], v105 src0_sel:WORD_1
	v_cvt_pk_f32_fp8_e32 v[152:153], v106
	v_cvt_pk_f32_fp8_sdwa v[154:155], v106 src0_sel:WORD_1
	v_cvt_pk_f32_fp8_e32 v[156:157], v107
	v_cvt_pk_f32_fp8_sdwa v[158:159], v107 src0_sel:WORD_1
	v_fmac_f32_e32 v0, v70, v144
	v_fmac_f32_e32 v1, v70, v145
	v_fmac_f32_e32 v2, v70, v146
	v_fmac_f32_e32 v3, v70, v147
	v_fmac_f32_e32 v4, v70, v148
	v_fmac_f32_e32 v5, v70, v149
	v_fmac_f32_e32 v6, v70, v150
	v_fmac_f32_e32 v7, v70, v151
	v_fmac_f32_e32 v8, v70, v152
	v_fmac_f32_e32 v9, v70, v153
	v_fmac_f32_e32 v10, v70, v154
	v_fmac_f32_e32 v11, v70, v155
	v_fmac_f32_e32 v12, v70, v156
	v_fmac_f32_e32 v13, v70, v157
	v_fmac_f32_e32 v14, v70, v158
	v_fmac_f32_e32 v15, v70, v159
	v_lshl_add_u32 v161, v22, 7, v160
	global_load_dwordx4 v[104:107], v161, s[14:15]
	s_waitcnt vmcnt(23)
	v_cvt_pk_f32_fp8_e32 v[144:145], v108
	v_cvt_pk_f32_fp8_sdwa v[146:147], v108 src0_sel:WORD_1
	v_cvt_pk_f32_fp8_e32 v[148:149], v109
	v_cvt_pk_f32_fp8_sdwa v[150:151], v109 src0_sel:WORD_1
	v_cvt_pk_f32_fp8_e32 v[152:153], v110
	v_cvt_pk_f32_fp8_sdwa v[154:155], v110 src0_sel:WORD_1
	v_cvt_pk_f32_fp8_e32 v[156:157], v111
	v_cvt_pk_f32_fp8_sdwa v[158:159], v111 src0_sel:WORD_1
	v_fmac_f32_e32 v0, v71, v144
	v_fmac_f32_e32 v1, v71, v145
	v_fmac_f32_e32 v2, v71, v146
	v_fmac_f32_e32 v3, v71, v147
	v_fmac_f32_e32 v4, v71, v148
	v_fmac_f32_e32 v5, v71, v149
	v_fmac_f32_e32 v6, v71, v150
	v_fmac_f32_e32 v7, v71, v151
	v_fmac_f32_e32 v8, v71, v152
	v_fmac_f32_e32 v9, v71, v153
	v_fmac_f32_e32 v10, v71, v154
	v_fmac_f32_e32 v11, v71, v155
	v_fmac_f32_e32 v12, v71, v156
	v_fmac_f32_e32 v13, v71, v157
	v_fmac_f32_e32 v14, v71, v158
	v_fmac_f32_e32 v15, v71, v159
	v_lshl_add_u32 v161, v23, 7, v160
	global_load_dwordx4 v[108:111], v161, s[14:15]
	s_waitcnt vmcnt(23)
	v_cvt_pk_f32_fp8_e32 v[144:145], v112
	v_cvt_pk_f32_fp8_sdwa v[146:147], v112 src0_sel:WORD_1
	v_cvt_pk_f32_fp8_e32 v[148:149], v113
	v_cvt_pk_f32_fp8_sdwa v[150:151], v113 src0_sel:WORD_1
	v_cvt_pk_f32_fp8_e32 v[152:153], v114
	v_cvt_pk_f32_fp8_sdwa v[154:155], v114 src0_sel:WORD_1
	v_cvt_pk_f32_fp8_e32 v[156:157], v115
	v_cvt_pk_f32_fp8_sdwa v[158:159], v115 src0_sel:WORD_1
	v_fmac_f32_e32 v0, v72, v144
	v_fmac_f32_e32 v1, v72, v145
	v_fmac_f32_e32 v2, v72, v146
	v_fmac_f32_e32 v3, v72, v147
	v_fmac_f32_e32 v4, v72, v148
	v_fmac_f32_e32 v5, v72, v149
	v_fmac_f32_e32 v6, v72, v150
	v_fmac_f32_e32 v7, v72, v151
	v_fmac_f32_e32 v8, v72, v152
	v_fmac_f32_e32 v9, v72, v153
	v_fmac_f32_e32 v10, v72, v154
	v_fmac_f32_e32 v11, v72, v155
	v_fmac_f32_e32 v12, v72, v156
	v_fmac_f32_e32 v13, v72, v157
	v_fmac_f32_e32 v14, v72, v158
	v_fmac_f32_e32 v15, v72, v159
	v_lshl_add_u32 v161, v24, 7, v160
	global_load_dwordx4 v[112:115], v161, s[14:15]
	s_waitcnt vmcnt(23)
	v_cvt_pk_f32_fp8_e32 v[144:145], v116
	v_cvt_pk_f32_fp8_sdwa v[146:147], v116 src0_sel:WORD_1
	v_cvt_pk_f32_fp8_e32 v[148:149], v117
	v_cvt_pk_f32_fp8_sdwa v[150:151], v117 src0_sel:WORD_1
	v_cvt_pk_f32_fp8_e32 v[152:153], v118
	v_cvt_pk_f32_fp8_sdwa v[154:155], v118 src0_sel:WORD_1
	v_cvt_pk_f32_fp8_e32 v[156:157], v119
	v_cvt_pk_f32_fp8_sdwa v[158:159], v119 src0_sel:WORD_1
	v_fmac_f32_e32 v0, v73, v144
	v_fmac_f32_e32 v1, v73, v145
	v_fmac_f32_e32 v2, v73, v146
	v_fmac_f32_e32 v3, v73, v147
	v_fmac_f32_e32 v4, v73, v148
	v_fmac_f32_e32 v5, v73, v149
	v_fmac_f32_e32 v6, v73, v150
	v_fmac_f32_e32 v7, v73, v151
	v_fmac_f32_e32 v8, v73, v152
	v_fmac_f32_e32 v9, v73, v153
	v_fmac_f32_e32 v10, v73, v154
	v_fmac_f32_e32 v11, v73, v155
	v_fmac_f32_e32 v12, v73, v156
	v_fmac_f32_e32 v13, v73, v157
	v_fmac_f32_e32 v14, v73, v158
	v_fmac_f32_e32 v15, v73, v159
	v_lshl_add_u32 v161, v25, 7, v160
	global_load_dwordx4 v[116:119], v161, s[14:15]
	s_waitcnt vmcnt(23)
	v_cvt_pk_f32_fp8_e32 v[144:145], v120
	v_cvt_pk_f32_fp8_sdwa v[146:147], v120 src0_sel:WORD_1
	v_cvt_pk_f32_fp8_e32 v[148:149], v121
	v_cvt_pk_f32_fp8_sdwa v[150:151], v121 src0_sel:WORD_1
	v_cvt_pk_f32_fp8_e32 v[152:153], v122
	v_cvt_pk_f32_fp8_sdwa v[154:155], v122 src0_sel:WORD_1
	v_cvt_pk_f32_fp8_e32 v[156:157], v123
	v_cvt_pk_f32_fp8_sdwa v[158:159], v123 src0_sel:WORD_1
	v_fmac_f32_e32 v0, v74, v144
	v_fmac_f32_e32 v1, v74, v145
	v_fmac_f32_e32 v2, v74, v146
	v_fmac_f32_e32 v3, v74, v147
	v_fmac_f32_e32 v4, v74, v148
	v_fmac_f32_e32 v5, v74, v149
	v_fmac_f32_e32 v6, v74, v150
	v_fmac_f32_e32 v7, v74, v151
	v_fmac_f32_e32 v8, v74, v152
	v_fmac_f32_e32 v9, v74, v153
	v_fmac_f32_e32 v10, v74, v154
	v_fmac_f32_e32 v11, v74, v155
	v_fmac_f32_e32 v12, v74, v156
	v_fmac_f32_e32 v13, v74, v157
	v_fmac_f32_e32 v14, v74, v158
	v_fmac_f32_e32 v15, v74, v159
	v_lshl_add_u32 v161, v26, 7, v160
	global_load_dwordx4 v[120:123], v161, s[14:15]
	s_waitcnt vmcnt(23)
	v_cvt_pk_f32_fp8_e32 v[144:145], v124
	v_cvt_pk_f32_fp8_sdwa v[146:147], v124 src0_sel:WORD_1
	v_cvt_pk_f32_fp8_e32 v[148:149], v125
	v_cvt_pk_f32_fp8_sdwa v[150:151], v125 src0_sel:WORD_1
	v_cvt_pk_f32_fp8_e32 v[152:153], v126
	v_cvt_pk_f32_fp8_sdwa v[154:155], v126 src0_sel:WORD_1
	v_cvt_pk_f32_fp8_e32 v[156:157], v127
	v_cvt_pk_f32_fp8_sdwa v[158:159], v127 src0_sel:WORD_1
	v_fmac_f32_e32 v0, v75, v144
	v_fmac_f32_e32 v1, v75, v145
	v_fmac_f32_e32 v2, v75, v146
	v_fmac_f32_e32 v3, v75, v147
	v_fmac_f32_e32 v4, v75, v148
	v_fmac_f32_e32 v5, v75, v149
	v_fmac_f32_e32 v6, v75, v150
	v_fmac_f32_e32 v7, v75, v151
	v_fmac_f32_e32 v8, v75, v152
	v_fmac_f32_e32 v9, v75, v153
	v_fmac_f32_e32 v10, v75, v154
	v_fmac_f32_e32 v11, v75, v155
	v_fmac_f32_e32 v12, v75, v156
	v_fmac_f32_e32 v13, v75, v157
	v_fmac_f32_e32 v14, v75, v158
	v_fmac_f32_e32 v15, v75, v159
	v_lshl_add_u32 v161, v27, 7, v160
	global_load_dwordx4 v[124:127], v161, s[14:15]
	s_waitcnt vmcnt(23)
; DI void phase_peer_b(const Params& p, int layer, const float* gnext, bool last) {
;     ...
;     for (int bt = 0; bt < 8; ++bt) {
;       u32x4 vr[16];
; #pragma unroll
;       for (int j = 0; j < 16; ++j) {
;         const int e = bt * 16 + j;
;         const int eidx = __builtin_amdgcn_readlane(e < 64 ? i0 : i1, e & 63);
;         vr[j] = *(const u32x4*)(EV + (size_t)eidx * DM + lane * 16);
;       }
; #pragma unroll
;       for (int j = 0; j < 16; ++j) {
;         const int e = bt * 16 + j;
;         const float wj = __int_as_float(__builtin_amdgcn_readlane(__float_as_int(e < 64 ? w0 : w1), e & 63));
; #pragma unroll
;         for (int w = 0; w < 4; ++w) {
;           const f32x2 lo = __builtin_amdgcn_cvt_pk_f32_fp8((int)vr[j][w], false);
;           const f32x2 hi = __builtin_amdgcn_cvt_pk_f32_fp8((int)vr[j][w], true);
;           acc[4 * w] += wj * lo[0]; acc[4 * w + 1] += wj * lo[1]; acc[4 * w + 2] += wj * hi[0]; acc[4 * w + 3] += wj * hi[1];
;         }
;       }
	v_cvt_pk_f32_fp8_e32 v[144:145], v128
	v_cvt_pk_f32_fp8_sdwa v[146:147], v128 src0_sel:WORD_1
	v_cvt_pk_f32_fp8_e32 v[148:149], v129
	v_cvt_pk_f32_fp8_sdwa v[150:151], v129 src0_sel:WORD_1
	v_cvt_pk_f32_fp8_e32 v[152:153], v130
	v_cvt_pk_f32_fp8_sdwa v[154:155], v130 src0_sel:WORD_1
	v_cvt_pk_f32_fp8_e32 v[156:157], v131
	v_cvt_pk_f32_fp8_sdwa v[158:159], v131 src0_sel:WORD_1
	v_fmac_f32_e32 v0, v76, v144
	v_fmac_f32_e32 v1, v76, v145
	v_fmac_f32_e32 v2, v76, v146
	v_fmac_f32_e32 v3, v76, v147
	v_fmac_f32_e32 v4, v76, v148
	v_fmac_f32_e32 v5, v76, v149
	v_fmac_f32_e32 v6, v76, v150
	v_fmac_f32_e32 v7, v76, v151
	v_fmac_f32_e32 v8, v76, v152
	v_fmac_f32_e32 v9, v76, v153
	v_fmac_f32_e32 v10, v76, v154
	v_fmac_f32_e32 v11, v76, v155
	v_fmac_f32_e32 v12, v76, v156
	v_fmac_f32_e32 v13, v76, v157
	v_fmac_f32_e32 v14, v76, v158
	v_fmac_f32_e32 v15, v76, v159
	v_lshl_add_u32 v161, v28, 7, v160
	global_load_dwordx4 v[128:131], v161, s[14:15]
	s_waitcnt vmcnt(23)
	v_cvt_pk_f32_fp8_e32 v[144:145], v132
	v_cvt_pk_f32_fp8_sdwa v[146:147], v132 src0_sel:WORD_1
	v_cvt_pk_f32_fp8_e32 v[148:149], v133
	v_cvt_pk_f32_fp8_sdwa v[150:151], v133 src0_sel:WORD_1
	v_cvt_pk_f32_fp8_e32 v[152:153], v134
	v_cvt_pk_f32_fp8_sdwa v[154:155], v134 src0_sel:WORD_1
	v_cvt_pk_f32_fp8_e32 v[156:157], v135
	v_cvt_pk_f32_fp8_sdwa v[158:159], v135 src0_sel:WORD_1
	v_fmac_f32_e32 v0, v77, v144
	v_fmac_f32_e32 v1, v77, v145
	v_fmac_f32_e32 v2, v77, v146
	v_fmac_f32_e32 v3, v77, v147
	v_fmac_f32_e32 v4, v77, v148
	v_fmac_f32_e32 v5, v77, v149
	v_fmac_f32_e32 v6, v77, v150
	v_fmac_f32_e32 v7, v77, v151
	v_fmac_f32_e32 v8, v77, v152
	v_fmac_f32_e32 v9, v77, v153
	v_fmac_f32_e32 v10, v77, v154
	v_fmac_f32_e32 v11, v77, v155
	v_fmac_f32_e32 v12, v77, v156
	v_fmac_f32_e32 v13, v77, v157
	v_fmac_f32_e32 v14, v77, v158
	v_fmac_f32_e32 v15, v77, v159
	v_lshl_add_u32 v161, v29, 7, v160
	global_load_dwordx4 v[132:135], v161, s[14:15]
	s_waitcnt vmcnt(23)
	v_cvt_pk_f32_fp8_e32 v[144:145], v136
	v_cvt_pk_f32_fp8_sdwa v[146:147], v136 src0_sel:WORD_1
	v_cvt_pk_f32_fp8_e32 v[148:149], v137
	v_cvt_pk_f32_fp8_sdwa v[150:151], v137 src0_sel:WORD_1
	v_cvt_pk_f32_fp8_e32 v[152:153], v138
	v_cvt_pk_f32_fp8_sdwa v[154:155], v138 src0_sel:WORD_1
	v_cvt_pk_f32_fp8_e32 v[156:157], v139
	v_cvt_pk_f32_fp8_sdwa v[158:159], v139 src0_sel:WORD_1
	v_fmac_f32_e32 v0, v78, v144
	v_fmac_f32_e32 v1, v78, v145
	v_fmac_f32_e32 v2, v78, v146
	v_fmac_f32_e32 v3, v78, v147
	v_fmac_f32_e32 v4, v78, v148
	v_fmac_f32_e32 v5, v78, v149
	v_fmac_f32_e32 v6, v78, v150
	v_fmac_f32_e32 v7, v78, v151
	v_fmac_f32_e32 v8, v78, v152
	v_fmac_f32_e32 v9, v78, v153
	v_fmac_f32_e32 v10, v78, v154
	v_fmac_f32_e32 v11, v78, v155
	v_fmac_f32_e32 v12, v78, v156
	v_fmac_f32_e32 v13, v78, v157
	v_fmac_f32_e32 v14, v78, v158
	v_fmac_f32_e32 v15, v78, v159
	v_lshl_add_u32 v161, v30, 7, v160
	global_load_dwordx4 v[136:139], v161, s[14:15]
	s_waitcnt vmcnt(23)
	v_cvt_pk_f32_fp8_e32 v[144:145], v140
	v_cvt_pk_f32_fp8_sdwa v[146:147], v140 src0_sel:WORD_1
	v_cvt_pk_f32_fp8_e32 v[148:149], v141
	v_cvt_pk_f32_fp8_sdwa v[150:151], v141 src0_sel:WORD_1
	v_cvt_pk_f32_fp8_e32 v[152:153], v142
	v_cvt_pk_f32_fp8_sdwa v[154:155], v142 src0_sel:WORD_1
	v_cvt_pk_f32_fp8_e32 v[156:157], v143
	v_cvt_pk_f32_fp8_sdwa v[158:159], v143 src0_sel:WORD_1
	v_fmac_f32_e32 v0, v79, v144
	v_fmac_f32_e32 v1, v79, v145
	v_fmac_f32_e32 v2, v79, v146
	v_fmac_f32_e32 v3, v79, v147
	v_fmac_f32_e32 v4, v79, v148
	v_fmac_f32_e32 v5, v79, v149
	v_fmac_f32_e32 v6, v79, v150
	v_fmac_f32_e32 v7, v79, v151
	v_fmac_f32_e32 v8, v79, v152
	v_fmac_f32_e32 v9, v79, v153
	v_fmac_f32_e32 v10, v79, v154
	v_fmac_f32_e32 v11, v79, v155
	v_fmac_f32_e32 v12, v79, v156
	v_fmac_f32_e32 v13, v79, v157
	v_fmac_f32_e32 v14, v79, v158
	v_fmac_f32_e32 v15, v79, v159
	v_lshl_add_u32 v161, v31, 7, v160
	global_load_dwordx4 v[140:143], v161, s[14:15]
	global_load_dwordx4 v[16:19], v163, s[16:17] offset:384
	global_load_dwordx4 v[20:23], v163, s[16:17] offset:400
	global_load_dwordx4 v[24:27], v163, s[16:17] offset:416
	global_load_dwordx4 v[28:31], v163, s[16:17] offset:432
	global_load_dwordx4 v[64:67], v163, s[18:19] offset:320
	global_load_dwordx4 v[68:71], v163, s[18:19] offset:336
	global_load_dwordx4 v[72:75], v163, s[18:19] offset:352
	global_load_dwordx4 v[76:79], v163, s[18:19] offset:368
	s_waitcnt vmcnt(23)
	v_cvt_pk_f32_fp8_e32 v[144:145], v80
	v_cvt_pk_f32_fp8_sdwa v[146:147], v80 src0_sel:WORD_1
	v_cvt_pk_f32_fp8_e32 v[148:149], v81
	v_cvt_pk_f32_fp8_sdwa v[150:151], v81 src0_sel:WORD_1
	v_cvt_pk_f32_fp8_e32 v[152:153], v82
	v_cvt_pk_f32_fp8_sdwa v[154:155], v82 src0_sel:WORD_1
	v_cvt_pk_f32_fp8_e32 v[156:157], v83
	v_cvt_pk_f32_fp8_sdwa v[158:159], v83 src0_sel:WORD_1
	v_fmac_f32_e32 v0, v48, v144
	v_fmac_f32_e32 v1, v48, v145
	v_fmac_f32_e32 v2, v48, v146
	v_fmac_f32_e32 v3, v48, v147
	v_fmac_f32_e32 v4, v48, v148
	v_fmac_f32_e32 v5, v48, v149
	v_fmac_f32_e32 v6, v48, v150
	v_fmac_f32_e32 v7, v48, v151
	v_fmac_f32_e32 v8, v48, v152
	v_fmac_f32_e32 v9, v48, v153
	v_fmac_f32_e32 v10, v48, v154
	v_fmac_f32_e32 v11, v48, v155
	v_fmac_f32_e32 v12, v48, v156
	v_fmac_f32_e32 v13, v48, v157
	v_fmac_f32_e32 v14, v48, v158
	v_fmac_f32_e32 v15, v48, v159
	v_lshl_add_u32 v161, v32, 7, v160
	global_load_dwordx4 v[80:83], v161, s[14:15]
	s_waitcnt vmcnt(23)
; DI void phase_peer_b(const Params& p, int layer, const float* gnext, bool last) {
;     ...
;     for (int bt = 0; bt < 8; ++bt) {
;       u32x4 vr[16];
; #pragma unroll
;       for (int j = 0; j < 16; ++j) {
;         const int e = bt * 16 + j;
;         const int eidx = __builtin_amdgcn_readlane(e < 64 ? i0 : i1, e & 63);
;         vr[j] = *(const u32x4*)(EV + (size_t)eidx * DM + lane * 16);
;       }
; #pragma unroll
;       for (int j = 0; j < 16; ++j) {
;         const int e = bt * 16 + j;
;         const float wj = __int_as_float(__builtin_amdgcn_readlane(__float_as_int(e < 64 ? w0 : w1), e & 63));
; #pragma unroll
;         for (int w = 0; w < 4; ++w) {
;           const f32x2 lo = __builtin_amdgcn_cvt_pk_f32_fp8((int)vr[j][w], false);
;           const f32x2 hi = __builtin_amdgcn_cvt_pk_f32_fp8((int)vr[j][w], true);
;           acc[4 * w] += wj * lo[0]; acc[4 * w + 1] += wj * lo[1]; acc[4 * w + 2] += wj * hi[0]; acc[4 * w + 3] += wj * hi[1];
;         }
;       }
	v_cvt_pk_f32_fp8_e32 v[144:145], v84
	v_cvt_pk_f32_fp8_sdwa v[146:147], v84 src0_sel:WORD_1
	v_cvt_pk_f32_fp8_e32 v[148:149], v85
	v_cvt_pk_f32_fp8_sdwa v[150:151], v85 src0_sel:WORD_1
	v_cvt_pk_f32_fp8_e32 v[152:153], v86
	v_cvt_pk_f32_fp8_sdwa v[154:155], v86 src0_sel:WORD_1
	v_cvt_pk_f32_fp8_e32 v[156:157], v87
	v_cvt_pk_f32_fp8_sdwa v[158:159], v87 src0_sel:WORD_1
	v_fmac_f32_e32 v0, v49, v144
	v_fmac_f32_e32 v1, v49, v145
	v_fmac_f32_e32 v2, v49, v146
	v_fmac_f32_e32 v3, v49, v147
	v_fmac_f32_e32 v4, v49, v148
	v_fmac_f32_e32 v5, v49, v149
	v_fmac_f32_e32 v6, v49, v150
	v_fmac_f32_e32 v7, v49, v151
	v_fmac_f32_e32 v8, v49, v152
	v_fmac_f32_e32 v9, v49, v153
	v_fmac_f32_e32 v10, v49, v154
	v_fmac_f32_e32 v11, v49, v155
	v_fmac_f32_e32 v12, v49, v156
	v_fmac_f32_e32 v13, v49, v157
	v_fmac_f32_e32 v14, v49, v158
	v_fmac_f32_e32 v15, v49, v159
	v_lshl_add_u32 v161, v33, 7, v160
	global_load_dwordx4 v[84:87], v161, s[14:15]
	s_waitcnt vmcnt(23)
	v_cvt_pk_f32_fp8_e32 v[144:145], v88
	v_cvt_pk_f32_fp8_sdwa v[146:147], v88 src0_sel:WORD_1
	v_cvt_pk_f32_fp8_e32 v[148:149], v89
	v_cvt_pk_f32_fp8_sdwa v[150:151], v89 src0_sel:WORD_1
	v_cvt_pk_f32_fp8_e32 v[152:153], v90
	v_cvt_pk_f32_fp8_sdwa v[154:155], v90 src0_sel:WORD_1
	v_cvt_pk_f32_fp8_e32 v[156:157], v91
	v_cvt_pk_f32_fp8_sdwa v[158:159], v91 src0_sel:WORD_1
	v_fmac_f32_e32 v0, v50, v144
	v_fmac_f32_e32 v1, v50, v145
	v_fmac_f32_e32 v2, v50, v146
	v_fmac_f32_e32 v3, v50, v147
	v_fmac_f32_e32 v4, v50, v148
	v_fmac_f32_e32 v5, v50, v149
	v_fmac_f32_e32 v6, v50, v150
	v_fmac_f32_e32 v7, v50, v151
	v_fmac_f32_e32 v8, v50, v152
	v_fmac_f32_e32 v9, v50, v153
	v_fmac_f32_e32 v10, v50, v154
	v_fmac_f32_e32 v11, v50, v155
	v_fmac_f32_e32 v12, v50, v156
	v_fmac_f32_e32 v13, v50, v157
	v_fmac_f32_e32 v14, v50, v158
	v_fmac_f32_e32 v15, v50, v159
	v_lshl_add_u32 v161, v34, 7, v160
	global_load_dwordx4 v[88:91], v161, s[14:15]
	s_waitcnt vmcnt(23)
	v_cvt_pk_f32_fp8_e32 v[144:145], v92
	v_cvt_pk_f32_fp8_sdwa v[146:147], v92 src0_sel:WORD_1
	v_cvt_pk_f32_fp8_e32 v[148:149], v93
	v_cvt_pk_f32_fp8_sdwa v[150:151], v93 src0_sel:WORD_1
	v_cvt_pk_f32_fp8_e32 v[152:153], v94
	v_cvt_pk_f32_fp8_sdwa v[154:155], v94 src0_sel:WORD_1
	v_cvt_pk_f32_fp8_e32 v[156:157], v95
	v_cvt_pk_f32_fp8_sdwa v[158:159], v95 src0_sel:WORD_1
	v_fmac_f32_e32 v0, v51, v144
	v_fmac_f32_e32 v1, v51, v145
	v_fmac_f32_e32 v2, v51, v146
	v_fmac_f32_e32 v3, v51, v147
	v_fmac_f32_e32 v4, v51, v148
	v_fmac_f32_e32 v5, v51, v149
	v_fmac_f32_e32 v6, v51, v150
	v_fmac_f32_e32 v7, v51, v151
	v_fmac_f32_e32 v8, v51, v152
	v_fmac_f32_e32 v9, v51, v153
	v_fmac_f32_e32 v10, v51, v154
	v_fmac_f32_e32 v11, v51, v155
	v_fmac_f32_e32 v12, v51, v156
	v_fmac_f32_e32 v13, v51, v157
	v_fmac_f32_e32 v14, v51, v158
	v_fmac_f32_e32 v15, v51, v159
	v_lshl_add_u32 v161, v35, 7, v160
	global_load_dwordx4 v[92:95], v161, s[14:15]
	s_waitcnt vmcnt(23)
	v_cvt_pk_f32_fp8_e32 v[144:145], v96
	v_cvt_pk_f32_fp8_sdwa v[146:147], v96 src0_sel:WORD_1
	v_cvt_pk_f32_fp8_e32 v[148:149], v97
	v_cvt_pk_f32_fp8_sdwa v[150:151], v97 src0_sel:WORD_1
	v_cvt_pk_f32_fp8_e32 v[152:153], v98
	v_cvt_pk_f32_fp8_sdwa v[154:155], v98 src0_sel:WORD_1
	v_cvt_pk_f32_fp8_e32 v[156:157], v99
	v_cvt_pk_f32_fp8_sdwa v[158:159], v99 src0_sel:WORD_1
	v_fmac_f32_e32 v0, v52, v144
	v_fmac_f32_e32 v1, v52, v145
	v_fmac_f32_e32 v2, v52, v146
	v_fmac_f32_e32 v3, v52, v147
	v_fmac_f32_e32 v4, v52, v148
	v_fmac_f32_e32 v5, v52, v149
	v_fmac_f32_e32 v6, v52, v150
	v_fmac_f32_e32 v7, v52, v151
	v_fmac_f32_e32 v8, v52, v152
	v_fmac_f32_e32 v9, v52, v153
	v_fmac_f32_e32 v10, v52, v154
	v_fmac_f32_e32 v11, v52, v155
	v_fmac_f32_e32 v12, v52, v156
	v_fmac_f32_e32 v13, v52, v157
	v_fmac_f32_e32 v14, v52, v158
	v_fmac_f32_e32 v15, v52, v159
	v_lshl_add_u32 v161, v36, 7, v160
	global_load_dwordx4 v[96:99], v161, s[14:15]
	s_waitcnt vmcnt(23)
	v_cvt_pk_f32_fp8_e32 v[144:145], v100
	v_cvt_pk_f32_fp8_sdwa v[146:147], v100 src0_sel:WORD_1
	v_cvt_pk_f32_fp8_e32 v[148:149], v101
	v_cvt_pk_f32_fp8_sdwa v[150:151], v101 src0_sel:WORD_1
	v_cvt_pk_f32_fp8_e32 v[152:153], v102
	v_cvt_pk_f32_fp8_sdwa v[154:155], v102 src0_sel:WORD_1
	v_cvt_pk_f32_fp8_e32 v[156:157], v103
	v_cvt_pk_f32_fp8_sdwa v[158:159], v103 src0_sel:WORD_1
	v_fmac_f32_e32 v0, v53, v144
	v_fmac_f32_e32 v1, v53, v145
	v_fmac_f32_e32 v2, v53, v146
	v_fmac_f32_e32 v3, v53, v147
	v_fmac_f32_e32 v4, v53, v148
	v_fmac_f32_e32 v5, v53, v149
	v_fmac_f32_e32 v6, v53, v150
	v_fmac_f32_e32 v7, v53, v151
	v_fmac_f32_e32 v8, v53, v152
	v_fmac_f32_e32 v9, v53, v153
	v_fmac_f32_e32 v10, v53, v154
	v_fmac_f32_e32 v11, v53, v155
	v_fmac_f32_e32 v12, v53, v156
	v_fmac_f32_e32 v13, v53, v157
	v_fmac_f32_e32 v14, v53, v158
	v_fmac_f32_e32 v15, v53, v159
	v_lshl_add_u32 v161, v37, 7, v160
	global_load_dwordx4 v[100:103], v161, s[14:15]
	s_waitcnt vmcnt(23)
	v_cvt_pk_f32_fp8_e32 v[144:145], v104
	v_cvt_pk_f32_fp8_sdwa v[146:147], v104 src0_sel:WORD_1
	v_cvt_pk_f32_fp8_e32 v[148:149], v105
	v_cvt_pk_f32_fp8_sdwa v[150:151], v105 src0_sel:WORD_1
	v_cvt_pk_f32_fp8_e32 v[152:153], v106
	v_cvt_pk_f32_fp8_sdwa v[154:155], v106 src0_sel:WORD_1
	v_cvt_pk_f32_fp8_e32 v[156:157], v107
	v_cvt_pk_f32_fp8_sdwa v[158:159], v107 src0_sel:WORD_1
	v_fmac_f32_e32 v0, v54, v144
	v_fmac_f32_e32 v1, v54, v145
	v_fmac_f32_e32 v2, v54, v146
	v_fmac_f32_e32 v3, v54, v147
	v_fmac_f32_e32 v4, v54, v148
	v_fmac_f32_e32 v5, v54, v149
	v_fmac_f32_e32 v6, v54, v150
	v_fmac_f32_e32 v7, v54, v151
	v_fmac_f32_e32 v8, v54, v152
	v_fmac_f32_e32 v9, v54, v153
	v_fmac_f32_e32 v10, v54, v154
	v_fmac_f32_e32 v11, v54, v155
	v_fmac_f32_e32 v12, v54, v156
	v_fmac_f32_e32 v13, v54, v157
	v_fmac_f32_e32 v14, v54, v158
	v_fmac_f32_e32 v15, v54, v159
	v_lshl_add_u32 v161, v38, 7, v160
	global_load_dwordx4 v[104:107], v161, s[14:15]
	s_waitcnt vmcnt(23)
; DI void phase_peer_b(const Params& p, int layer, const float* gnext, bool last) {
;     ...
;     for (int bt = 0; bt < 8; ++bt) {
;       u32x4 vr[16];
; #pragma unroll
;       for (int j = 0; j < 16; ++j) {
;         const int e = bt * 16 + j;
;         const int eidx = __builtin_amdgcn_readlane(e < 64 ? i0 : i1, e & 63);
;         vr[j] = *(const u32x4*)(EV + (size_t)eidx * DM + lane * 16);
;       }
; #pragma unroll
;       for (int j = 0; j < 16; ++j) {
;         const int e = bt * 16 + j;
;         const float wj = __int_as_float(__builtin_amdgcn_readlane(__float_as_int(e < 64 ? w0 : w1), e & 63));
; #pragma unroll
;         for (int w = 0; w < 4; ++w) {
;           const f32x2 lo = __builtin_amdgcn_cvt_pk_f32_fp8((int)vr[j][w], false);
;           const f32x2 hi = __builtin_amdgcn_cvt_pk_f32_fp8((int)vr[j][w], true);
;           acc[4 * w] += wj * lo[0]; acc[4 * w + 1] += wj * lo[1]; acc[4 * w + 2] += wj * hi[0]; acc[4 * w + 3] += wj * hi[1];
;         }
;       }
	v_cvt_pk_f32_fp8_e32 v[144:145], v108
	v_cvt_pk_f32_fp8_sdwa v[146:147], v108 src0_sel:WORD_1
	v_cvt_pk_f32_fp8_e32 v[148:149], v109
	v_cvt_pk_f32_fp8_sdwa v[150:151], v109 src0_sel:WORD_1
	v_cvt_pk_f32_fp8_e32 v[152:153], v110
	v_cvt_pk_f32_fp8_sdwa v[154:155], v110 src0_sel:WORD_1
	v_cvt_pk_f32_fp8_e32 v[156:157], v111
	v_cvt_pk_f32_fp8_sdwa v[158:159], v111 src0_sel:WORD_1
	v_fmac_f32_e32 v0, v55, v144
	v_fmac_f32_e32 v1, v55, v145
	v_fmac_f32_e32 v2, v55, v146
	v_fmac_f32_e32 v3, v55, v147
	v_fmac_f32_e32 v4, v55, v148
	v_fmac_f32_e32 v5, v55, v149
	v_fmac_f32_e32 v6, v55, v150
	v_fmac_f32_e32 v7, v55, v151
	v_fmac_f32_e32 v8, v55, v152
	v_fmac_f32_e32 v9, v55, v153
	v_fmac_f32_e32 v10, v55, v154
	v_fmac_f32_e32 v11, v55, v155
	v_fmac_f32_e32 v12, v55, v156
	v_fmac_f32_e32 v13, v55, v157
	v_fmac_f32_e32 v14, v55, v158
	v_fmac_f32_e32 v15, v55, v159
	v_lshl_add_u32 v161, v39, 7, v160
	global_load_dwordx4 v[108:111], v161, s[14:15]
	s_waitcnt vmcnt(23)
	v_cvt_pk_f32_fp8_e32 v[144:145], v112
	v_cvt_pk_f32_fp8_sdwa v[146:147], v112 src0_sel:WORD_1
	v_cvt_pk_f32_fp8_e32 v[148:149], v113
	v_cvt_pk_f32_fp8_sdwa v[150:151], v113 src0_sel:WORD_1
	v_cvt_pk_f32_fp8_e32 v[152:153], v114
	v_cvt_pk_f32_fp8_sdwa v[154:155], v114 src0_sel:WORD_1
	v_cvt_pk_f32_fp8_e32 v[156:157], v115
	v_cvt_pk_f32_fp8_sdwa v[158:159], v115 src0_sel:WORD_1
	v_fmac_f32_e32 v0, v56, v144
	v_fmac_f32_e32 v1, v56, v145
	v_fmac_f32_e32 v2, v56, v146
	v_fmac_f32_e32 v3, v56, v147
	v_fmac_f32_e32 v4, v56, v148
	v_fmac_f32_e32 v5, v56, v149
	v_fmac_f32_e32 v6, v56, v150
	v_fmac_f32_e32 v7, v56, v151
	v_fmac_f32_e32 v8, v56, v152
	v_fmac_f32_e32 v9, v56, v153
	v_fmac_f32_e32 v10, v56, v154
	v_fmac_f32_e32 v11, v56, v155
	v_fmac_f32_e32 v12, v56, v156
	v_fmac_f32_e32 v13, v56, v157
	v_fmac_f32_e32 v14, v56, v158
	v_fmac_f32_e32 v15, v56, v159
	v_lshl_add_u32 v161, v40, 7, v160
	global_load_dwordx4 v[112:115], v161, s[14:15]
	s_waitcnt vmcnt(23)
	v_cvt_pk_f32_fp8_e32 v[144:145], v116
	v_cvt_pk_f32_fp8_sdwa v[146:147], v116 src0_sel:WORD_1
	v_cvt_pk_f32_fp8_e32 v[148:149], v117
	v_cvt_pk_f32_fp8_sdwa v[150:151], v117 src0_sel:WORD_1
	v_cvt_pk_f32_fp8_e32 v[152:153], v118
	v_cvt_pk_f32_fp8_sdwa v[154:155], v118 src0_sel:WORD_1
	v_cvt_pk_f32_fp8_e32 v[156:157], v119
	v_cvt_pk_f32_fp8_sdwa v[158:159], v119 src0_sel:WORD_1
	v_fmac_f32_e32 v0, v57, v144
	v_fmac_f32_e32 v1, v57, v145
	v_fmac_f32_e32 v2, v57, v146
	v_fmac_f32_e32 v3, v57, v147
	v_fmac_f32_e32 v4, v57, v148
	v_fmac_f32_e32 v5, v57, v149
	v_fmac_f32_e32 v6, v57, v150
	v_fmac_f32_e32 v7, v57, v151
	v_fmac_f32_e32 v8, v57, v152
	v_fmac_f32_e32 v9, v57, v153
	v_fmac_f32_e32 v10, v57, v154
	v_fmac_f32_e32 v11, v57, v155
	v_fmac_f32_e32 v12, v57, v156
	v_fmac_f32_e32 v13, v57, v157
	v_fmac_f32_e32 v14, v57, v158
	v_fmac_f32_e32 v15, v57, v159
	v_lshl_add_u32 v161, v41, 7, v160
	global_load_dwordx4 v[116:119], v161, s[14:15]
	s_waitcnt vmcnt(23)
	v_cvt_pk_f32_fp8_e32 v[144:145], v120
	v_cvt_pk_f32_fp8_sdwa v[146:147], v120 src0_sel:WORD_1
	v_cvt_pk_f32_fp8_e32 v[148:149], v121
	v_cvt_pk_f32_fp8_sdwa v[150:151], v121 src0_sel:WORD_1
	v_cvt_pk_f32_fp8_e32 v[152:153], v122
	v_cvt_pk_f32_fp8_sdwa v[154:155], v122 src0_sel:WORD_1
	v_cvt_pk_f32_fp8_e32 v[156:157], v123
	v_cvt_pk_f32_fp8_sdwa v[158:159], v123 src0_sel:WORD_1
	v_fmac_f32_e32 v0, v58, v144
	v_fmac_f32_e32 v1, v58, v145
	v_fmac_f32_e32 v2, v58, v146
	v_fmac_f32_e32 v3, v58, v147
	v_fmac_f32_e32 v4, v58, v148
	v_fmac_f32_e32 v5, v58, v149
	v_fmac_f32_e32 v6, v58, v150
	v_fmac_f32_e32 v7, v58, v151
	v_fmac_f32_e32 v8, v58, v152
	v_fmac_f32_e32 v9, v58, v153
	v_fmac_f32_e32 v10, v58, v154
	v_fmac_f32_e32 v11, v58, v155
	v_fmac_f32_e32 v12, v58, v156
	v_fmac_f32_e32 v13, v58, v157
	v_fmac_f32_e32 v14, v58, v158
	v_fmac_f32_e32 v15, v58, v159
	v_lshl_add_u32 v161, v42, 7, v160
	global_load_dwordx4 v[120:123], v161, s[14:15]
	s_waitcnt vmcnt(23)
	v_cvt_pk_f32_fp8_e32 v[144:145], v124
	v_cvt_pk_f32_fp8_sdwa v[146:147], v124 src0_sel:WORD_1
	v_cvt_pk_f32_fp8_e32 v[148:149], v125
	v_cvt_pk_f32_fp8_sdwa v[150:151], v125 src0_sel:WORD_1
	v_cvt_pk_f32_fp8_e32 v[152:153], v126
	v_cvt_pk_f32_fp8_sdwa v[154:155], v126 src0_sel:WORD_1
	v_cvt_pk_f32_fp8_e32 v[156:157], v127
	v_cvt_pk_f32_fp8_sdwa v[158:159], v127 src0_sel:WORD_1
	v_fmac_f32_e32 v0, v59, v144
	v_fmac_f32_e32 v1, v59, v145
	v_fmac_f32_e32 v2, v59, v146
	v_fmac_f32_e32 v3, v59, v147
	v_fmac_f32_e32 v4, v59, v148
	v_fmac_f32_e32 v5, v59, v149
	v_fmac_f32_e32 v6, v59, v150
	v_fmac_f32_e32 v7, v59, v151
	v_fmac_f32_e32 v8, v59, v152
	v_fmac_f32_e32 v9, v59, v153
	v_fmac_f32_e32 v10, v59, v154
	v_fmac_f32_e32 v11, v59, v155
	v_fmac_f32_e32 v12, v59, v156
	v_fmac_f32_e32 v13, v59, v157
	v_fmac_f32_e32 v14, v59, v158
	v_fmac_f32_e32 v15, v59, v159
	v_lshl_add_u32 v161, v43, 7, v160
	global_load_dwordx4 v[124:127], v161, s[14:15]
	s_waitcnt vmcnt(23)
	v_cvt_pk_f32_fp8_e32 v[144:145], v128
	v_cvt_pk_f32_fp8_sdwa v[146:147], v128 src0_sel:WORD_1
	v_cvt_pk_f32_fp8_e32 v[148:149], v129
	v_cvt_pk_f32_fp8_sdwa v[150:151], v129 src0_sel:WORD_1
	v_cvt_pk_f32_fp8_e32 v[152:153], v130
	v_cvt_pk_f32_fp8_sdwa v[154:155], v130 src0_sel:WORD_1
	v_cvt_pk_f32_fp8_e32 v[156:157], v131
	v_cvt_pk_f32_fp8_sdwa v[158:159], v131 src0_sel:WORD_1
	v_fmac_f32_e32 v0, v60, v144
	v_fmac_f32_e32 v1, v60, v145
	v_fmac_f32_e32 v2, v60, v146
	v_fmac_f32_e32 v3, v60, v147
	v_fmac_f32_e32 v4, v60, v148
	v_fmac_f32_e32 v5, v60, v149
	v_fmac_f32_e32 v6, v60, v150
	v_fmac_f32_e32 v7, v60, v151
	v_fmac_f32_e32 v8, v60, v152
	v_fmac_f32_e32 v9, v60, v153
	v_fmac_f32_e32 v10, v60, v154
	v_fmac_f32_e32 v11, v60, v155
	v_fmac_f32_e32 v12, v60, v156
	v_fmac_f32_e32 v13, v60, v157
	v_fmac_f32_e32 v14, v60, v158
	v_fmac_f32_e32 v15, v60, v159
	v_lshl_add_u32 v161, v44, 7, v160
	global_load_dwordx4 v[128:131], v161, s[14:15]
	s_waitcnt vmcnt(23)
; DI void phase_peer_b(const Params& p, int layer, const float* gnext, bool last) {
;     ...
;     for (int bt = 0; bt < 8; ++bt) {
;       u32x4 vr[16];
; #pragma unroll
;       for (int j = 0; j < 16; ++j) {
;         const int e = bt * 16 + j;
;         const int eidx = __builtin_amdgcn_readlane(e < 64 ? i0 : i1, e & 63);
;         vr[j] = *(const u32x4*)(EV + (size_t)eidx * DM + lane * 16);
;       }
; #pragma unroll
;       for (int j = 0; j < 16; ++j) {
;         const int e = bt * 16 + j;
;         const float wj = __int_as_float(__builtin_amdgcn_readlane(__float_as_int(e < 64 ? w0 : w1), e & 63));
; #pragma unroll
;         for (int w = 0; w < 4; ++w) {
;           const f32x2 lo = __builtin_amdgcn_cvt_pk_f32_fp8((int)vr[j][w], false);
;           const f32x2 hi = __builtin_amdgcn_cvt_pk_f32_fp8((int)vr[j][w], true);
;           acc[4 * w] += wj * lo[0]; acc[4 * w + 1] += wj * lo[1]; acc[4 * w + 2] += wj * hi[0]; acc[4 * w + 3] += wj * hi[1];
;         }
;       }
	v_cvt_pk_f32_fp8_e32 v[144:145], v132
	v_cvt_pk_f32_fp8_sdwa v[146:147], v132 src0_sel:WORD_1
	v_cvt_pk_f32_fp8_e32 v[148:149], v133
	v_cvt_pk_f32_fp8_sdwa v[150:151], v133 src0_sel:WORD_1
	v_cvt_pk_f32_fp8_e32 v[152:153], v134
	v_cvt_pk_f32_fp8_sdwa v[154:155], v134 src0_sel:WORD_1
	v_cvt_pk_f32_fp8_e32 v[156:157], v135
	v_cvt_pk_f32_fp8_sdwa v[158:159], v135 src0_sel:WORD_1
	v_fmac_f32_e32 v0, v61, v144
	v_fmac_f32_e32 v1, v61, v145
	v_fmac_f32_e32 v2, v61, v146
	v_fmac_f32_e32 v3, v61, v147
	v_fmac_f32_e32 v4, v61, v148
	v_fmac_f32_e32 v5, v61, v149
	v_fmac_f32_e32 v6, v61, v150
	v_fmac_f32_e32 v7, v61, v151
	v_fmac_f32_e32 v8, v61, v152
	v_fmac_f32_e32 v9, v61, v153
	v_fmac_f32_e32 v10, v61, v154
	v_fmac_f32_e32 v11, v61, v155
	v_fmac_f32_e32 v12, v61, v156
	v_fmac_f32_e32 v13, v61, v157
	v_fmac_f32_e32 v14, v61, v158
	v_fmac_f32_e32 v15, v61, v159
	v_lshl_add_u32 v161, v45, 7, v160
	global_load_dwordx4 v[132:135], v161, s[14:15]
	s_waitcnt vmcnt(23)
	v_cvt_pk_f32_fp8_e32 v[144:145], v136
	v_cvt_pk_f32_fp8_sdwa v[146:147], v136 src0_sel:WORD_1
	v_cvt_pk_f32_fp8_e32 v[148:149], v137
	v_cvt_pk_f32_fp8_sdwa v[150:151], v137 src0_sel:WORD_1
	v_cvt_pk_f32_fp8_e32 v[152:153], v138
	v_cvt_pk_f32_fp8_sdwa v[154:155], v138 src0_sel:WORD_1
	v_cvt_pk_f32_fp8_e32 v[156:157], v139
	v_cvt_pk_f32_fp8_sdwa v[158:159], v139 src0_sel:WORD_1
	v_fmac_f32_e32 v0, v62, v144
	v_fmac_f32_e32 v1, v62, v145
	v_fmac_f32_e32 v2, v62, v146
	v_fmac_f32_e32 v3, v62, v147
	v_fmac_f32_e32 v4, v62, v148
	v_fmac_f32_e32 v5, v62, v149
	v_fmac_f32_e32 v6, v62, v150
	v_fmac_f32_e32 v7, v62, v151
	v_fmac_f32_e32 v8, v62, v152
	v_fmac_f32_e32 v9, v62, v153
	v_fmac_f32_e32 v10, v62, v154
	v_fmac_f32_e32 v11, v62, v155
	v_fmac_f32_e32 v12, v62, v156
	v_fmac_f32_e32 v13, v62, v157
	v_fmac_f32_e32 v14, v62, v158
	v_fmac_f32_e32 v15, v62, v159
	v_lshl_add_u32 v161, v46, 7, v160
	global_load_dwordx4 v[136:139], v161, s[14:15]
	s_waitcnt vmcnt(23)
	v_cvt_pk_f32_fp8_e32 v[144:145], v140
	v_cvt_pk_f32_fp8_sdwa v[146:147], v140 src0_sel:WORD_1
	v_cvt_pk_f32_fp8_e32 v[148:149], v141
	v_cvt_pk_f32_fp8_sdwa v[150:151], v141 src0_sel:WORD_1
	v_cvt_pk_f32_fp8_e32 v[152:153], v142
	v_cvt_pk_f32_fp8_sdwa v[154:155], v142 src0_sel:WORD_1
	v_cvt_pk_f32_fp8_e32 v[156:157], v143
	v_cvt_pk_f32_fp8_sdwa v[158:159], v143 src0_sel:WORD_1
	v_fmac_f32_e32 v0, v63, v144
	v_fmac_f32_e32 v1, v63, v145
	v_fmac_f32_e32 v2, v63, v146
	v_fmac_f32_e32 v3, v63, v147
	v_fmac_f32_e32 v4, v63, v148
	v_fmac_f32_e32 v5, v63, v149
	v_fmac_f32_e32 v6, v63, v150
	v_fmac_f32_e32 v7, v63, v151
	v_fmac_f32_e32 v8, v63, v152
	v_fmac_f32_e32 v9, v63, v153
	v_fmac_f32_e32 v10, v63, v154
	v_fmac_f32_e32 v11, v63, v155
	v_fmac_f32_e32 v12, v63, v156
	v_fmac_f32_e32 v13, v63, v157
	v_fmac_f32_e32 v14, v63, v158
	v_fmac_f32_e32 v15, v63, v159
	v_lshl_add_u32 v161, v47, 7, v160
	global_load_dwordx4 v[140:143], v161, s[14:15]
	global_load_dwordx4 v[32:35], v163, s[16:17] offset:448
	global_load_dwordx4 v[36:39], v163, s[16:17] offset:464
	global_load_dwordx4 v[40:43], v163, s[16:17] offset:480
	global_load_dwordx4 v[44:47], v163, s[16:17] offset:496
	global_load_dwordx4 v[48:51], v163, s[18:19] offset:384
	global_load_dwordx4 v[52:55], v163, s[18:19] offset:400
	global_load_dwordx4 v[56:59], v163, s[18:19] offset:416
	global_load_dwordx4 v[60:63], v163, s[18:19] offset:432
	s_waitcnt vmcnt(23)
	v_cvt_pk_f32_fp8_e32 v[144:145], v80
	v_cvt_pk_f32_fp8_sdwa v[146:147], v80 src0_sel:WORD_1
	v_cvt_pk_f32_fp8_e32 v[148:149], v81
	v_cvt_pk_f32_fp8_sdwa v[150:151], v81 src0_sel:WORD_1
	v_cvt_pk_f32_fp8_e32 v[152:153], v82
	v_cvt_pk_f32_fp8_sdwa v[154:155], v82 src0_sel:WORD_1
	v_cvt_pk_f32_fp8_e32 v[156:157], v83
	v_cvt_pk_f32_fp8_sdwa v[158:159], v83 src0_sel:WORD_1
	v_fmac_f32_e32 v0, v64, v144
	v_fmac_f32_e32 v1, v64, v145
	v_fmac_f32_e32 v2, v64, v146
	v_fmac_f32_e32 v3, v64, v147
	v_fmac_f32_e32 v4, v64, v148
	v_fmac_f32_e32 v5, v64, v149
	v_fmac_f32_e32 v6, v64, v150
	v_fmac_f32_e32 v7, v64, v151
	v_fmac_f32_e32 v8, v64, v152
	v_fmac_f32_e32 v9, v64, v153
	v_fmac_f32_e32 v10, v64, v154
	v_fmac_f32_e32 v11, v64, v155
	v_fmac_f32_e32 v12, v64, v156
	v_fmac_f32_e32 v13, v64, v157
	v_fmac_f32_e32 v14, v64, v158
	v_fmac_f32_e32 v15, v64, v159
	v_lshl_add_u32 v161, v16, 7, v160
	global_load_dwordx4 v[80:83], v161, s[14:15]
	s_waitcnt vmcnt(23)
	v_cvt_pk_f32_fp8_e32 v[144:145], v84
	v_cvt_pk_f32_fp8_sdwa v[146:147], v84 src0_sel:WORD_1
	v_cvt_pk_f32_fp8_e32 v[148:149], v85
	v_cvt_pk_f32_fp8_sdwa v[150:151], v85 src0_sel:WORD_1
	v_cvt_pk_f32_fp8_e32 v[152:153], v86
	v_cvt_pk_f32_fp8_sdwa v[154:155], v86 src0_sel:WORD_1
	v_cvt_pk_f32_fp8_e32 v[156:157], v87
	v_cvt_pk_f32_fp8_sdwa v[158:159], v87 src0_sel:WORD_1
	v_fmac_f32_e32 v0, v65, v144
	v_fmac_f32_e32 v1, v65, v145
	v_fmac_f32_e32 v2, v65, v146
	v_fmac_f32_e32 v3, v65, v147
	v_fmac_f32_e32 v4, v65, v148
	v_fmac_f32_e32 v5, v65, v149
	v_fmac_f32_e32 v6, v65, v150
	v_fmac_f32_e32 v7, v65, v151
	v_fmac_f32_e32 v8, v65, v152
	v_fmac_f32_e32 v9, v65, v153
	v_fmac_f32_e32 v10, v65, v154
	v_fmac_f32_e32 v11, v65, v155
	v_fmac_f32_e32 v12, v65, v156
	v_fmac_f32_e32 v13, v65, v157
	v_fmac_f32_e32 v14, v65, v158
	v_fmac_f32_e32 v15, v65, v159
	v_lshl_add_u32 v161, v17, 7, v160
	global_load_dwordx4 v[84:87], v161, s[14:15]
	s_waitcnt vmcnt(23)
; DI void phase_peer_b(const Params& p, int layer, const float* gnext, bool last) {
;     ...
;     for (int bt = 0; bt < 8; ++bt) {
;       u32x4 vr[16];
; #pragma unroll
;       for (int j = 0; j < 16; ++j) {
;         const int e = bt * 16 + j;
;         const int eidx = __builtin_amdgcn_readlane(e < 64 ? i0 : i1, e & 63);
;         vr[j] = *(const u32x4*)(EV + (size_t)eidx * DM + lane * 16);
;       }
; #pragma unroll
;       for (int j = 0; j < 16; ++j) {
;         const int e = bt * 16 + j;
;         const float wj = __int_as_float(__builtin_amdgcn_readlane(__float_as_int(e < 64 ? w0 : w1), e & 63));
; #pragma unroll
;         for (int w = 0; w < 4; ++w) {
;           const f32x2 lo = __builtin_amdgcn_cvt_pk_f32_fp8((int)vr[j][w], false);
;           const f32x2 hi = __builtin_amdgcn_cvt_pk_f32_fp8((int)vr[j][w], true);
;           acc[4 * w] += wj * lo[0]; acc[4 * w + 1] += wj * lo[1]; acc[4 * w + 2] += wj * hi[0]; acc[4 * w + 3] += wj * hi[1];
;         }
;       }
	v_cvt_pk_f32_fp8_e32 v[144:145], v88
	v_cvt_pk_f32_fp8_sdwa v[146:147], v88 src0_sel:WORD_1
	v_cvt_pk_f32_fp8_e32 v[148:149], v89
	v_cvt_pk_f32_fp8_sdwa v[150:151], v89 src0_sel:WORD_1
	v_cvt_pk_f32_fp8_e32 v[152:153], v90
	v_cvt_pk_f32_fp8_sdwa v[154:155], v90 src0_sel:WORD_1
	v_cvt_pk_f32_fp8_e32 v[156:157], v91
	v_cvt_pk_f32_fp8_sdwa v[158:159], v91 src0_sel:WORD_1
	v_fmac_f32_e32 v0, v66, v144
	v_fmac_f32_e32 v1, v66, v145
	v_fmac_f32_e32 v2, v66, v146
	v_fmac_f32_e32 v3, v66, v147
	v_fmac_f32_e32 v4, v66, v148
	v_fmac_f32_e32 v5, v66, v149
	v_fmac_f32_e32 v6, v66, v150
	v_fmac_f32_e32 v7, v66, v151
	v_fmac_f32_e32 v8, v66, v152
	v_fmac_f32_e32 v9, v66, v153
	v_fmac_f32_e32 v10, v66, v154
	v_fmac_f32_e32 v11, v66, v155
	v_fmac_f32_e32 v12, v66, v156
	v_fmac_f32_e32 v13, v66, v157
	v_fmac_f32_e32 v14, v66, v158
	v_fmac_f32_e32 v15, v66, v159
	v_lshl_add_u32 v161, v18, 7, v160
	global_load_dwordx4 v[88:91], v161, s[14:15]
	s_waitcnt vmcnt(23)
	v_cvt_pk_f32_fp8_e32 v[144:145], v92
	v_cvt_pk_f32_fp8_sdwa v[146:147], v92 src0_sel:WORD_1
	v_cvt_pk_f32_fp8_e32 v[148:149], v93
	v_cvt_pk_f32_fp8_sdwa v[150:151], v93 src0_sel:WORD_1
	v_cvt_pk_f32_fp8_e32 v[152:153], v94
	v_cvt_pk_f32_fp8_sdwa v[154:155], v94 src0_sel:WORD_1
	v_cvt_pk_f32_fp8_e32 v[156:157], v95
	v_cvt_pk_f32_fp8_sdwa v[158:159], v95 src0_sel:WORD_1
	v_fmac_f32_e32 v0, v67, v144
	v_fmac_f32_e32 v1, v67, v145
	v_fmac_f32_e32 v2, v67, v146
	v_fmac_f32_e32 v3, v67, v147
	v_fmac_f32_e32 v4, v67, v148
	v_fmac_f32_e32 v5, v67, v149
	v_fmac_f32_e32 v6, v67, v150
	v_fmac_f32_e32 v7, v67, v151
	v_fmac_f32_e32 v8, v67, v152
	v_fmac_f32_e32 v9, v67, v153
	v_fmac_f32_e32 v10, v67, v154
	v_fmac_f32_e32 v11, v67, v155
	v_fmac_f32_e32 v12, v67, v156
	v_fmac_f32_e32 v13, v67, v157
	v_fmac_f32_e32 v14, v67, v158
	v_fmac_f32_e32 v15, v67, v159
	v_lshl_add_u32 v161, v19, 7, v160
	global_load_dwordx4 v[92:95], v161, s[14:15]
	s_waitcnt vmcnt(23)
	v_cvt_pk_f32_fp8_e32 v[144:145], v96
	v_cvt_pk_f32_fp8_sdwa v[146:147], v96 src0_sel:WORD_1
	v_cvt_pk_f32_fp8_e32 v[148:149], v97
	v_cvt_pk_f32_fp8_sdwa v[150:151], v97 src0_sel:WORD_1
	v_cvt_pk_f32_fp8_e32 v[152:153], v98
	v_cvt_pk_f32_fp8_sdwa v[154:155], v98 src0_sel:WORD_1
	v_cvt_pk_f32_fp8_e32 v[156:157], v99
	v_cvt_pk_f32_fp8_sdwa v[158:159], v99 src0_sel:WORD_1
	v_fmac_f32_e32 v0, v68, v144
	v_fmac_f32_e32 v1, v68, v145
	v_fmac_f32_e32 v2, v68, v146
	v_fmac_f32_e32 v3, v68, v147
	v_fmac_f32_e32 v4, v68, v148
	v_fmac_f32_e32 v5, v68, v149
	v_fmac_f32_e32 v6, v68, v150
	v_fmac_f32_e32 v7, v68, v151
	v_fmac_f32_e32 v8, v68, v152
	v_fmac_f32_e32 v9, v68, v153
	v_fmac_f32_e32 v10, v68, v154
	v_fmac_f32_e32 v11, v68, v155
	v_fmac_f32_e32 v12, v68, v156
	v_fmac_f32_e32 v13, v68, v157
	v_fmac_f32_e32 v14, v68, v158
	v_fmac_f32_e32 v15, v68, v159
	v_lshl_add_u32 v161, v20, 7, v160
	global_load_dwordx4 v[96:99], v161, s[14:15]
	s_waitcnt vmcnt(23)
	v_cvt_pk_f32_fp8_e32 v[144:145], v100
	v_cvt_pk_f32_fp8_sdwa v[146:147], v100 src0_sel:WORD_1
	v_cvt_pk_f32_fp8_e32 v[148:149], v101
	v_cvt_pk_f32_fp8_sdwa v[150:151], v101 src0_sel:WORD_1
	v_cvt_pk_f32_fp8_e32 v[152:153], v102
	v_cvt_pk_f32_fp8_sdwa v[154:155], v102 src0_sel:WORD_1
	v_cvt_pk_f32_fp8_e32 v[156:157], v103
	v_cvt_pk_f32_fp8_sdwa v[158:159], v103 src0_sel:WORD_1
	v_fmac_f32_e32 v0, v69, v144
	v_fmac_f32_e32 v1, v69, v145
	v_fmac_f32_e32 v2, v69, v146
	v_fmac_f32_e32 v3, v69, v147
	v_fmac_f32_e32 v4, v69, v148
	v_fmac_f32_e32 v5, v69, v149
	v_fmac_f32_e32 v6, v69, v150
	v_fmac_f32_e32 v7, v69, v151
	v_fmac_f32_e32 v8, v69, v152
	v_fmac_f32_e32 v9, v69, v153
	v_fmac_f32_e32 v10, v69, v154
	v_fmac_f32_e32 v11, v69, v155
	v_fmac_f32_e32 v12, v69, v156
	v_fmac_f32_e32 v13, v69, v157
	v_fmac_f32_e32 v14, v69, v158
	v_fmac_f32_e32 v15, v69, v159
	v_lshl_add_u32 v161, v21, 7, v160
	global_load_dwordx4 v[100:103], v161, s[14:15]
	s_waitcnt vmcnt(23)
	v_cvt_pk_f32_fp8_e32 v[144:145], v104
	v_cvt_pk_f32_fp8_sdwa v[146:147], v104 src0_sel:WORD_1
	v_cvt_pk_f32_fp8_e32 v[148:149], v105
	v_cvt_pk_f32_fp8_sdwa v[150:151], v105 src0_sel:WORD_1
	v_cvt_pk_f32_fp8_e32 v[152:153], v106
	v_cvt_pk_f32_fp8_sdwa v[154:155], v106 src0_sel:WORD_1
	v_cvt_pk_f32_fp8_e32 v[156:157], v107
	v_cvt_pk_f32_fp8_sdwa v[158:159], v107 src0_sel:WORD_1
	v_fmac_f32_e32 v0, v70, v144
	v_fmac_f32_e32 v1, v70, v145
	v_fmac_f32_e32 v2, v70, v146
	v_fmac_f32_e32 v3, v70, v147
	v_fmac_f32_e32 v4, v70, v148
	v_fmac_f32_e32 v5, v70, v149
	v_fmac_f32_e32 v6, v70, v150
	v_fmac_f32_e32 v7, v70, v151
	v_fmac_f32_e32 v8, v70, v152
	v_fmac_f32_e32 v9, v70, v153
	v_fmac_f32_e32 v10, v70, v154
	v_fmac_f32_e32 v11, v70, v155
	v_fmac_f32_e32 v12, v70, v156
	v_fmac_f32_e32 v13, v70, v157
	v_fmac_f32_e32 v14, v70, v158
	v_fmac_f32_e32 v15, v70, v159
	v_lshl_add_u32 v161, v22, 7, v160
	global_load_dwordx4 v[104:107], v161, s[14:15]
	s_waitcnt vmcnt(23)
	v_cvt_pk_f32_fp8_e32 v[144:145], v108
	v_cvt_pk_f32_fp8_sdwa v[146:147], v108 src0_sel:WORD_1
	v_cvt_pk_f32_fp8_e32 v[148:149], v109
	v_cvt_pk_f32_fp8_sdwa v[150:151], v109 src0_sel:WORD_1
	v_cvt_pk_f32_fp8_e32 v[152:153], v110
	v_cvt_pk_f32_fp8_sdwa v[154:155], v110 src0_sel:WORD_1
	v_cvt_pk_f32_fp8_e32 v[156:157], v111
	v_cvt_pk_f32_fp8_sdwa v[158:159], v111 src0_sel:WORD_1
	v_fmac_f32_e32 v0, v71, v144
	v_fmac_f32_e32 v1, v71, v145
	v_fmac_f32_e32 v2, v71, v146
	v_fmac_f32_e32 v3, v71, v147
	v_fmac_f32_e32 v4, v71, v148
	v_fmac_f32_e32 v5, v71, v149
	v_fmac_f32_e32 v6, v71, v150
	v_fmac_f32_e32 v7, v71, v151
	v_fmac_f32_e32 v8, v71, v152
	v_fmac_f32_e32 v9, v71, v153
	v_fmac_f32_e32 v10, v71, v154
	v_fmac_f32_e32 v11, v71, v155
	v_fmac_f32_e32 v12, v71, v156
	v_fmac_f32_e32 v13, v71, v157
	v_fmac_f32_e32 v14, v71, v158
	v_fmac_f32_e32 v15, v71, v159
	v_lshl_add_u32 v161, v23, 7, v160
	global_load_dwordx4 v[108:111], v161, s[14:15]
	s_waitcnt vmcnt(23)
; DI void phase_peer_b(const Params& p, int layer, const float* gnext, bool last) {
;     ...
;     for (int bt = 0; bt < 8; ++bt) {
;       u32x4 vr[16];
; #pragma unroll
;       for (int j = 0; j < 16; ++j) {
;         const int e = bt * 16 + j;
;         const int eidx = __builtin_amdgcn_readlane(e < 64 ? i0 : i1, e & 63);
;         vr[j] = *(const u32x4*)(EV + (size_t)eidx * DM + lane * 16);
;       }
; #pragma unroll
;       for (int j = 0; j < 16; ++j) {
;         const int e = bt * 16 + j;
;         const float wj = __int_as_float(__builtin_amdgcn_readlane(__float_as_int(e < 64 ? w0 : w1), e & 63));
; #pragma unroll
;         for (int w = 0; w < 4; ++w) {
;           const f32x2 lo = __builtin_amdgcn_cvt_pk_f32_fp8((int)vr[j][w], false);
;           const f32x2 hi = __builtin_amdgcn_cvt_pk_f32_fp8((int)vr[j][w], true);
;           acc[4 * w] += wj * lo[0]; acc[4 * w + 1] += wj * lo[1]; acc[4 * w + 2] += wj * hi[0]; acc[4 * w + 3] += wj * hi[1];
;         }
;       }
	v_cvt_pk_f32_fp8_e32 v[144:145], v112
	v_cvt_pk_f32_fp8_sdwa v[146:147], v112 src0_sel:WORD_1
	v_cvt_pk_f32_fp8_e32 v[148:149], v113
	v_cvt_pk_f32_fp8_sdwa v[150:151], v113 src0_sel:WORD_1
	v_cvt_pk_f32_fp8_e32 v[152:153], v114
	v_cvt_pk_f32_fp8_sdwa v[154:155], v114 src0_sel:WORD_1
	v_cvt_pk_f32_fp8_e32 v[156:157], v115
	v_cvt_pk_f32_fp8_sdwa v[158:159], v115 src0_sel:WORD_1
	v_fmac_f32_e32 v0, v72, v144
	v_fmac_f32_e32 v1, v72, v145
	v_fmac_f32_e32 v2, v72, v146
	v_fmac_f32_e32 v3, v72, v147
	v_fmac_f32_e32 v4, v72, v148
	v_fmac_f32_e32 v5, v72, v149
	v_fmac_f32_e32 v6, v72, v150
	v_fmac_f32_e32 v7, v72, v151
	v_fmac_f32_e32 v8, v72, v152
	v_fmac_f32_e32 v9, v72, v153
	v_fmac_f32_e32 v10, v72, v154
	v_fmac_f32_e32 v11, v72, v155
	v_fmac_f32_e32 v12, v72, v156
	v_fmac_f32_e32 v13, v72, v157
	v_fmac_f32_e32 v14, v72, v158
	v_fmac_f32_e32 v15, v72, v159
	v_lshl_add_u32 v161, v24, 7, v160
	global_load_dwordx4 v[112:115], v161, s[14:15]
	s_waitcnt vmcnt(23)
	v_cvt_pk_f32_fp8_e32 v[144:145], v116
	v_cvt_pk_f32_fp8_sdwa v[146:147], v116 src0_sel:WORD_1
	v_cvt_pk_f32_fp8_e32 v[148:149], v117
	v_cvt_pk_f32_fp8_sdwa v[150:151], v117 src0_sel:WORD_1
	v_cvt_pk_f32_fp8_e32 v[152:153], v118
	v_cvt_pk_f32_fp8_sdwa v[154:155], v118 src0_sel:WORD_1
	v_cvt_pk_f32_fp8_e32 v[156:157], v119
	v_cvt_pk_f32_fp8_sdwa v[158:159], v119 src0_sel:WORD_1
	v_fmac_f32_e32 v0, v73, v144
	v_fmac_f32_e32 v1, v73, v145
	v_fmac_f32_e32 v2, v73, v146
	v_fmac_f32_e32 v3, v73, v147
	v_fmac_f32_e32 v4, v73, v148
	v_fmac_f32_e32 v5, v73, v149
	v_fmac_f32_e32 v6, v73, v150
	v_fmac_f32_e32 v7, v73, v151
	v_fmac_f32_e32 v8, v73, v152
	v_fmac_f32_e32 v9, v73, v153
	v_fmac_f32_e32 v10, v73, v154
	v_fmac_f32_e32 v11, v73, v155
	v_fmac_f32_e32 v12, v73, v156
	v_fmac_f32_e32 v13, v73, v157
	v_fmac_f32_e32 v14, v73, v158
	v_fmac_f32_e32 v15, v73, v159
	v_lshl_add_u32 v161, v25, 7, v160
	global_load_dwordx4 v[116:119], v161, s[14:15]
	s_waitcnt vmcnt(23)
	v_cvt_pk_f32_fp8_e32 v[144:145], v120
	v_cvt_pk_f32_fp8_sdwa v[146:147], v120 src0_sel:WORD_1
	v_cvt_pk_f32_fp8_e32 v[148:149], v121
	v_cvt_pk_f32_fp8_sdwa v[150:151], v121 src0_sel:WORD_1
	v_cvt_pk_f32_fp8_e32 v[152:153], v122
	v_cvt_pk_f32_fp8_sdwa v[154:155], v122 src0_sel:WORD_1
	v_cvt_pk_f32_fp8_e32 v[156:157], v123
	v_cvt_pk_f32_fp8_sdwa v[158:159], v123 src0_sel:WORD_1
	v_fmac_f32_e32 v0, v74, v144
	v_fmac_f32_e32 v1, v74, v145
	v_fmac_f32_e32 v2, v74, v146
	v_fmac_f32_e32 v3, v74, v147
	v_fmac_f32_e32 v4, v74, v148
	v_fmac_f32_e32 v5, v74, v149
	v_fmac_f32_e32 v6, v74, v150
	v_fmac_f32_e32 v7, v74, v151
	v_fmac_f32_e32 v8, v74, v152
	v_fmac_f32_e32 v9, v74, v153
	v_fmac_f32_e32 v10, v74, v154
	v_fmac_f32_e32 v11, v74, v155
	v_fmac_f32_e32 v12, v74, v156
	v_fmac_f32_e32 v13, v74, v157
	v_fmac_f32_e32 v14, v74, v158
	v_fmac_f32_e32 v15, v74, v159
	v_lshl_add_u32 v161, v26, 7, v160
	global_load_dwordx4 v[120:123], v161, s[14:15]
	s_waitcnt vmcnt(23)
	v_cvt_pk_f32_fp8_e32 v[144:145], v124
	v_cvt_pk_f32_fp8_sdwa v[146:147], v124 src0_sel:WORD_1
	v_cvt_pk_f32_fp8_e32 v[148:149], v125
	v_cvt_pk_f32_fp8_sdwa v[150:151], v125 src0_sel:WORD_1
	v_cvt_pk_f32_fp8_e32 v[152:153], v126
	v_cvt_pk_f32_fp8_sdwa v[154:155], v126 src0_sel:WORD_1
	v_cvt_pk_f32_fp8_e32 v[156:157], v127
	v_cvt_pk_f32_fp8_sdwa v[158:159], v127 src0_sel:WORD_1
	v_fmac_f32_e32 v0, v75, v144
	v_fmac_f32_e32 v1, v75, v145
	v_fmac_f32_e32 v2, v75, v146
	v_fmac_f32_e32 v3, v75, v147
	v_fmac_f32_e32 v4, v75, v148
	v_fmac_f32_e32 v5, v75, v149
	v_fmac_f32_e32 v6, v75, v150
	v_fmac_f32_e32 v7, v75, v151
	v_fmac_f32_e32 v8, v75, v152
	v_fmac_f32_e32 v9, v75, v153
	v_fmac_f32_e32 v10, v75, v154
	v_fmac_f32_e32 v11, v75, v155
	v_fmac_f32_e32 v12, v75, v156
	v_fmac_f32_e32 v13, v75, v157
	v_fmac_f32_e32 v14, v75, v158
	v_fmac_f32_e32 v15, v75, v159
	v_lshl_add_u32 v161, v27, 7, v160
	global_load_dwordx4 v[124:127], v161, s[14:15]
	s_waitcnt vmcnt(23)
	v_cvt_pk_f32_fp8_e32 v[144:145], v128
	v_cvt_pk_f32_fp8_sdwa v[146:147], v128 src0_sel:WORD_1
	v_cvt_pk_f32_fp8_e32 v[148:149], v129
	v_cvt_pk_f32_fp8_sdwa v[150:151], v129 src0_sel:WORD_1
	v_cvt_pk_f32_fp8_e32 v[152:153], v130
	v_cvt_pk_f32_fp8_sdwa v[154:155], v130 src0_sel:WORD_1
	v_cvt_pk_f32_fp8_e32 v[156:157], v131
	v_cvt_pk_f32_fp8_sdwa v[158:159], v131 src0_sel:WORD_1
	v_fmac_f32_e32 v0, v76, v144
	v_fmac_f32_e32 v1, v76, v145
	v_fmac_f32_e32 v2, v76, v146
	v_fmac_f32_e32 v3, v76, v147
	v_fmac_f32_e32 v4, v76, v148
	v_fmac_f32_e32 v5, v76, v149
	v_fmac_f32_e32 v6, v76, v150
	v_fmac_f32_e32 v7, v76, v151
	v_fmac_f32_e32 v8, v76, v152
	v_fmac_f32_e32 v9, v76, v153
	v_fmac_f32_e32 v10, v76, v154
	v_fmac_f32_e32 v11, v76, v155
	v_fmac_f32_e32 v12, v76, v156
	v_fmac_f32_e32 v13, v76, v157
	v_fmac_f32_e32 v14, v76, v158
	v_fmac_f32_e32 v15, v76, v159
	v_lshl_add_u32 v161, v28, 7, v160
	global_load_dwordx4 v[128:131], v161, s[14:15]
	s_waitcnt vmcnt(23)
	v_cvt_pk_f32_fp8_e32 v[144:145], v132
	v_cvt_pk_f32_fp8_sdwa v[146:147], v132 src0_sel:WORD_1
	v_cvt_pk_f32_fp8_e32 v[148:149], v133
	v_cvt_pk_f32_fp8_sdwa v[150:151], v133 src0_sel:WORD_1
	v_cvt_pk_f32_fp8_e32 v[152:153], v134
	v_cvt_pk_f32_fp8_sdwa v[154:155], v134 src0_sel:WORD_1
	v_cvt_pk_f32_fp8_e32 v[156:157], v135
	v_cvt_pk_f32_fp8_sdwa v[158:159], v135 src0_sel:WORD_1
	v_fmac_f32_e32 v0, v77, v144
	v_fmac_f32_e32 v1, v77, v145
	v_fmac_f32_e32 v2, v77, v146
	v_fmac_f32_e32 v3, v77, v147
	v_fmac_f32_e32 v4, v77, v148
	v_fmac_f32_e32 v5, v77, v149
	v_fmac_f32_e32 v6, v77, v150
	v_fmac_f32_e32 v7, v77, v151
	v_fmac_f32_e32 v8, v77, v152
	v_fmac_f32_e32 v9, v77, v153
	v_fmac_f32_e32 v10, v77, v154
	v_fmac_f32_e32 v11, v77, v155
	v_fmac_f32_e32 v12, v77, v156
	v_fmac_f32_e32 v13, v77, v157
	v_fmac_f32_e32 v14, v77, v158
	v_fmac_f32_e32 v15, v77, v159
	v_lshl_add_u32 v161, v29, 7, v160
	global_load_dwordx4 v[132:135], v161, s[14:15]
	s_waitcnt vmcnt(23)
; DI void phase_peer_b(const Params& p, int layer, const float* gnext, bool last) {
;     ...
;     for (int bt = 0; bt < 8; ++bt) {
;       u32x4 vr[16];
; #pragma unroll
;       for (int j = 0; j < 16; ++j) {
;         const int e = bt * 16 + j;
;         const int eidx = __builtin_amdgcn_readlane(e < 64 ? i0 : i1, e & 63);
;         vr[j] = *(const u32x4*)(EV + (size_t)eidx * DM + lane * 16);
;       }
; #pragma unroll
;       for (int j = 0; j < 16; ++j) {
;         const int e = bt * 16 + j;
;         const float wj = __int_as_float(__builtin_amdgcn_readlane(__float_as_int(e < 64 ? w0 : w1), e & 63));
; #pragma unroll
;         for (int w = 0; w < 4; ++w) {
;           const f32x2 lo = __builtin_amdgcn_cvt_pk_f32_fp8((int)vr[j][w], false);
;           const f32x2 hi = __builtin_amdgcn_cvt_pk_f32_fp8((int)vr[j][w], true);
;           acc[4 * w] += wj * lo[0]; acc[4 * w + 1] += wj * lo[1]; acc[4 * w + 2] += wj * hi[0]; acc[4 * w + 3] += wj * hi[1];
;         }
;       }
	v_cvt_pk_f32_fp8_e32 v[144:145], v136
	v_cvt_pk_f32_fp8_sdwa v[146:147], v136 src0_sel:WORD_1
	v_cvt_pk_f32_fp8_e32 v[148:149], v137
	v_cvt_pk_f32_fp8_sdwa v[150:151], v137 src0_sel:WORD_1
	v_cvt_pk_f32_fp8_e32 v[152:153], v138
	v_cvt_pk_f32_fp8_sdwa v[154:155], v138 src0_sel:WORD_1
	v_cvt_pk_f32_fp8_e32 v[156:157], v139
	v_cvt_pk_f32_fp8_sdwa v[158:159], v139 src0_sel:WORD_1
	v_fmac_f32_e32 v0, v78, v144
	v_fmac_f32_e32 v1, v78, v145
	v_fmac_f32_e32 v2, v78, v146
	v_fmac_f32_e32 v3, v78, v147
	v_fmac_f32_e32 v4, v78, v148
	v_fmac_f32_e32 v5, v78, v149
	v_fmac_f32_e32 v6, v78, v150
	v_fmac_f32_e32 v7, v78, v151
	v_fmac_f32_e32 v8, v78, v152
	v_fmac_f32_e32 v9, v78, v153
	v_fmac_f32_e32 v10, v78, v154
	v_fmac_f32_e32 v11, v78, v155
	v_fmac_f32_e32 v12, v78, v156
	v_fmac_f32_e32 v13, v78, v157
	v_fmac_f32_e32 v14, v78, v158
	v_fmac_f32_e32 v15, v78, v159
	v_lshl_add_u32 v161, v30, 7, v160
	global_load_dwordx4 v[136:139], v161, s[14:15]
	s_waitcnt vmcnt(23)
	v_cvt_pk_f32_fp8_e32 v[144:145], v140
	v_cvt_pk_f32_fp8_sdwa v[146:147], v140 src0_sel:WORD_1
	v_cvt_pk_f32_fp8_e32 v[148:149], v141
	v_cvt_pk_f32_fp8_sdwa v[150:151], v141 src0_sel:WORD_1
	v_cvt_pk_f32_fp8_e32 v[152:153], v142
	v_cvt_pk_f32_fp8_sdwa v[154:155], v142 src0_sel:WORD_1
	v_cvt_pk_f32_fp8_e32 v[156:157], v143
	v_cvt_pk_f32_fp8_sdwa v[158:159], v143 src0_sel:WORD_1
	v_fmac_f32_e32 v0, v79, v144
	v_fmac_f32_e32 v1, v79, v145
	v_fmac_f32_e32 v2, v79, v146
	v_fmac_f32_e32 v3, v79, v147
	v_fmac_f32_e32 v4, v79, v148
	v_fmac_f32_e32 v5, v79, v149
	v_fmac_f32_e32 v6, v79, v150
	v_fmac_f32_e32 v7, v79, v151
	v_fmac_f32_e32 v8, v79, v152
	v_fmac_f32_e32 v9, v79, v153
	v_fmac_f32_e32 v10, v79, v154
	v_fmac_f32_e32 v11, v79, v155
	v_fmac_f32_e32 v12, v79, v156
	v_fmac_f32_e32 v13, v79, v157
	v_fmac_f32_e32 v14, v79, v158
	v_fmac_f32_e32 v15, v79, v159
	v_lshl_add_u32 v161, v31, 7, v160
	global_load_dwordx4 v[140:143], v161, s[14:15]
	global_load_dwordx4 v[64:67], v163, s[18:19] offset:448
	global_load_dwordx4 v[68:71], v163, s[18:19] offset:464
	global_load_dwordx4 v[72:75], v163, s[18:19] offset:480
	global_load_dwordx4 v[76:79], v163, s[18:19] offset:496
	s_waitcnt vmcnt(19)
	v_cvt_pk_f32_fp8_e32 v[144:145], v80
	v_cvt_pk_f32_fp8_sdwa v[146:147], v80 src0_sel:WORD_1
	v_cvt_pk_f32_fp8_e32 v[148:149], v81
	v_cvt_pk_f32_fp8_sdwa v[150:151], v81 src0_sel:WORD_1
	v_cvt_pk_f32_fp8_e32 v[152:153], v82
	v_cvt_pk_f32_fp8_sdwa v[154:155], v82 src0_sel:WORD_1
	v_cvt_pk_f32_fp8_e32 v[156:157], v83
	v_cvt_pk_f32_fp8_sdwa v[158:159], v83 src0_sel:WORD_1
	v_fmac_f32_e32 v0, v48, v144
	v_fmac_f32_e32 v1, v48, v145
	v_fmac_f32_e32 v2, v48, v146
	v_fmac_f32_e32 v3, v48, v147
	v_fmac_f32_e32 v4, v48, v148
	v_fmac_f32_e32 v5, v48, v149
	v_fmac_f32_e32 v6, v48, v150
	v_fmac_f32_e32 v7, v48, v151
	v_fmac_f32_e32 v8, v48, v152
	v_fmac_f32_e32 v9, v48, v153
	v_fmac_f32_e32 v10, v48, v154
	v_fmac_f32_e32 v11, v48, v155
	v_fmac_f32_e32 v12, v48, v156
	v_fmac_f32_e32 v13, v48, v157
	v_fmac_f32_e32 v14, v48, v158
	v_fmac_f32_e32 v15, v48, v159
	v_lshl_add_u32 v161, v32, 7, v160
	global_load_dwordx4 v[80:83], v161, s[14:15]
	s_waitcnt vmcnt(19)
	v_cvt_pk_f32_fp8_e32 v[144:145], v84
	v_cvt_pk_f32_fp8_sdwa v[146:147], v84 src0_sel:WORD_1
	v_cvt_pk_f32_fp8_e32 v[148:149], v85
	v_cvt_pk_f32_fp8_sdwa v[150:151], v85 src0_sel:WORD_1
	v_cvt_pk_f32_fp8_e32 v[152:153], v86
	v_cvt_pk_f32_fp8_sdwa v[154:155], v86 src0_sel:WORD_1
	v_cvt_pk_f32_fp8_e32 v[156:157], v87
	v_cvt_pk_f32_fp8_sdwa v[158:159], v87 src0_sel:WORD_1
	v_fmac_f32_e32 v0, v49, v144
	v_fmac_f32_e32 v1, v49, v145
	v_fmac_f32_e32 v2, v49, v146
	v_fmac_f32_e32 v3, v49, v147
	v_fmac_f32_e32 v4, v49, v148
	v_fmac_f32_e32 v5, v49, v149
	v_fmac_f32_e32 v6, v49, v150
	v_fmac_f32_e32 v7, v49, v151
	v_fmac_f32_e32 v8, v49, v152
	v_fmac_f32_e32 v9, v49, v153
	v_fmac_f32_e32 v10, v49, v154
	v_fmac_f32_e32 v11, v49, v155
	v_fmac_f32_e32 v12, v49, v156
	v_fmac_f32_e32 v13, v49, v157
	v_fmac_f32_e32 v14, v49, v158
	v_fmac_f32_e32 v15, v49, v159
	v_lshl_add_u32 v161, v33, 7, v160
	global_load_dwordx4 v[84:87], v161, s[14:15]
	s_waitcnt vmcnt(19)
	v_cvt_pk_f32_fp8_e32 v[144:145], v88
	v_cvt_pk_f32_fp8_sdwa v[146:147], v88 src0_sel:WORD_1
	v_cvt_pk_f32_fp8_e32 v[148:149], v89
	v_cvt_pk_f32_fp8_sdwa v[150:151], v89 src0_sel:WORD_1
	v_cvt_pk_f32_fp8_e32 v[152:153], v90
	v_cvt_pk_f32_fp8_sdwa v[154:155], v90 src0_sel:WORD_1
	v_cvt_pk_f32_fp8_e32 v[156:157], v91
	v_cvt_pk_f32_fp8_sdwa v[158:159], v91 src0_sel:WORD_1
	v_fmac_f32_e32 v0, v50, v144
	v_fmac_f32_e32 v1, v50, v145
	v_fmac_f32_e32 v2, v50, v146
	v_fmac_f32_e32 v3, v50, v147
	v_fmac_f32_e32 v4, v50, v148
	v_fmac_f32_e32 v5, v50, v149
	v_fmac_f32_e32 v6, v50, v150
	v_fmac_f32_e32 v7, v50, v151
	v_fmac_f32_e32 v8, v50, v152
	v_fmac_f32_e32 v9, v50, v153
	v_fmac_f32_e32 v10, v50, v154
	v_fmac_f32_e32 v11, v50, v155
	v_fmac_f32_e32 v12, v50, v156
	v_fmac_f32_e32 v13, v50, v157
	v_fmac_f32_e32 v14, v50, v158
	v_fmac_f32_e32 v15, v50, v159
	v_lshl_add_u32 v161, v34, 7, v160
	global_load_dwordx4 v[88:91], v161, s[14:15]
	s_waitcnt vmcnt(19)
	v_cvt_pk_f32_fp8_e32 v[144:145], v92
	v_cvt_pk_f32_fp8_sdwa v[146:147], v92 src0_sel:WORD_1
	v_cvt_pk_f32_fp8_e32 v[148:149], v93
	v_cvt_pk_f32_fp8_sdwa v[150:151], v93 src0_sel:WORD_1
	v_cvt_pk_f32_fp8_e32 v[152:153], v94
	v_cvt_pk_f32_fp8_sdwa v[154:155], v94 src0_sel:WORD_1
	v_cvt_pk_f32_fp8_e32 v[156:157], v95
	v_cvt_pk_f32_fp8_sdwa v[158:159], v95 src0_sel:WORD_1
	v_fmac_f32_e32 v0, v51, v144
	v_fmac_f32_e32 v1, v51, v145
	v_fmac_f32_e32 v2, v51, v146
	v_fmac_f32_e32 v3, v51, v147
	v_fmac_f32_e32 v4, v51, v148
	v_fmac_f32_e32 v5, v51, v149
	v_fmac_f32_e32 v6, v51, v150
	v_fmac_f32_e32 v7, v51, v151
	v_fmac_f32_e32 v8, v51, v152
	v_fmac_f32_e32 v9, v51, v153
	v_fmac_f32_e32 v10, v51, v154
	v_fmac_f32_e32 v11, v51, v155
	v_fmac_f32_e32 v12, v51, v156
	v_fmac_f32_e32 v13, v51, v157
	v_fmac_f32_e32 v14, v51, v158
	v_fmac_f32_e32 v15, v51, v159
	v_lshl_add_u32 v161, v35, 7, v160
	global_load_dwordx4 v[92:95], v161, s[14:15]
	s_waitcnt vmcnt(19)
; DI void phase_peer_b(const Params& p, int layer, const float* gnext, bool last) {
;     ...
;     for (int bt = 0; bt < 8; ++bt) {
;       u32x4 vr[16];
; #pragma unroll
;       for (int j = 0; j < 16; ++j) {
;         const int e = bt * 16 + j;
;         const int eidx = __builtin_amdgcn_readlane(e < 64 ? i0 : i1, e & 63);
;         vr[j] = *(const u32x4*)(EV + (size_t)eidx * DM + lane * 16);
;       }
; #pragma unroll
;       for (int j = 0; j < 16; ++j) {
;         const int e = bt * 16 + j;
;         const float wj = __int_as_float(__builtin_amdgcn_readlane(__float_as_int(e < 64 ? w0 : w1), e & 63));
; #pragma unroll
;         for (int w = 0; w < 4; ++w) {
;           const f32x2 lo = __builtin_amdgcn_cvt_pk_f32_fp8((int)vr[j][w], false);
;           const f32x2 hi = __builtin_amdgcn_cvt_pk_f32_fp8((int)vr[j][w], true);
;           acc[4 * w] += wj * lo[0]; acc[4 * w + 1] += wj * lo[1]; acc[4 * w + 2] += wj * hi[0]; acc[4 * w + 3] += wj * hi[1];
;         }
;       }
	v_cvt_pk_f32_fp8_e32 v[144:145], v96
	v_cvt_pk_f32_fp8_sdwa v[146:147], v96 src0_sel:WORD_1
	v_cvt_pk_f32_fp8_e32 v[148:149], v97
	v_cvt_pk_f32_fp8_sdwa v[150:151], v97 src0_sel:WORD_1
	v_cvt_pk_f32_fp8_e32 v[152:153], v98
	v_cvt_pk_f32_fp8_sdwa v[154:155], v98 src0_sel:WORD_1
	v_cvt_pk_f32_fp8_e32 v[156:157], v99
	v_cvt_pk_f32_fp8_sdwa v[158:159], v99 src0_sel:WORD_1
	v_fmac_f32_e32 v0, v52, v144
	v_fmac_f32_e32 v1, v52, v145
	v_fmac_f32_e32 v2, v52, v146
	v_fmac_f32_e32 v3, v52, v147
	v_fmac_f32_e32 v4, v52, v148
	v_fmac_f32_e32 v5, v52, v149
	v_fmac_f32_e32 v6, v52, v150
	v_fmac_f32_e32 v7, v52, v151
	v_fmac_f32_e32 v8, v52, v152
	v_fmac_f32_e32 v9, v52, v153
	v_fmac_f32_e32 v10, v52, v154
	v_fmac_f32_e32 v11, v52, v155
	v_fmac_f32_e32 v12, v52, v156
	v_fmac_f32_e32 v13, v52, v157
	v_fmac_f32_e32 v14, v52, v158
	v_fmac_f32_e32 v15, v52, v159
	v_lshl_add_u32 v161, v36, 7, v160
	global_load_dwordx4 v[96:99], v161, s[14:15]
	s_waitcnt vmcnt(19)
	v_cvt_pk_f32_fp8_e32 v[144:145], v100
	v_cvt_pk_f32_fp8_sdwa v[146:147], v100 src0_sel:WORD_1
	v_cvt_pk_f32_fp8_e32 v[148:149], v101
	v_cvt_pk_f32_fp8_sdwa v[150:151], v101 src0_sel:WORD_1
	v_cvt_pk_f32_fp8_e32 v[152:153], v102
	v_cvt_pk_f32_fp8_sdwa v[154:155], v102 src0_sel:WORD_1
	v_cvt_pk_f32_fp8_e32 v[156:157], v103
	v_cvt_pk_f32_fp8_sdwa v[158:159], v103 src0_sel:WORD_1
	v_fmac_f32_e32 v0, v53, v144
	v_fmac_f32_e32 v1, v53, v145
	v_fmac_f32_e32 v2, v53, v146
	v_fmac_f32_e32 v3, v53, v147
	v_fmac_f32_e32 v4, v53, v148
	v_fmac_f32_e32 v5, v53, v149
	v_fmac_f32_e32 v6, v53, v150
	v_fmac_f32_e32 v7, v53, v151
	v_fmac_f32_e32 v8, v53, v152
	v_fmac_f32_e32 v9, v53, v153
	v_fmac_f32_e32 v10, v53, v154
	v_fmac_f32_e32 v11, v53, v155
	v_fmac_f32_e32 v12, v53, v156
	v_fmac_f32_e32 v13, v53, v157
	v_fmac_f32_e32 v14, v53, v158
	v_fmac_f32_e32 v15, v53, v159
	v_lshl_add_u32 v161, v37, 7, v160
	global_load_dwordx4 v[100:103], v161, s[14:15]
	s_waitcnt vmcnt(19)
	v_cvt_pk_f32_fp8_e32 v[144:145], v104
	v_cvt_pk_f32_fp8_sdwa v[146:147], v104 src0_sel:WORD_1
	v_cvt_pk_f32_fp8_e32 v[148:149], v105
	v_cvt_pk_f32_fp8_sdwa v[150:151], v105 src0_sel:WORD_1
	v_cvt_pk_f32_fp8_e32 v[152:153], v106
	v_cvt_pk_f32_fp8_sdwa v[154:155], v106 src0_sel:WORD_1
	v_cvt_pk_f32_fp8_e32 v[156:157], v107
	v_cvt_pk_f32_fp8_sdwa v[158:159], v107 src0_sel:WORD_1
	v_fmac_f32_e32 v0, v54, v144
	v_fmac_f32_e32 v1, v54, v145
	v_fmac_f32_e32 v2, v54, v146
	v_fmac_f32_e32 v3, v54, v147
	v_fmac_f32_e32 v4, v54, v148
	v_fmac_f32_e32 v5, v54, v149
	v_fmac_f32_e32 v6, v54, v150
	v_fmac_f32_e32 v7, v54, v151
	v_fmac_f32_e32 v8, v54, v152
	v_fmac_f32_e32 v9, v54, v153
	v_fmac_f32_e32 v10, v54, v154
	v_fmac_f32_e32 v11, v54, v155
	v_fmac_f32_e32 v12, v54, v156
	v_fmac_f32_e32 v13, v54, v157
	v_fmac_f32_e32 v14, v54, v158
	v_fmac_f32_e32 v15, v54, v159
	v_lshl_add_u32 v161, v38, 7, v160
	global_load_dwordx4 v[104:107], v161, s[14:15]
	s_waitcnt vmcnt(19)
	v_cvt_pk_f32_fp8_e32 v[144:145], v108
	v_cvt_pk_f32_fp8_sdwa v[146:147], v108 src0_sel:WORD_1
	v_cvt_pk_f32_fp8_e32 v[148:149], v109
	v_cvt_pk_f32_fp8_sdwa v[150:151], v109 src0_sel:WORD_1
	v_cvt_pk_f32_fp8_e32 v[152:153], v110
	v_cvt_pk_f32_fp8_sdwa v[154:155], v110 src0_sel:WORD_1
	v_cvt_pk_f32_fp8_e32 v[156:157], v111
	v_cvt_pk_f32_fp8_sdwa v[158:159], v111 src0_sel:WORD_1
	v_fmac_f32_e32 v0, v55, v144
	v_fmac_f32_e32 v1, v55, v145
	v_fmac_f32_e32 v2, v55, v146
	v_fmac_f32_e32 v3, v55, v147
	v_fmac_f32_e32 v4, v55, v148
	v_fmac_f32_e32 v5, v55, v149
	v_fmac_f32_e32 v6, v55, v150
	v_fmac_f32_e32 v7, v55, v151
	v_fmac_f32_e32 v8, v55, v152
	v_fmac_f32_e32 v9, v55, v153
	v_fmac_f32_e32 v10, v55, v154
	v_fmac_f32_e32 v11, v55, v155
	v_fmac_f32_e32 v12, v55, v156
	v_fmac_f32_e32 v13, v55, v157
	v_fmac_f32_e32 v14, v55, v158
	v_fmac_f32_e32 v15, v55, v159
	v_lshl_add_u32 v161, v39, 7, v160
	global_load_dwordx4 v[108:111], v161, s[14:15]
	s_waitcnt vmcnt(19)
	v_cvt_pk_f32_fp8_e32 v[144:145], v112
	v_cvt_pk_f32_fp8_sdwa v[146:147], v112 src0_sel:WORD_1
	v_cvt_pk_f32_fp8_e32 v[148:149], v113
	v_cvt_pk_f32_fp8_sdwa v[150:151], v113 src0_sel:WORD_1
	v_cvt_pk_f32_fp8_e32 v[152:153], v114
	v_cvt_pk_f32_fp8_sdwa v[154:155], v114 src0_sel:WORD_1
	v_cvt_pk_f32_fp8_e32 v[156:157], v115
	v_cvt_pk_f32_fp8_sdwa v[158:159], v115 src0_sel:WORD_1
	v_fmac_f32_e32 v0, v56, v144
	v_fmac_f32_e32 v1, v56, v145
	v_fmac_f32_e32 v2, v56, v146
	v_fmac_f32_e32 v3, v56, v147
	v_fmac_f32_e32 v4, v56, v148
	v_fmac_f32_e32 v5, v56, v149
	v_fmac_f32_e32 v6, v56, v150
	v_fmac_f32_e32 v7, v56, v151
	v_fmac_f32_e32 v8, v56, v152
	v_fmac_f32_e32 v9, v56, v153
	v_fmac_f32_e32 v10, v56, v154
	v_fmac_f32_e32 v11, v56, v155
	v_fmac_f32_e32 v12, v56, v156
	v_fmac_f32_e32 v13, v56, v157
	v_fmac_f32_e32 v14, v56, v158
	v_fmac_f32_e32 v15, v56, v159
	v_lshl_add_u32 v161, v40, 7, v160
	global_load_dwordx4 v[112:115], v161, s[14:15]
	s_waitcnt vmcnt(19)
	v_cvt_pk_f32_fp8_e32 v[144:145], v116
	v_cvt_pk_f32_fp8_sdwa v[146:147], v116 src0_sel:WORD_1
	v_cvt_pk_f32_fp8_e32 v[148:149], v117
	v_cvt_pk_f32_fp8_sdwa v[150:151], v117 src0_sel:WORD_1
	v_cvt_pk_f32_fp8_e32 v[152:153], v118
	v_cvt_pk_f32_fp8_sdwa v[154:155], v118 src0_sel:WORD_1
	v_cvt_pk_f32_fp8_e32 v[156:157], v119
	v_cvt_pk_f32_fp8_sdwa v[158:159], v119 src0_sel:WORD_1
	v_fmac_f32_e32 v0, v57, v144
	v_fmac_f32_e32 v1, v57, v145
	v_fmac_f32_e32 v2, v57, v146
	v_fmac_f32_e32 v3, v57, v147
	v_fmac_f32_e32 v4, v57, v148
	v_fmac_f32_e32 v5, v57, v149
	v_fmac_f32_e32 v6, v57, v150
	v_fmac_f32_e32 v7, v57, v151
	v_fmac_f32_e32 v8, v57, v152
	v_fmac_f32_e32 v9, v57, v153
	v_fmac_f32_e32 v10, v57, v154
	v_fmac_f32_e32 v11, v57, v155
	v_fmac_f32_e32 v12, v57, v156
	v_fmac_f32_e32 v13, v57, v157
	v_fmac_f32_e32 v14, v57, v158
	v_fmac_f32_e32 v15, v57, v159
	v_lshl_add_u32 v161, v41, 7, v160
	global_load_dwordx4 v[116:119], v161, s[14:15]
	s_waitcnt vmcnt(19)
; DI void phase_peer_b(const Params& p, int layer, const float* gnext, bool last) {
;     ...
;     for (int bt = 0; bt < 8; ++bt) {
;       u32x4 vr[16];
; #pragma unroll
;       for (int j = 0; j < 16; ++j) {
;         const int e = bt * 16 + j;
;         const int eidx = __builtin_amdgcn_readlane(e < 64 ? i0 : i1, e & 63);
;         vr[j] = *(const u32x4*)(EV + (size_t)eidx * DM + lane * 16);
;       }
; #pragma unroll
;       for (int j = 0; j < 16; ++j) {
;         const int e = bt * 16 + j;
;         const float wj = __int_as_float(__builtin_amdgcn_readlane(__float_as_int(e < 64 ? w0 : w1), e & 63));
; #pragma unroll
;         for (int w = 0; w < 4; ++w) {
;           const f32x2 lo = __builtin_amdgcn_cvt_pk_f32_fp8((int)vr[j][w], false);
;           const f32x2 hi = __builtin_amdgcn_cvt_pk_f32_fp8((int)vr[j][w], true);
;           acc[4 * w] += wj * lo[0]; acc[4 * w + 1] += wj * lo[1]; acc[4 * w + 2] += wj * hi[0]; acc[4 * w + 3] += wj * hi[1];
;         }
;       }
	v_cvt_pk_f32_fp8_e32 v[144:145], v120
	v_cvt_pk_f32_fp8_sdwa v[146:147], v120 src0_sel:WORD_1
	v_cvt_pk_f32_fp8_e32 v[148:149], v121
	v_cvt_pk_f32_fp8_sdwa v[150:151], v121 src0_sel:WORD_1
	v_cvt_pk_f32_fp8_e32 v[152:153], v122
	v_cvt_pk_f32_fp8_sdwa v[154:155], v122 src0_sel:WORD_1
	v_cvt_pk_f32_fp8_e32 v[156:157], v123
	v_cvt_pk_f32_fp8_sdwa v[158:159], v123 src0_sel:WORD_1
	v_fmac_f32_e32 v0, v58, v144
	v_fmac_f32_e32 v1, v58, v145
	v_fmac_f32_e32 v2, v58, v146
	v_fmac_f32_e32 v3, v58, v147
	v_fmac_f32_e32 v4, v58, v148
	v_fmac_f32_e32 v5, v58, v149
	v_fmac_f32_e32 v6, v58, v150
	v_fmac_f32_e32 v7, v58, v151
	v_fmac_f32_e32 v8, v58, v152
	v_fmac_f32_e32 v9, v58, v153
	v_fmac_f32_e32 v10, v58, v154
	v_fmac_f32_e32 v11, v58, v155
	v_fmac_f32_e32 v12, v58, v156
	v_fmac_f32_e32 v13, v58, v157
	v_fmac_f32_e32 v14, v58, v158
	v_fmac_f32_e32 v15, v58, v159
	v_lshl_add_u32 v161, v42, 7, v160
	global_load_dwordx4 v[120:123], v161, s[14:15]
	s_waitcnt vmcnt(19)
	v_cvt_pk_f32_fp8_e32 v[144:145], v124
	v_cvt_pk_f32_fp8_sdwa v[146:147], v124 src0_sel:WORD_1
	v_cvt_pk_f32_fp8_e32 v[148:149], v125
	v_cvt_pk_f32_fp8_sdwa v[150:151], v125 src0_sel:WORD_1
	v_cvt_pk_f32_fp8_e32 v[152:153], v126
	v_cvt_pk_f32_fp8_sdwa v[154:155], v126 src0_sel:WORD_1
	v_cvt_pk_f32_fp8_e32 v[156:157], v127
	v_cvt_pk_f32_fp8_sdwa v[158:159], v127 src0_sel:WORD_1
	v_fmac_f32_e32 v0, v59, v144
	v_fmac_f32_e32 v1, v59, v145
	v_fmac_f32_e32 v2, v59, v146
	v_fmac_f32_e32 v3, v59, v147
	v_fmac_f32_e32 v4, v59, v148
	v_fmac_f32_e32 v5, v59, v149
	v_fmac_f32_e32 v6, v59, v150
	v_fmac_f32_e32 v7, v59, v151
	v_fmac_f32_e32 v8, v59, v152
	v_fmac_f32_e32 v9, v59, v153
	v_fmac_f32_e32 v10, v59, v154
	v_fmac_f32_e32 v11, v59, v155
	v_fmac_f32_e32 v12, v59, v156
	v_fmac_f32_e32 v13, v59, v157
	v_fmac_f32_e32 v14, v59, v158
	v_fmac_f32_e32 v15, v59, v159
	v_lshl_add_u32 v161, v43, 7, v160
	global_load_dwordx4 v[124:127], v161, s[14:15]
	s_waitcnt vmcnt(19)
	v_cvt_pk_f32_fp8_e32 v[144:145], v128
	v_cvt_pk_f32_fp8_sdwa v[146:147], v128 src0_sel:WORD_1
	v_cvt_pk_f32_fp8_e32 v[148:149], v129
	v_cvt_pk_f32_fp8_sdwa v[150:151], v129 src0_sel:WORD_1
	v_cvt_pk_f32_fp8_e32 v[152:153], v130
	v_cvt_pk_f32_fp8_sdwa v[154:155], v130 src0_sel:WORD_1
	v_cvt_pk_f32_fp8_e32 v[156:157], v131
	v_cvt_pk_f32_fp8_sdwa v[158:159], v131 src0_sel:WORD_1
	v_fmac_f32_e32 v0, v60, v144
	v_fmac_f32_e32 v1, v60, v145
	v_fmac_f32_e32 v2, v60, v146
	v_fmac_f32_e32 v3, v60, v147
	v_fmac_f32_e32 v4, v60, v148
	v_fmac_f32_e32 v5, v60, v149
	v_fmac_f32_e32 v6, v60, v150
	v_fmac_f32_e32 v7, v60, v151
	v_fmac_f32_e32 v8, v60, v152
	v_fmac_f32_e32 v9, v60, v153
	v_fmac_f32_e32 v10, v60, v154
	v_fmac_f32_e32 v11, v60, v155
	v_fmac_f32_e32 v12, v60, v156
	v_fmac_f32_e32 v13, v60, v157
	v_fmac_f32_e32 v14, v60, v158
	v_fmac_f32_e32 v15, v60, v159
	v_lshl_add_u32 v161, v44, 7, v160
	global_load_dwordx4 v[128:131], v161, s[14:15]
	s_waitcnt vmcnt(19)
	v_cvt_pk_f32_fp8_e32 v[144:145], v132
	v_cvt_pk_f32_fp8_sdwa v[146:147], v132 src0_sel:WORD_1
	v_cvt_pk_f32_fp8_e32 v[148:149], v133
	v_cvt_pk_f32_fp8_sdwa v[150:151], v133 src0_sel:WORD_1
	v_cvt_pk_f32_fp8_e32 v[152:153], v134
	v_cvt_pk_f32_fp8_sdwa v[154:155], v134 src0_sel:WORD_1
	v_cvt_pk_f32_fp8_e32 v[156:157], v135
	v_cvt_pk_f32_fp8_sdwa v[158:159], v135 src0_sel:WORD_1
	v_fmac_f32_e32 v0, v61, v144
	v_fmac_f32_e32 v1, v61, v145
	v_fmac_f32_e32 v2, v61, v146
	v_fmac_f32_e32 v3, v61, v147
	v_fmac_f32_e32 v4, v61, v148
	v_fmac_f32_e32 v5, v61, v149
	v_fmac_f32_e32 v6, v61, v150
	v_fmac_f32_e32 v7, v61, v151
	v_fmac_f32_e32 v8, v61, v152
	v_fmac_f32_e32 v9, v61, v153
	v_fmac_f32_e32 v10, v61, v154
	v_fmac_f32_e32 v11, v61, v155
	v_fmac_f32_e32 v12, v61, v156
	v_fmac_f32_e32 v13, v61, v157
	v_fmac_f32_e32 v14, v61, v158
	v_fmac_f32_e32 v15, v61, v159
	v_lshl_add_u32 v161, v45, 7, v160
	global_load_dwordx4 v[132:135], v161, s[14:15]
	s_waitcnt vmcnt(19)
	v_cvt_pk_f32_fp8_e32 v[144:145], v136
	v_cvt_pk_f32_fp8_sdwa v[146:147], v136 src0_sel:WORD_1
	v_cvt_pk_f32_fp8_e32 v[148:149], v137
	v_cvt_pk_f32_fp8_sdwa v[150:151], v137 src0_sel:WORD_1
	v_cvt_pk_f32_fp8_e32 v[152:153], v138
	v_cvt_pk_f32_fp8_sdwa v[154:155], v138 src0_sel:WORD_1
	v_cvt_pk_f32_fp8_e32 v[156:157], v139
	v_cvt_pk_f32_fp8_sdwa v[158:159], v139 src0_sel:WORD_1
	v_fmac_f32_e32 v0, v62, v144
	v_fmac_f32_e32 v1, v62, v145
	v_fmac_f32_e32 v2, v62, v146
	v_fmac_f32_e32 v3, v62, v147
	v_fmac_f32_e32 v4, v62, v148
	v_fmac_f32_e32 v5, v62, v149
	v_fmac_f32_e32 v6, v62, v150
	v_fmac_f32_e32 v7, v62, v151
	v_fmac_f32_e32 v8, v62, v152
	v_fmac_f32_e32 v9, v62, v153
	v_fmac_f32_e32 v10, v62, v154
	v_fmac_f32_e32 v11, v62, v155
	v_fmac_f32_e32 v12, v62, v156
	v_fmac_f32_e32 v13, v62, v157
	v_fmac_f32_e32 v14, v62, v158
	v_fmac_f32_e32 v15, v62, v159
	v_lshl_add_u32 v161, v46, 7, v160
	global_load_dwordx4 v[136:139], v161, s[14:15]
	s_waitcnt vmcnt(19)
	v_cvt_pk_f32_fp8_e32 v[144:145], v140
	v_cvt_pk_f32_fp8_sdwa v[146:147], v140 src0_sel:WORD_1
	v_cvt_pk_f32_fp8_e32 v[148:149], v141
	v_cvt_pk_f32_fp8_sdwa v[150:151], v141 src0_sel:WORD_1
	v_cvt_pk_f32_fp8_e32 v[152:153], v142
	v_cvt_pk_f32_fp8_sdwa v[154:155], v142 src0_sel:WORD_1
	v_cvt_pk_f32_fp8_e32 v[156:157], v143
	v_cvt_pk_f32_fp8_sdwa v[158:159], v143 src0_sel:WORD_1
	v_fmac_f32_e32 v0, v63, v144
	v_fmac_f32_e32 v1, v63, v145
	v_fmac_f32_e32 v2, v63, v146
	v_fmac_f32_e32 v3, v63, v147
	v_fmac_f32_e32 v4, v63, v148
	v_fmac_f32_e32 v5, v63, v149
	v_fmac_f32_e32 v6, v63, v150
	v_fmac_f32_e32 v7, v63, v151
	v_fmac_f32_e32 v8, v63, v152
	v_fmac_f32_e32 v9, v63, v153
	v_fmac_f32_e32 v10, v63, v154
	v_fmac_f32_e32 v11, v63, v155
	v_fmac_f32_e32 v12, v63, v156
	v_fmac_f32_e32 v13, v63, v157
	v_fmac_f32_e32 v14, v63, v158
	v_fmac_f32_e32 v15, v63, v159
	v_lshl_add_u32 v161, v47, 7, v160
	global_load_dwordx4 v[140:143], v161, s[14:15]
	s_waitcnt vmcnt(15)
; DI void phase_peer_b(const Params& p, int layer, const float* gnext, bool last) {
;     ...
;     for (int bt = 0; bt < 8; ++bt) {
;       u32x4 vr[16];
; #pragma unroll
;       for (int j = 0; j < 16; ++j) {
;         const int e = bt * 16 + j;
;         const int eidx = __builtin_amdgcn_readlane(e < 64 ? i0 : i1, e & 63);
;         vr[j] = *(const u32x4*)(EV + (size_t)eidx * DM + lane * 16);
;       }
; #pragma unroll
;       for (int j = 0; j < 16; ++j) {
;         const int e = bt * 16 + j;
;         const float wj = __int_as_float(__builtin_amdgcn_readlane(__float_as_int(e < 64 ? w0 : w1), e & 63));
; #pragma unroll
;         for (int w = 0; w < 4; ++w) {
;           const f32x2 lo = __builtin_amdgcn_cvt_pk_f32_fp8((int)vr[j][w], false);
;           const f32x2 hi = __builtin_amdgcn_cvt_pk_f32_fp8((int)vr[j][w], true);
;           acc[4 * w] += wj * lo[0]; acc[4 * w + 1] += wj * lo[1]; acc[4 * w + 2] += wj * hi[0]; acc[4 * w + 3] += wj * hi[1];
;         }
;       }
	v_cvt_pk_f32_fp8_e32 v[144:145], v80
	v_cvt_pk_f32_fp8_sdwa v[146:147], v80 src0_sel:WORD_1
	v_cvt_pk_f32_fp8_e32 v[148:149], v81
	v_cvt_pk_f32_fp8_sdwa v[150:151], v81 src0_sel:WORD_1
	v_cvt_pk_f32_fp8_e32 v[152:153], v82
	v_cvt_pk_f32_fp8_sdwa v[154:155], v82 src0_sel:WORD_1
	v_cvt_pk_f32_fp8_e32 v[156:157], v83
	v_cvt_pk_f32_fp8_sdwa v[158:159], v83 src0_sel:WORD_1
	v_fmac_f32_e32 v0, v64, v144
	v_fmac_f32_e32 v1, v64, v145
	v_fmac_f32_e32 v2, v64, v146
	v_fmac_f32_e32 v3, v64, v147
	v_fmac_f32_e32 v4, v64, v148
	v_fmac_f32_e32 v5, v64, v149
	v_fmac_f32_e32 v6, v64, v150
	v_fmac_f32_e32 v7, v64, v151
	v_fmac_f32_e32 v8, v64, v152
	v_fmac_f32_e32 v9, v64, v153
	v_fmac_f32_e32 v10, v64, v154
	v_fmac_f32_e32 v11, v64, v155
	v_fmac_f32_e32 v12, v64, v156
	v_fmac_f32_e32 v13, v64, v157
	v_fmac_f32_e32 v14, v64, v158
	v_fmac_f32_e32 v15, v64, v159
	s_waitcnt vmcnt(14)
	v_cvt_pk_f32_fp8_e32 v[144:145], v84
	v_cvt_pk_f32_fp8_sdwa v[146:147], v84 src0_sel:WORD_1
	v_cvt_pk_f32_fp8_e32 v[148:149], v85
	v_cvt_pk_f32_fp8_sdwa v[150:151], v85 src0_sel:WORD_1
	v_cvt_pk_f32_fp8_e32 v[152:153], v86
	v_cvt_pk_f32_fp8_sdwa v[154:155], v86 src0_sel:WORD_1
	v_cvt_pk_f32_fp8_e32 v[156:157], v87
	v_cvt_pk_f32_fp8_sdwa v[158:159], v87 src0_sel:WORD_1
	v_fmac_f32_e32 v0, v65, v144
	v_fmac_f32_e32 v1, v65, v145
	v_fmac_f32_e32 v2, v65, v146
	v_fmac_f32_e32 v3, v65, v147
	v_fmac_f32_e32 v4, v65, v148
	v_fmac_f32_e32 v5, v65, v149
	v_fmac_f32_e32 v6, v65, v150
	v_fmac_f32_e32 v7, v65, v151
	v_fmac_f32_e32 v8, v65, v152
	v_fmac_f32_e32 v9, v65, v153
	v_fmac_f32_e32 v10, v65, v154
	v_fmac_f32_e32 v11, v65, v155
	v_fmac_f32_e32 v12, v65, v156
	v_fmac_f32_e32 v13, v65, v157
	v_fmac_f32_e32 v14, v65, v158
	v_fmac_f32_e32 v15, v65, v159
	s_waitcnt vmcnt(13)
	v_cvt_pk_f32_fp8_e32 v[144:145], v88
	v_cvt_pk_f32_fp8_sdwa v[146:147], v88 src0_sel:WORD_1
	v_cvt_pk_f32_fp8_e32 v[148:149], v89
	v_cvt_pk_f32_fp8_sdwa v[150:151], v89 src0_sel:WORD_1
	v_cvt_pk_f32_fp8_e32 v[152:153], v90
	v_cvt_pk_f32_fp8_sdwa v[154:155], v90 src0_sel:WORD_1
	v_cvt_pk_f32_fp8_e32 v[156:157], v91
	v_cvt_pk_f32_fp8_sdwa v[158:159], v91 src0_sel:WORD_1
	v_fmac_f32_e32 v0, v66, v144
	v_fmac_f32_e32 v1, v66, v145
	v_fmac_f32_e32 v2, v66, v146
	v_fmac_f32_e32 v3, v66, v147
	v_fmac_f32_e32 v4, v66, v148
	v_fmac_f32_e32 v5, v66, v149
	v_fmac_f32_e32 v6, v66, v150
	v_fmac_f32_e32 v7, v66, v151
	v_fmac_f32_e32 v8, v66, v152
	v_fmac_f32_e32 v9, v66, v153
	v_fmac_f32_e32 v10, v66, v154
	v_fmac_f32_e32 v11, v66, v155
	v_fmac_f32_e32 v12, v66, v156
	v_fmac_f32_e32 v13, v66, v157
	v_fmac_f32_e32 v14, v66, v158
	v_fmac_f32_e32 v15, v66, v159
	s_waitcnt vmcnt(12)
	v_cvt_pk_f32_fp8_e32 v[144:145], v92
	v_cvt_pk_f32_fp8_sdwa v[146:147], v92 src0_sel:WORD_1
	v_cvt_pk_f32_fp8_e32 v[148:149], v93
	v_cvt_pk_f32_fp8_sdwa v[150:151], v93 src0_sel:WORD_1
	v_cvt_pk_f32_fp8_e32 v[152:153], v94
	v_cvt_pk_f32_fp8_sdwa v[154:155], v94 src0_sel:WORD_1
	v_cvt_pk_f32_fp8_e32 v[156:157], v95
	v_cvt_pk_f32_fp8_sdwa v[158:159], v95 src0_sel:WORD_1
	v_fmac_f32_e32 v0, v67, v144
	v_fmac_f32_e32 v1, v67, v145
	v_fmac_f32_e32 v2, v67, v146
	v_fmac_f32_e32 v3, v67, v147
	v_fmac_f32_e32 v4, v67, v148
	v_fmac_f32_e32 v5, v67, v149
	v_fmac_f32_e32 v6, v67, v150
	v_fmac_f32_e32 v7, v67, v151
	v_fmac_f32_e32 v8, v67, v152
	v_fmac_f32_e32 v9, v67, v153
	v_fmac_f32_e32 v10, v67, v154
	v_fmac_f32_e32 v11, v67, v155
	v_fmac_f32_e32 v12, v67, v156
	v_fmac_f32_e32 v13, v67, v157
	v_fmac_f32_e32 v14, v67, v158
	v_fmac_f32_e32 v15, v67, v159
	s_waitcnt vmcnt(11)
	v_cvt_pk_f32_fp8_e32 v[144:145], v96
	v_cvt_pk_f32_fp8_sdwa v[146:147], v96 src0_sel:WORD_1
	v_cvt_pk_f32_fp8_e32 v[148:149], v97
	v_cvt_pk_f32_fp8_sdwa v[150:151], v97 src0_sel:WORD_1
	v_cvt_pk_f32_fp8_e32 v[152:153], v98
	v_cvt_pk_f32_fp8_sdwa v[154:155], v98 src0_sel:WORD_1
	v_cvt_pk_f32_fp8_e32 v[156:157], v99
	v_cvt_pk_f32_fp8_sdwa v[158:159], v99 src0_sel:WORD_1
	v_fmac_f32_e32 v0, v68, v144
	v_fmac_f32_e32 v1, v68, v145
	v_fmac_f32_e32 v2, v68, v146
	v_fmac_f32_e32 v3, v68, v147
	v_fmac_f32_e32 v4, v68, v148
	v_fmac_f32_e32 v5, v68, v149
	v_fmac_f32_e32 v6, v68, v150
	v_fmac_f32_e32 v7, v68, v151
	v_fmac_f32_e32 v8, v68, v152
	v_fmac_f32_e32 v9, v68, v153
	v_fmac_f32_e32 v10, v68, v154
	v_fmac_f32_e32 v11, v68, v155
	v_fmac_f32_e32 v12, v68, v156
	v_fmac_f32_e32 v13, v68, v157
	v_fmac_f32_e32 v14, v68, v158
	v_fmac_f32_e32 v15, v68, v159
	s_waitcnt vmcnt(10)
	v_cvt_pk_f32_fp8_e32 v[144:145], v100
	v_cvt_pk_f32_fp8_sdwa v[146:147], v100 src0_sel:WORD_1
	v_cvt_pk_f32_fp8_e32 v[148:149], v101
	v_cvt_pk_f32_fp8_sdwa v[150:151], v101 src0_sel:WORD_1
	v_cvt_pk_f32_fp8_e32 v[152:153], v102
	v_cvt_pk_f32_fp8_sdwa v[154:155], v102 src0_sel:WORD_1
	v_cvt_pk_f32_fp8_e32 v[156:157], v103
	v_cvt_pk_f32_fp8_sdwa v[158:159], v103 src0_sel:WORD_1
	v_fmac_f32_e32 v0, v69, v144
	v_fmac_f32_e32 v1, v69, v145
	v_fmac_f32_e32 v2, v69, v146
	v_fmac_f32_e32 v3, v69, v147
	v_fmac_f32_e32 v4, v69, v148
	v_fmac_f32_e32 v5, v69, v149
	v_fmac_f32_e32 v6, v69, v150
	v_fmac_f32_e32 v7, v69, v151
	v_fmac_f32_e32 v8, v69, v152
	v_fmac_f32_e32 v9, v69, v153
	v_fmac_f32_e32 v10, v69, v154
	v_fmac_f32_e32 v11, v69, v155
	v_fmac_f32_e32 v12, v69, v156
	v_fmac_f32_e32 v13, v69, v157
	v_fmac_f32_e32 v14, v69, v158
	v_fmac_f32_e32 v15, v69, v159
	s_waitcnt vmcnt(9)
; DI void phase_peer_b(const Params& p, int layer, const float* gnext, bool last) {
;     ...
;     for (int bt = 0; bt < 8; ++bt) {
;       u32x4 vr[16];
; #pragma unroll
;       for (int j = 0; j < 16; ++j) {
;         const int e = bt * 16 + j;
;         const int eidx = __builtin_amdgcn_readlane(e < 64 ? i0 : i1, e & 63);
;         vr[j] = *(const u32x4*)(EV + (size_t)eidx * DM + lane * 16);
;       }
; #pragma unroll
;       for (int j = 0; j < 16; ++j) {
;         const int e = bt * 16 + j;
;         const float wj = __int_as_float(__builtin_amdgcn_readlane(__float_as_int(e < 64 ? w0 : w1), e & 63));
; #pragma unroll
;         for (int w = 0; w < 4; ++w) {
;           const f32x2 lo = __builtin_amdgcn_cvt_pk_f32_fp8((int)vr[j][w], false);
;           const f32x2 hi = __builtin_amdgcn_cvt_pk_f32_fp8((int)vr[j][w], true);
;           acc[4 * w] += wj * lo[0]; acc[4 * w + 1] += wj * lo[1]; acc[4 * w + 2] += wj * hi[0]; acc[4 * w + 3] += wj * hi[1];
;         }
;       }
	v_cvt_pk_f32_fp8_e32 v[144:145], v104
	v_cvt_pk_f32_fp8_sdwa v[146:147], v104 src0_sel:WORD_1
	v_cvt_pk_f32_fp8_e32 v[148:149], v105
	v_cvt_pk_f32_fp8_sdwa v[150:151], v105 src0_sel:WORD_1
	v_cvt_pk_f32_fp8_e32 v[152:153], v106
	v_cvt_pk_f32_fp8_sdwa v[154:155], v106 src0_sel:WORD_1
	v_cvt_pk_f32_fp8_e32 v[156:157], v107
	v_cvt_pk_f32_fp8_sdwa v[158:159], v107 src0_sel:WORD_1
	v_fmac_f32_e32 v0, v70, v144
	v_fmac_f32_e32 v1, v70, v145
	v_fmac_f32_e32 v2, v70, v146
	v_fmac_f32_e32 v3, v70, v147
	v_fmac_f32_e32 v4, v70, v148
	v_fmac_f32_e32 v5, v70, v149
	v_fmac_f32_e32 v6, v70, v150
	v_fmac_f32_e32 v7, v70, v151
	v_fmac_f32_e32 v8, v70, v152
	v_fmac_f32_e32 v9, v70, v153
	v_fmac_f32_e32 v10, v70, v154
	v_fmac_f32_e32 v11, v70, v155
	v_fmac_f32_e32 v12, v70, v156
	v_fmac_f32_e32 v13, v70, v157
	v_fmac_f32_e32 v14, v70, v158
	v_fmac_f32_e32 v15, v70, v159
	s_waitcnt vmcnt(8)
	v_cvt_pk_f32_fp8_e32 v[144:145], v108
	v_cvt_pk_f32_fp8_sdwa v[146:147], v108 src0_sel:WORD_1
	v_cvt_pk_f32_fp8_e32 v[148:149], v109
	v_cvt_pk_f32_fp8_sdwa v[150:151], v109 src0_sel:WORD_1
	v_cvt_pk_f32_fp8_e32 v[152:153], v110
	v_cvt_pk_f32_fp8_sdwa v[154:155], v110 src0_sel:WORD_1
	v_cvt_pk_f32_fp8_e32 v[156:157], v111
	v_cvt_pk_f32_fp8_sdwa v[158:159], v111 src0_sel:WORD_1
	v_fmac_f32_e32 v0, v71, v144
	v_fmac_f32_e32 v1, v71, v145
	v_fmac_f32_e32 v2, v71, v146
	v_fmac_f32_e32 v3, v71, v147
	v_fmac_f32_e32 v4, v71, v148
	v_fmac_f32_e32 v5, v71, v149
	v_fmac_f32_e32 v6, v71, v150
	v_fmac_f32_e32 v7, v71, v151
	v_fmac_f32_e32 v8, v71, v152
	v_fmac_f32_e32 v9, v71, v153
	v_fmac_f32_e32 v10, v71, v154
	v_fmac_f32_e32 v11, v71, v155
	v_fmac_f32_e32 v12, v71, v156
	v_fmac_f32_e32 v13, v71, v157
	v_fmac_f32_e32 v14, v71, v158
	v_fmac_f32_e32 v15, v71, v159
	s_waitcnt vmcnt(7)
	v_cvt_pk_f32_fp8_e32 v[144:145], v112
	v_cvt_pk_f32_fp8_sdwa v[146:147], v112 src0_sel:WORD_1
	v_cvt_pk_f32_fp8_e32 v[148:149], v113
	v_cvt_pk_f32_fp8_sdwa v[150:151], v113 src0_sel:WORD_1
	v_cvt_pk_f32_fp8_e32 v[152:153], v114
	v_cvt_pk_f32_fp8_sdwa v[154:155], v114 src0_sel:WORD_1
	v_cvt_pk_f32_fp8_e32 v[156:157], v115
	v_cvt_pk_f32_fp8_sdwa v[158:159], v115 src0_sel:WORD_1
	v_fmac_f32_e32 v0, v72, v144
	v_fmac_f32_e32 v1, v72, v145
	v_fmac_f32_e32 v2, v72, v146
	v_fmac_f32_e32 v3, v72, v147
	v_fmac_f32_e32 v4, v72, v148
	v_fmac_f32_e32 v5, v72, v149
	v_fmac_f32_e32 v6, v72, v150
	v_fmac_f32_e32 v7, v72, v151
	v_fmac_f32_e32 v8, v72, v152
	v_fmac_f32_e32 v9, v72, v153
	v_fmac_f32_e32 v10, v72, v154
	v_fmac_f32_e32 v11, v72, v155
	v_fmac_f32_e32 v12, v72, v156
	v_fmac_f32_e32 v13, v72, v157
	v_fmac_f32_e32 v14, v72, v158
	v_fmac_f32_e32 v15, v72, v159
	s_waitcnt vmcnt(6)
	v_cvt_pk_f32_fp8_e32 v[144:145], v116
	v_cvt_pk_f32_fp8_sdwa v[146:147], v116 src0_sel:WORD_1
	v_cvt_pk_f32_fp8_e32 v[148:149], v117
	v_cvt_pk_f32_fp8_sdwa v[150:151], v117 src0_sel:WORD_1
	v_cvt_pk_f32_fp8_e32 v[152:153], v118
	v_cvt_pk_f32_fp8_sdwa v[154:155], v118 src0_sel:WORD_1
	v_cvt_pk_f32_fp8_e32 v[156:157], v119
	v_cvt_pk_f32_fp8_sdwa v[158:159], v119 src0_sel:WORD_1
	v_fmac_f32_e32 v0, v73, v144
	v_fmac_f32_e32 v1, v73, v145
	v_fmac_f32_e32 v2, v73, v146
	v_fmac_f32_e32 v3, v73, v147
	v_fmac_f32_e32 v4, v73, v148
	v_fmac_f32_e32 v5, v73, v149
	v_fmac_f32_e32 v6, v73, v150
	v_fmac_f32_e32 v7, v73, v151
	v_fmac_f32_e32 v8, v73, v152
	v_fmac_f32_e32 v9, v73, v153
	v_fmac_f32_e32 v10, v73, v154
	v_fmac_f32_e32 v11, v73, v155
	v_fmac_f32_e32 v12, v73, v156
	v_fmac_f32_e32 v13, v73, v157
	v_fmac_f32_e32 v14, v73, v158
	v_fmac_f32_e32 v15, v73, v159
	s_waitcnt vmcnt(5)
	v_cvt_pk_f32_fp8_e32 v[144:145], v120
	v_cvt_pk_f32_fp8_sdwa v[146:147], v120 src0_sel:WORD_1
	v_cvt_pk_f32_fp8_e32 v[148:149], v121
	v_cvt_pk_f32_fp8_sdwa v[150:151], v121 src0_sel:WORD_1
	v_cvt_pk_f32_fp8_e32 v[152:153], v122
	v_cvt_pk_f32_fp8_sdwa v[154:155], v122 src0_sel:WORD_1
	v_cvt_pk_f32_fp8_e32 v[156:157], v123
	v_cvt_pk_f32_fp8_sdwa v[158:159], v123 src0_sel:WORD_1
	v_fmac_f32_e32 v0, v74, v144
	v_fmac_f32_e32 v1, v74, v145
	v_fmac_f32_e32 v2, v74, v146
	v_fmac_f32_e32 v3, v74, v147
	v_fmac_f32_e32 v4, v74, v148
	v_fmac_f32_e32 v5, v74, v149
	v_fmac_f32_e32 v6, v74, v150
	v_fmac_f32_e32 v7, v74, v151
	v_fmac_f32_e32 v8, v74, v152
	v_fmac_f32_e32 v9, v74, v153
	v_fmac_f32_e32 v10, v74, v154
	v_fmac_f32_e32 v11, v74, v155
	v_fmac_f32_e32 v12, v74, v156
	v_fmac_f32_e32 v13, v74, v157
	v_fmac_f32_e32 v14, v74, v158
	v_fmac_f32_e32 v15, v74, v159
	s_waitcnt vmcnt(4)
	v_cvt_pk_f32_fp8_e32 v[144:145], v124
	v_cvt_pk_f32_fp8_sdwa v[146:147], v124 src0_sel:WORD_1
	v_cvt_pk_f32_fp8_e32 v[148:149], v125
	v_cvt_pk_f32_fp8_sdwa v[150:151], v125 src0_sel:WORD_1
	v_cvt_pk_f32_fp8_e32 v[152:153], v126
	v_cvt_pk_f32_fp8_sdwa v[154:155], v126 src0_sel:WORD_1
	v_cvt_pk_f32_fp8_e32 v[156:157], v127
	v_cvt_pk_f32_fp8_sdwa v[158:159], v127 src0_sel:WORD_1
	v_fmac_f32_e32 v0, v75, v144
	v_fmac_f32_e32 v1, v75, v145
	v_fmac_f32_e32 v2, v75, v146
	v_fmac_f32_e32 v3, v75, v147
	v_fmac_f32_e32 v4, v75, v148
	v_fmac_f32_e32 v5, v75, v149
	v_fmac_f32_e32 v6, v75, v150
	v_fmac_f32_e32 v7, v75, v151
	v_fmac_f32_e32 v8, v75, v152
	v_fmac_f32_e32 v9, v75, v153
	v_fmac_f32_e32 v10, v75, v154
	v_fmac_f32_e32 v11, v75, v155
	v_fmac_f32_e32 v12, v75, v156
	v_fmac_f32_e32 v13, v75, v157
	v_fmac_f32_e32 v14, v75, v158
	v_fmac_f32_e32 v15, v75, v159
	s_waitcnt vmcnt(3)
; DI void phase_peer_b(const Params& p, int layer, const float* gnext, bool last) {
;     ...
;       for (int j = 0; j < 16; ++j) {
;         const int e = bt * 16 + j;
;         const float wj = __int_as_float(__builtin_amdgcn_readlane(__float_as_int(e < 64 ? w0 : w1), e & 63));
; #pragma unroll
;         for (int w = 0; w < 4; ++w) {
;           const f32x2 lo = __builtin_amdgcn_cvt_pk_f32_fp8((int)vr[j][w], false);
;           const f32x2 hi = __builtin_amdgcn_cvt_pk_f32_fp8((int)vr[j][w], true);
;           acc[4 * w] += wj * lo[0]; acc[4 * w + 1] += wj * lo[1]; acc[4 * w + 2] += wj * hi[0]; acc[4 * w + 3] += wj * hi[1];
;         }
;       }
;     }
;       float* hp = hbuf + row * DM;
;       float hn[16];
; #pragma unroll
;       for (int q = 0; q < 2; ++q) {
;         const float4 a = *(const float4*)(hp + lane * 16 + q * 8);
;         const float4 bq = *(const float4*)(hp + lane * 16 + q * 8 + 4);
;         hn[q * 8 + 0] = a.x + acc[q * 8 + 0]; hn[q * 8 + 1] = a.y + acc[q * 8 + 1]; hn[q * 8 + 2] = a.z + acc[q * 8 + 2]; hn[q * 8 + 3] = a.w + acc[q * 8 + 3];
;         hn[q * 8 + 4] = bq.x + acc[q * 8 + 4]; hn[q * 8 + 5] = bq.y + acc[q * 8 + 5]; hn[q * 8 + 6] = bq.z + acc[q * 8 + 6]; hn[q * 8 + 7] = bq.w + acc[q * 8 + 7];
	v_cvt_pk_f32_fp8_e32 v[144:145], v128
	v_cvt_pk_f32_fp8_sdwa v[146:147], v128 src0_sel:WORD_1
	v_cvt_pk_f32_fp8_e32 v[148:149], v129
	v_cvt_pk_f32_fp8_sdwa v[150:151], v129 src0_sel:WORD_1
	v_cvt_pk_f32_fp8_e32 v[152:153], v130
	v_cvt_pk_f32_fp8_sdwa v[154:155], v130 src0_sel:WORD_1
	v_cvt_pk_f32_fp8_e32 v[156:157], v131
	v_cvt_pk_f32_fp8_sdwa v[158:159], v131 src0_sel:WORD_1
	v_fmac_f32_e32 v0, v76, v144
	v_fmac_f32_e32 v1, v76, v145
	v_fmac_f32_e32 v2, v76, v146
	v_fmac_f32_e32 v3, v76, v147
	v_fmac_f32_e32 v4, v76, v148
	v_fmac_f32_e32 v5, v76, v149
	v_fmac_f32_e32 v6, v76, v150
	v_fmac_f32_e32 v7, v76, v151
	v_fmac_f32_e32 v8, v76, v152
	v_fmac_f32_e32 v9, v76, v153
	v_fmac_f32_e32 v10, v76, v154
	v_fmac_f32_e32 v11, v76, v155
	v_fmac_f32_e32 v12, v76, v156
	v_fmac_f32_e32 v13, v76, v157
	v_fmac_f32_e32 v14, v76, v158
	v_fmac_f32_e32 v15, v76, v159
	s_waitcnt vmcnt(2)
	v_cvt_pk_f32_fp8_e32 v[144:145], v132
	v_cvt_pk_f32_fp8_sdwa v[146:147], v132 src0_sel:WORD_1
	v_cvt_pk_f32_fp8_e32 v[148:149], v133
	v_cvt_pk_f32_fp8_sdwa v[150:151], v133 src0_sel:WORD_1
	v_cvt_pk_f32_fp8_e32 v[152:153], v134
	v_cvt_pk_f32_fp8_sdwa v[154:155], v134 src0_sel:WORD_1
	v_cvt_pk_f32_fp8_e32 v[156:157], v135
	v_cvt_pk_f32_fp8_sdwa v[158:159], v135 src0_sel:WORD_1
	v_fmac_f32_e32 v0, v77, v144
	v_fmac_f32_e32 v1, v77, v145
	v_fmac_f32_e32 v2, v77, v146
	v_fmac_f32_e32 v3, v77, v147
	v_fmac_f32_e32 v4, v77, v148
	v_fmac_f32_e32 v5, v77, v149
	v_fmac_f32_e32 v6, v77, v150
	v_fmac_f32_e32 v7, v77, v151
	v_fmac_f32_e32 v8, v77, v152
	v_fmac_f32_e32 v9, v77, v153
	v_fmac_f32_e32 v10, v77, v154
	v_fmac_f32_e32 v11, v77, v155
	v_fmac_f32_e32 v12, v77, v156
	v_fmac_f32_e32 v13, v77, v157
	v_fmac_f32_e32 v14, v77, v158
	v_fmac_f32_e32 v15, v77, v159
	s_waitcnt vmcnt(1)
	v_cvt_pk_f32_fp8_e32 v[144:145], v136
	v_cvt_pk_f32_fp8_sdwa v[146:147], v136 src0_sel:WORD_1
	v_cvt_pk_f32_fp8_e32 v[148:149], v137
	v_cvt_pk_f32_fp8_sdwa v[150:151], v137 src0_sel:WORD_1
	v_cvt_pk_f32_fp8_e32 v[152:153], v138
	v_cvt_pk_f32_fp8_sdwa v[154:155], v138 src0_sel:WORD_1
	v_cvt_pk_f32_fp8_e32 v[156:157], v139
	v_cvt_pk_f32_fp8_sdwa v[158:159], v139 src0_sel:WORD_1
	v_fmac_f32_e32 v0, v78, v144
	v_fmac_f32_e32 v1, v78, v145
	v_fmac_f32_e32 v2, v78, v146
	v_fmac_f32_e32 v3, v78, v147
	v_fmac_f32_e32 v4, v78, v148
	v_fmac_f32_e32 v5, v78, v149
	v_fmac_f32_e32 v6, v78, v150
	v_fmac_f32_e32 v7, v78, v151
	v_fmac_f32_e32 v8, v78, v152
	v_fmac_f32_e32 v9, v78, v153
	v_fmac_f32_e32 v10, v78, v154
	v_fmac_f32_e32 v11, v78, v155
	v_fmac_f32_e32 v12, v78, v156
	v_fmac_f32_e32 v13, v78, v157
	v_fmac_f32_e32 v14, v78, v158
	v_fmac_f32_e32 v15, v78, v159
	s_waitcnt vmcnt(0)
	v_cvt_pk_f32_fp8_e32 v[144:145], v140
	v_cvt_pk_f32_fp8_sdwa v[146:147], v140 src0_sel:WORD_1
	v_cvt_pk_f32_fp8_e32 v[148:149], v141
	v_cvt_pk_f32_fp8_sdwa v[150:151], v141 src0_sel:WORD_1
	v_cvt_pk_f32_fp8_e32 v[152:153], v142
	v_cvt_pk_f32_fp8_sdwa v[154:155], v142 src0_sel:WORD_1
	v_cvt_pk_f32_fp8_e32 v[156:157], v143
	v_cvt_pk_f32_fp8_sdwa v[158:159], v143 src0_sel:WORD_1
	v_fmac_f32_e32 v0, v79, v144
	v_fmac_f32_e32 v1, v79, v145
	v_fmac_f32_e32 v2, v79, v146
	v_fmac_f32_e32 v3, v79, v147
	v_fmac_f32_e32 v4, v79, v148
	v_fmac_f32_e32 v5, v79, v149
	v_fmac_f32_e32 v6, v79, v150
	v_fmac_f32_e32 v7, v79, v151
	v_fmac_f32_e32 v8, v79, v152
	v_fmac_f32_e32 v9, v79, v153
	v_fmac_f32_e32 v10, v79, v154
	v_fmac_f32_e32 v11, v79, v155
	v_fmac_f32_e32 v12, v79, v156
	v_fmac_f32_e32 v13, v79, v157
	v_fmac_f32_e32 v14, v79, v158
	v_fmac_f32_e32 v15, v79, v159
	global_load_dwordx4 v[80:83], v164, s[20:21] offset:0
	global_load_dwordx4 v[84:87], v164, s[20:21] offset:16
	global_load_dwordx4 v[88:91], v164, s[20:21] offset:32
	global_load_dwordx4 v[92:95], v164, s[20:21] offset:48
	s_waitcnt vmcnt(0)
	v_add_f32_e32 v80, v80, v0
	v_add_f32_e32 v81, v81, v1
	v_add_f32_e32 v82, v82, v2
	v_add_f32_e32 v83, v83, v3
	v_add_f32_e32 v84, v84, v4
	v_add_f32_e32 v85, v85, v5
	v_add_f32_e32 v86, v86, v6
	v_add_f32_e32 v87, v87, v7
	v_add_f32_e32 v88, v88, v8
	v_add_f32_e32 v89, v89, v9
	v_add_f32_e32 v90, v90, v10
	v_add_f32_e32 v91, v91, v11
	v_add_f32_e32 v92, v92, v12
	v_add_f32_e32 v93, v93, v13
	v_add_f32_e32 v94, v94, v14
	v_add_f32_e32 v95, v95, v15
	global_store_dwordx4 v164, v[80:83], s[20:21] offset:0
	global_store_dwordx4 v164, v[84:87], s[20:21] offset:16
	global_store_dwordx4 v164, v[88:91], s[20:21] offset:32
	global_store_dwordx4 v164, v[92:95], s[20:21] offset:48
	s_add_u32 s22, s22, s23
	s_cmpk_lt_u32 s22, 0x2010
	s_cbranch_scc1 .Lpv0_item
; DI unsigned pack2(float a, float b) { return (unsigned)f2bf(a) | ((unsigned)f2bf(b) << 16); }
; DI void phase_peer_b(const Params& p, int layer, const float* gnext, bool last) {
;     ...
;       float ss = 0.f;
; #pragma unroll
;       for (int i = 0; i < 16; ++i) ss += hn[i] * hn[i];
;       ss = wave_sum(ss);
;       const float rn = rsqrtf(ss * (1.f / 1024.f) + 1e-6f);
;       float y[16];
; #pragma unroll
;       for (int q = 0; q < 2; ++q) {
;         const float4 ga = *(const float4*)(gnext + lane * 16 + q * 8);
;         const float4 gb = *(const float4*)(gnext + lane * 16 + q * 8 + 4);
;         y[q * 8 + 0] = hn[q * 8 + 0] * rn * ga.x; y[q * 8 + 1] = hn[q * 8 + 1] * rn * ga.y; y[q * 8 + 2] = hn[q * 8 + 2] * rn * ga.z; y[q * 8 + 3] = hn[q * 8 + 3] * rn * ga.w;
;         y[q * 8 + 4] = hn[q * 8 + 4] * rn * gb.x; y[q * 8 + 5] = hn[q * 8 + 5] * rn * gb.y; y[q * 8 + 6] = hn[q * 8 + 6] * rn * gb.z; y[q * 8 + 7] = hn[q * 8 + 7] * rn * gb.w;
;       }
;       if (!last) {
; #pragma unroll
;         for (int q = 0; q < 2; ++q) {
;           *(float4*)(hp + lane * 16 + q * 8) = make_float4(hn[q * 8 + 0], hn[q * 8 + 1], hn[q * 8 + 2], hn[q * 8 + 3]);
;           *(float4*)(hp + lane * 16 + q * 8 + 4) = make_float4(hn[q * 8 + 4], hn[q * 8 + 5], hn[q * 8 + 6], hn[q * 8 + 7]);
;           u32x4 o;
;           o[0] = pack2(y[q * 8 + 0], y[q * 8 + 1]); o[1] = pack2(y[q * 8 + 2], y[q * 8 + 3]); o[2] = pack2(y[q * 8 + 4], y[q * 8 + 5]); o[3] = pack2(y[q * 8 + 6], y[q * 8 + 7]);
;           *(u32x4*)(xnw + row * DM + lane * 16 + q * 8) = o;
.Lpv0_end:
	s_add_u32 s90, s90, 1
	s_waitcnt vmcnt(0) lgkmcnt(0)
	s_barrier
	s_cmp_lg_u32 s94, 0
	s_cbranch_scc1 .Lsy0_skip
	s_mov_b64 exec, 1
	buffer_wbl2 sc1
	s_waitcnt vmcnt(0)
	s_add_u32 s26, s68, 0x1e000000
	s_addc_u32 s27, s69, 0
	v_mov_b32_e32 v2, 0
	v_mov_b32_e32 v0, 1
	global_atomic_add v2, v0, s[26:27]
	s_mul_i32 s24, s70, s90
	s_mov_b32 s25, 0
	v_mov_b32_e32 v1, s24
.Lsy0_poll:
	s_sleep 1
	global_load_dword v0, v2, s[26:27] sc1
	s_add_u32 s25, s25, 1
	s_waitcnt vmcnt(0)
	v_cmp_ge_u32_e32 vcc, v0, v1
	s_cmp_lg_u64 vcc, 0
	s_cbranch_scc1 .Lsy0_done
	s_cmp_lt_u32 s25, 0x40000
	s_cbranch_scc1 .Lsy0_poll
.Lsy0_done:
	buffer_inv sc1
	s_waitcnt vmcnt(0)
	s_mov_b64 exec, -1
.Lsy0_skip:
	s_barrier
	s_mov_b64 exec, -1
	v_mbcnt_lo_u32_b32 v165, -1, 0
	v_mbcnt_hi_u32_b32 v165, -1, v165
	v_lshlrev_b32_e32 v160, 4, v165
	v_lshlrev_b32_e32 v161, 3, v165
	s_sub_u32 s24, s72, 0xc8
	s_subb_u32 s25, s73, 0
	s_load_dwordx2 s[16:17], s[24:25], 0x50
	s_load_dwordx2 s[20:21], s[24:25], 0xb0
	s_waitcnt lgkmcnt(0)
	global_load_dwordx4 v[16:19], v160, s[16:17]
	global_load_dwordx4 v[20:23], v160, s[16:17] offset:1024
	global_load_dwordx4 v[24:27], v160, s[16:17] offset:2048
	global_load_dwordx4 v[28:31], v160, s[16:17] offset:3072
	s_lshl_b32 s22, s95, 2
	s_add_u32 s22, s22, s94
	s_lshl_b32 s23, s70, 2
	s_cmp_ge_u32 s22, 0x10080
	s_cbranch_scc1 .Lpn0_end
.Lpn0_row:
	s_lshl_b32 s24, s22, 12
	s_add_u32 s14, s68, s24
	s_addc_u32 s15, s69, 0
	global_load_dwordx4 v[0:3], v160, s[14:15]
	global_load_dwordx4 v[4:7], v160, s[14:15] offset:1024
	global_load_dwordx4 v[8:11], v160, s[14:15] offset:2048
	global_load_dwordx4 v[12:15], v160, s[14:15] offset:3072
	s_waitcnt vmcnt(0)
	v_mul_f32_e32 v32, v0, v0
	v_fmac_f32_e32 v32, v1, v1
	v_fmac_f32_e32 v32, v2, v2
	v_fmac_f32_e32 v32, v3, v3
	v_fmac_f32_e32 v32, v4, v4
	v_fmac_f32_e32 v32, v5, v5
	v_fmac_f32_e32 v32, v6, v6
	v_fmac_f32_e32 v32, v7, v7
	v_fmac_f32_e32 v32, v8, v8
	v_fmac_f32_e32 v32, v9, v9
	v_fmac_f32_e32 v32, v10, v10
	v_fmac_f32_e32 v32, v11, v11
	v_fmac_f32_e32 v32, v12, v12
	v_fmac_f32_e32 v32, v13, v13
	v_fmac_f32_e32 v32, v14, v14
	v_fmac_f32_e32 v32, v15, v15
	s_nop 1
	v_add_f32_dpp v33, v32, v32 quad_perm:[1,0,3,2] row_mask:0xf bank_mask:0xf
	s_nop 1
	v_add_f32_dpp v32, v33, v33 quad_perm:[2,3,0,1] row_mask:0xf bank_mask:0xf
	s_nop 1
	v_add_f32_dpp v33, v32, v32 row_half_mirror row_mask:0xf bank_mask:0xf
	s_nop 1
	v_add_f32_dpp v32, v33, v33 row_mirror row_mask:0xf bank_mask:0xf
	s_nop 1
	v_readlane_b32 s24, v32, 0
	v_readlane_b32 s25, v32, 16
	v_readlane_b32 s26, v32, 32
	v_readlane_b32 s27, v32, 48
	s_nop 3
	v_mov_b32_e32 v33, s24
	v_add_f32_e32 v33, s25, v33
	v_add_f32_e32 v33, s26, v33
	v_add_f32_e32 v33, s27, v33
	v_mul_f32_e32 v33, 0x3a800000, v33
	v_add_f32_e32 v33, 0x358637bd, v33
	v_rsq_f32_e32 v33, v33
	s_nop 1
	v_mul_f32_e32 v0, v0, v33
	v_mul_f32_e32 v1, v1, v33
	v_mul_f32_e32 v2, v2, v33
	v_mul_f32_e32 v3, v3, v33
	v_mul_f32_e32 v4, v4, v33
	v_mul_f32_e32 v5, v5, v33
	v_mul_f32_e32 v6, v6, v33
	v_mul_f32_e32 v7, v7, v33
	v_mul_f32_e32 v8, v8, v33
	v_mul_f32_e32 v9, v9, v33
	v_mul_f32_e32 v10, v10, v33
	v_mul_f32_e32 v11, v11, v33
	v_mul_f32_e32 v12, v12, v33
	v_mul_f32_e32 v13, v13, v33
	v_mul_f32_e32 v14, v14, v33
	v_mul_f32_e32 v15, v15, v33
	v_mul_f32_e32 v0, v0, v16
	v_mul_f32_e32 v1, v1, v17
	v_mul_f32_e32 v2, v2, v18
	v_mul_f32_e32 v3, v3, v19
	v_mul_f32_e32 v4, v4, v20
	v_mul_f32_e32 v5, v5, v21
	v_mul_f32_e32 v6, v6, v22
	v_mul_f32_e32 v7, v7, v23
	v_mul_f32_e32 v8, v8, v24
	v_mul_f32_e32 v9, v9, v25
	v_mul_f32_e32 v10, v10, v26
	v_mul_f32_e32 v11, v11, v27
	v_mul_f32_e32 v12, v12, v28
	v_mul_f32_e32 v13, v13, v29
	v_mul_f32_e32 v14, v14, v30
	v_mul_f32_e32 v15, v15, v31
	s_lshl_b32 s24, s22, 11
	s_add_u32 s24, s24, 0x10080000
	s_add_u32 s18, s68, s24
	s_addc_u32 s19, s69, 0
	v_cvt_pk_bf16_f32 v40, v0, v1
	v_cvt_pk_bf16_f32 v41, v2, v3
	v_cvt_pk_bf16_f32 v42, v4, v5
	v_cvt_pk_bf16_f32 v43, v6, v7
	v_cvt_pk_bf16_f32 v44, v8, v9
	v_cvt_pk_bf16_f32 v45, v10, v11
	v_cvt_pk_bf16_f32 v46, v12, v13
	v_cvt_pk_bf16_f32 v47, v14, v15
	global_store_dwordx2 v161, v[40:41], s[18:19] offset:0
	global_store_dwordx2 v161, v[42:43], s[18:19] offset:512
	global_store_dwordx2 v161, v[44:45], s[18:19] offset:1024
	global_store_dwordx2 v161, v[46:47], s[18:19] offset:1536
.Lpn0_next:
	s_add_u32 s22, s22, s23
	s_cmp_lt_u32 s22, 0x10080
	s_cbranch_scc1 .Lpn0_row
.Lpn0_end:
.LBB0_506:
	s_mov_b64 exec, -1
	s_add_u32 s90, s90, 1
	s_waitcnt vmcnt(0) lgkmcnt(0)
	s_barrier
	s_and_saveexec_b64 s[12:13], s[0:1]
	s_cbranch_execz .LBB0_516
	buffer_wbl2 sc1
	s_waitcnt vmcnt(0)
	s_add_u32 s14, s68, 0x1e000000
	s_addc_u32 s15, s69, 0
	v_mov_b32_e32 v2, 0
	v_mov_b32_e32 v0, 1
	global_atomic_add v2, v0, s[14:15]
	s_mul_i32 s16, s70, s90
	s_mov_b32 s17, 0
	v_mov_b32_e32 v1, s16

; #define PH_SYNC(n) run_phase<n>(p, smem); grid.sync();
; __global__ void __launch_bounds__(256, 2) hybrid_fwd(Params p) {
;     ...
;   PH_SYNC(0) PH_SYNC(1) PH_SYNC(2) PH_SYNC(3) PH_SYNC(4) PH_SYNC(5) PH_SYNC(6) PH_SYNC(7)
;   PH_SYNC(8) PH_SYNC(17) PH_SYNC(9) PH_SYNC(10) PH_SYNC(11) PH_SYNC(12) PH_SYNC(13) PH_SYNC(14) PH_SYNC(15)
;   PH_SYNC(16)
.LBB0_544:
	s_waitcnt vmcnt(63) expcnt(7) lgkmcnt(15)
	s_add_u32 s90, s90, 1
	s_waitcnt vmcnt(0) lgkmcnt(0)
	s_barrier
	s_and_saveexec_b64 s[12:13], s[0:1]
	s_cbranch_execz .LBB0_554
	buffer_wbl2 sc1
	s_waitcnt vmcnt(0)
	s_add_u32 s14, s68, 0x1e000000
	s_addc_u32 s15, s69, 0
	v_mov_b32_e32 v2, 0
	v_mov_b32_e32 v0, 1
	global_atomic_add v2, v0, s[14:15]
	s_mul_i32 s16, s70, s90
	s_mov_b32 s17, 0
	v_mov_b32_e32 v1, s16

; #define PH_SYNC(n) run_phase<n>(p, smem); grid.sync();
; __global__ void __launch_bounds__(256, 2) hybrid_fwd(Params p) {
;     ...
;   PH_SYNC(0) PH_SYNC(1) PH_SYNC(2) PH_SYNC(3) PH_SYNC(4) PH_SYNC(5) PH_SYNC(6) PH_SYNC(7)
;   PH_SYNC(8) PH_SYNC(17) PH_SYNC(9) PH_SYNC(10) PH_SYNC(11) PH_SYNC(12) PH_SYNC(13) PH_SYNC(14) PH_SYNC(15)
;   PH_SYNC(16)
.LBB0_565:
	s_add_u32 s90, s90, 1
	s_waitcnt vmcnt(0) lgkmcnt(0)
	s_barrier
	s_and_saveexec_b64 s[12:13], s[0:1]
	s_cbranch_execz .LBB0_575
	buffer_wbl2 sc1
	s_waitcnt vmcnt(0)
	s_add_u32 s14, s68, 0x1e000000
	s_addc_u32 s15, s69, 0
	v_mov_b32_e32 v2, 0
	v_mov_b32_e32 v0, 1
	global_atomic_add v2, v0, s[14:15]
	s_mul_i32 s16, s70, s90
	s_mov_b32 s17, 0
	v_mov_b32_e32 v1, s16

; #define PH_SYNC(n) run_phase<n>(p, smem); grid.sync();
; __global__ void __launch_bounds__(256, 2) hybrid_fwd(Params p) {
;     ...
;   PH_SYNC(0) PH_SYNC(1) PH_SYNC(2) PH_SYNC(3) PH_SYNC(4) PH_SYNC(5) PH_SYNC(6) PH_SYNC(7)
;   PH_SYNC(8) PH_SYNC(17) PH_SYNC(9) PH_SYNC(10) PH_SYNC(11) PH_SYNC(12) PH_SYNC(13) PH_SYNC(14) PH_SYNC(15)
;   PH_SYNC(16)
.LBB0_630:
	s_or_b64 exec, exec, s[18:19]
	s_add_u32 s90, s90, 1
	s_waitcnt vmcnt(0) lgkmcnt(0)
	s_barrier
	s_and_saveexec_b64 s[12:13], s[0:1]
	s_cbranch_execz .LBB0_640
	buffer_wbl2 sc1
	s_waitcnt vmcnt(0)
	s_add_u32 s14, s68, 0x1e000000
	s_addc_u32 s15, s69, 0
	v_mov_b32_e32 v2, 0
	v_mov_b32_e32 v0, 1
	global_atomic_add v2, v0, s[14:15]
	s_mul_i32 s16, s70, s90
	s_mov_b32 s17, 0
	v_mov_b32_e32 v1, s16

; #define PH_SYNC(n) run_phase<n>(p, smem); grid.sync();
; __global__ void __launch_bounds__(256, 2) hybrid_fwd(Params p) {
;     ...
;   PH_SYNC(0) PH_SYNC(1) PH_SYNC(2) PH_SYNC(3) PH_SYNC(4) PH_SYNC(5) PH_SYNC(6) PH_SYNC(7)
;   PH_SYNC(8) PH_SYNC(17) PH_SYNC(9) PH_SYNC(10) PH_SYNC(11) PH_SYNC(12) PH_SYNC(13) PH_SYNC(14) PH_SYNC(15)
;   PH_SYNC(16)
.LBB0_663:
	s_or_b64 exec, exec, s[12:13]
	s_add_u32 s90, s90, 1
	s_waitcnt vmcnt(0) lgkmcnt(0)
	s_barrier
	s_and_saveexec_b64 s[4:5], s[0:1]
	s_cbranch_execz .LBB0_673
	buffer_wbl2 sc1
	s_waitcnt vmcnt(0)
	s_add_u32 s12, s68, 0x1e000000
	s_addc_u32 s13, s69, 0
	v_mov_b32_e32 v2, 0
	v_mov_b32_e32 v0, 1
	global_atomic_add v2, v0, s[12:13]
	s_mul_i32 s14, s70, s90
	s_mov_b32 s15, 0
	v_mov_b32_e32 v1, s14

; #define PH_SYNC(n) run_phase<n>(p, smem); grid.sync();
; __global__ void __launch_bounds__(256, 2) hybrid_fwd(Params p) {
;     ...
;   PH_SYNC(0) PH_SYNC(1) PH_SYNC(2) PH_SYNC(3) PH_SYNC(4) PH_SYNC(5) PH_SYNC(6) PH_SYNC(7)
;   PH_SYNC(8) PH_SYNC(17) PH_SYNC(9) PH_SYNC(10) PH_SYNC(11) PH_SYNC(12) PH_SYNC(13) PH_SYNC(14) PH_SYNC(15)
;   PH_SYNC(16)
.LBB0_685:
	s_waitcnt vmcnt(63) expcnt(7) lgkmcnt(15)
	s_add_u32 s90, s90, 1
	s_waitcnt vmcnt(0) lgkmcnt(0)
	s_barrier
	s_and_saveexec_b64 s[4:5], s[0:1]
	s_cbranch_execz .LBB0_695
	buffer_wbl2 sc1
	s_waitcnt vmcnt(0)
	s_add_u32 s6, s68, 0x1e000000
	s_addc_u32 s7, s69, 0
	v_mov_b32_e32 v2, 0
	v_mov_b32_e32 v0, 1
	global_atomic_add v2, v0, s[6:7]
	s_mul_i32 s8, s70, s90
	s_mov_b32 s9, 0
	v_mov_b32_e32 v1, s8

; #define PH_SYNC(n) run_phase<n>(p, smem); grid.sync();
; __global__ void __launch_bounds__(256, 2) hybrid_fwd(Params p) {
;     ...
;   PH_SYNC(0) PH_SYNC(1) PH_SYNC(2) PH_SYNC(3) PH_SYNC(4) PH_SYNC(5) PH_SYNC(6) PH_SYNC(7)
;   PH_SYNC(8) PH_SYNC(17) PH_SYNC(9) PH_SYNC(10) PH_SYNC(11) PH_SYNC(12) PH_SYNC(13) PH_SYNC(14) PH_SYNC(15)
;   PH_SYNC(16)
.LBB0_712:
	s_waitcnt lgkmcnt(0)
	s_add_u32 s90, s90, 1
	s_waitcnt vmcnt(0) lgkmcnt(0)
	s_barrier
	s_and_saveexec_b64 s[2:3], s[0:1]
	s_cbranch_execz .LBB0_722
	buffer_wbl2 sc1
	s_waitcnt vmcnt(0)
	s_add_u32 s0, s68, 0x1e000000
	s_addc_u32 s1, s69, 0
	v_mov_b32_e32 v2, 0
	v_mov_b32_e32 v0, 1
	global_atomic_add v2, v0, s[0:1]
	s_mul_i32 s4, s70, s90
	s_mov_b32 s5, 0
	v_mov_b32_e32 v1, s4

; DI void phase_peer_b(const Params& p, int layer, const float* gnext, bool last) {
;   const int tid = threadIdx.x, lane = tid & 63, wave = tid >> 6;
;   const float* wbuf = (const float*)(p.ws + OFF_R + R_WBUF);
;   const int* ibuf = (const int*)(p.ws + OFF_R + R_IBUF);
;   u16* xnw = (u16*)(p.ws + OFF_XN);
;   float* hbuf = (float*)(p.ws + OFF_H);
;   const unsigned char* EV = (const unsigned char*)(p.ws + OFF_EXP) + (size_t)(layer * 2 + 1) * NEXP * DM;
; #pragma unroll 1
;   for (size_t row = (size_t)blockIdx.x * 4 + wave; row < (size_t)T; row += (size_t)gridDim.x * 4) {
;     const int i0 = ibuf[row * 128 + lane], i1 = ibuf[row * 128 + 64 + lane];
;     const float w0 = wbuf[row * 128 + lane], w1 = wbuf[row * 128 + 64 + lane];
.LBB0_722:
	s_or_b64 exec, exec, s[2:3]
	s_barrier
	s_mov_b64 exec, -1
	v_mbcnt_lo_u32_b32 v165, -1, 0
	v_mbcnt_hi_u32_b32 v165, -1, v165
	v_and_b32_e32 v160, 7, v165
	v_lshlrev_b32_e32 v167, 6, v160
	v_lshlrev_b32_e32 v160, 4, v160
	v_lshrrev_b32_e32 v166, 3, v165
	s_and_b32 s24, s95, 7
	s_lshr_b32 s22, s95, 3
	s_lshr_b32 s23, s70, 3
	s_cmp_ge_u32 s22, s23
	s_cbranch_scc1 .Lpv1_end
	s_lshl_b32 s22, s22, 2
	s_add_u32 s22, s22, s94
	s_lshl_b32 s23, s23, 2
	s_lshl_b32 s25, s24, 21
	s_add_u32 s25, s25, 0x1b0c0000
	s_add_u32 s14, s68, s25
	s_addc_u32 s15, s69, 0
	s_add_u32 s16, s68, 0x2b4b0800
	s_addc_u32 s17, s69, 0
	s_add_u32 s18, s68, 0x294a0800
	s_addc_u32 s19, s69, 0
	s_lshl_b32 s25, s24, 9
	s_add_u32 s20, s68, s25
	s_addc_u32 s21, s69, 0
	s_cmpk_ge_u32 s22, 0x2010
	s_cbranch_scc1 .Lpv1_end

; DI unsigned pack2(float a, float b) { return (unsigned)f2bf(a) | ((unsigned)f2bf(b) << 16); }
; DI void phase_peer_b(const Params& p, int layer, const float* gnext, bool last) {
;     ...
;       float ss = 0.f;
; #pragma unroll
;       for (int i = 0; i < 16; ++i) ss += hn[i] * hn[i];
;       ss = wave_sum(ss);
;       const float rn = rsqrtf(ss * (1.f / 1024.f) + 1e-6f);
;       float y[16];
; #pragma unroll
;       for (int q = 0; q < 2; ++q) {
;         const float4 ga = *(const float4*)(gnext + lane * 16 + q * 8);
;         const float4 gb = *(const float4*)(gnext + lane * 16 + q * 8 + 4);
;         y[q * 8 + 0] = hn[q * 8 + 0] * rn * ga.x; y[q * 8 + 1] = hn[q * 8 + 1] * rn * ga.y; y[q * 8 + 2] = hn[q * 8 + 2] * rn * ga.z; y[q * 8 + 3] = hn[q * 8 + 3] * rn * ga.w;
;         y[q * 8 + 4] = hn[q * 8 + 4] * rn * gb.x; y[q * 8 + 5] = hn[q * 8 + 5] * rn * gb.y; y[q * 8 + 6] = hn[q * 8 + 6] * rn * gb.z; y[q * 8 + 7] = hn[q * 8 + 7] * rn * gb.w;
;       }
;       if (!last) {
; #pragma unroll
;         for (int q = 0; q < 2; ++q) {
;           *(float4*)(hp + lane * 16 + q * 8) = make_float4(hn[q * 8 + 0], hn[q * 8 + 1], hn[q * 8 + 2], hn[q * 8 + 3]);
;           *(float4*)(hp + lane * 16 + q * 8 + 4) = make_float4(hn[q * 8 + 4], hn[q * 8 + 5], hn[q * 8 + 6], hn[q * 8 + 7]);
;           u32x4 o;
;           o[0] = pack2(y[q * 8 + 0], y[q * 8 + 1]); o[1] = pack2(y[q * 8 + 2], y[q * 8 + 3]); o[2] = pack2(y[q * 8 + 4], y[q * 8 + 5]); o[3] = pack2(y[q * 8 + 6], y[q * 8 + 7]);
;           *(u32x4*)(xnw + row * DM + lane * 16 + q * 8) = o;
;         }
;       } else {
;         const int b = (int)(row / LT), t = (int)(row % LT);
;         if (t >= 16) {
;           float* op = p.out + ((size_t)b * 8192 + (t - 16)) * DM;
; #pragma unroll
;           for (int q = 0; q < 2; ++q) {
;             *(float4*)(op + lane * 16 + q * 8) = make_float4(y[q * 8 + 0], y[q * 8 + 1], y[q * 8 + 2], y[q * 8 + 3]);
;             *(float4*)(op + lane * 16 + q * 8 + 4) = make_float4(y[q * 8 + 4], y[q * 8 + 5], y[q * 8 + 6], y[q * 8 + 7]);
;           }
;         }
.Lsy1_skip:
	s_barrier
	s_mov_b64 exec, -1
	v_mbcnt_lo_u32_b32 v165, -1, 0
	v_mbcnt_hi_u32_b32 v165, -1, v165
	v_lshlrev_b32_e32 v160, 4, v165
	v_lshlrev_b32_e32 v161, 3, v165
	s_sub_u32 s24, s72, 0xc8
	s_subb_u32 s25, s73, 0
	s_load_dwordx2 s[16:17], s[24:25], 0xa8
	s_load_dwordx2 s[20:21], s[24:25], 0xb0
	s_waitcnt lgkmcnt(0)
	global_load_dwordx4 v[16:19], v160, s[16:17]
	global_load_dwordx4 v[20:23], v160, s[16:17] offset:1024
	global_load_dwordx4 v[24:27], v160, s[16:17] offset:2048
	global_load_dwordx4 v[28:31], v160, s[16:17] offset:3072
	s_lshl_b32 s22, s95, 2
	s_add_u32 s22, s22, s94
	s_lshl_b32 s23, s70, 2
	s_cmp_ge_u32 s22, 0x10080
	s_cbranch_scc1 .Lpn1_end
.Lpn1_row:
	s_lshl_b32 s24, s22, 12
	s_add_u32 s14, s68, s24
	s_addc_u32 s15, s69, 0
	global_load_dwordx4 v[0:3], v160, s[14:15]
	global_load_dwordx4 v[4:7], v160, s[14:15] offset:1024
	global_load_dwordx4 v[8:11], v160, s[14:15] offset:2048
	global_load_dwordx4 v[12:15], v160, s[14:15] offset:3072
	s_waitcnt vmcnt(0)
	v_mul_f32_e32 v32, v0, v0
	v_fmac_f32_e32 v32, v1, v1
	v_fmac_f32_e32 v32, v2, v2
	v_fmac_f32_e32 v32, v3, v3
	v_fmac_f32_e32 v32, v4, v4
	v_fmac_f32_e32 v32, v5, v5
	v_fmac_f32_e32 v32, v6, v6
	v_fmac_f32_e32 v32, v7, v7
	v_fmac_f32_e32 v32, v8, v8
	v_fmac_f32_e32 v32, v9, v9
	v_fmac_f32_e32 v32, v10, v10
	v_fmac_f32_e32 v32, v11, v11
	v_fmac_f32_e32 v32, v12, v12
	v_fmac_f32_e32 v32, v13, v13
	v_fmac_f32_e32 v32, v14, v14
	v_fmac_f32_e32 v32, v15, v15
	s_nop 1
	v_add_f32_dpp v33, v32, v32 quad_perm:[1,0,3,2] row_mask:0xf bank_mask:0xf
	s_nop 1
	v_add_f32_dpp v32, v33, v33 quad_perm:[2,3,0,1] row_mask:0xf bank_mask:0xf
	s_nop 1
	v_add_f32_dpp v33, v32, v32 row_half_mirror row_mask:0xf bank_mask:0xf
	s_nop 1
	v_add_f32_dpp v32, v33, v33 row_mirror row_mask:0xf bank_mask:0xf
	s_nop 1
	v_readlane_b32 s24, v32, 0
	v_readlane_b32 s25, v32, 16
	v_readlane_b32 s26, v32, 32
	v_readlane_b32 s27, v32, 48
	s_nop 3
	v_mov_b32_e32 v33, s24
	v_add_f32_e32 v33, s25, v33
	v_add_f32_e32 v33, s26, v33
	v_add_f32_e32 v33, s27, v33
	v_mul_f32_e32 v33, 0x3a800000, v33
	v_add_f32_e32 v33, 0x358637bd, v33
	v_rsq_f32_e32 v33, v33
	s_nop 1
	v_mul_f32_e32 v0, v0, v33
	v_mul_f32_e32 v1, v1, v33
	v_mul_f32_e32 v2, v2, v33
	v_mul_f32_e32 v3, v3, v33
	v_mul_f32_e32 v4, v4, v33
	v_mul_f32_e32 v5, v5, v33
	v_mul_f32_e32 v6, v6, v33
	v_mul_f32_e32 v7, v7, v33
	v_mul_f32_e32 v8, v8, v33
	v_mul_f32_e32 v9, v9, v33
	v_mul_f32_e32 v10, v10, v33
	v_mul_f32_e32 v11, v11, v33
	v_mul_f32_e32 v12, v12, v33
	v_mul_f32_e32 v13, v13, v33
	v_mul_f32_e32 v14, v14, v33
	v_mul_f32_e32 v15, v15, v33
	v_mul_f32_e32 v0, v0, v16
	v_mul_f32_e32 v1, v1, v17
	v_mul_f32_e32 v2, v2, v18
	v_mul_f32_e32 v3, v3, v19
	v_mul_f32_e32 v4, v4, v20
	v_mul_f32_e32 v5, v5, v21
	v_mul_f32_e32 v6, v6, v22
	v_mul_f32_e32 v7, v7, v23
	v_mul_f32_e32 v8, v8, v24
	v_mul_f32_e32 v9, v9, v25
	v_mul_f32_e32 v10, v10, v26
	v_mul_f32_e32 v11, v11, v27
	v_mul_f32_e32 v12, v12, v28
	v_mul_f32_e32 v13, v13, v29
	v_mul_f32_e32 v14, v14, v30
	v_mul_f32_e32 v15, v15, v31
	s_mul_hi_u32 s24, s22, 0xff803fe1
	s_lshr_b32 s24, s24, 13
	s_mul_i32 s25, s24, 0x2010
	s_sub_u32 s25, s22, s25
	s_cmp_lt_u32 s25, 16
	s_cbranch_scc1 .Lpn1_next
	s_lshl_b32 s24, s24, 13
	s_add_u32 s24, s24, s25
	s_sub_u32 s24, s24, 16
	s_lshl_b32 s24, s24, 12
	s_add_u32 s18, s20, s24
	s_addc_u32 s19, s21, 0
	global_store_dwordx4 v160, v[0:3], s[18:19] offset:0
	global_store_dwordx4 v160, v[4:7], s[18:19] offset:1024
	global_store_dwordx4 v160, v[8:11], s[18:19] offset:2048
	global_store_dwordx4 v160, v[12:15], s[18:19] offset:3072

; __global__ void __launch_bounds__(256, 2) hybrid_fwd(Params p) {
;     ...
;   run_phase<18>(p, smem);
; }
.Lpn1_end:
.LBB0_729:
	s_endpgm
